# re-phased GEMM loops without the per-block s_setprio 1/0 pairs
# baseline (speedup 1.0000x reference)
; #define PG8_STAGE(bufoff, gbase) do { _Pragma("unroll") for (int _i = 0; _i < 2; ++_i) \
;         __builtin_amdgcn_global_load_lds((const unsigned*)((const char*)(gbase) + voffA[_i]), (LAS unsigned*)(lds + (bufoff) + ldsw + _i * 8192), 16, 0, 0); } while (0)
; #define PG8_LDA(dst, b, h) do { _Pragma("unroll") for (int m = 0; m < 4; ++m) _Pragma("unroll") for (int k = 0; k < 2; ++k) dst[m][k] = *(const LAS bf16x8*)(lds + PG8_SA(b, h) + aoff + m * 2048 + k * 1024); } while (0)
; #define PG8_LDB(dst, b, h) do { _Pragma("unroll") for (int n = 0; n < 2; ++n) _Pragma("unroll") for (int k = 0; k < 2; ++k) dst[n][k] = *(const LAS bf16x8*)(lds + PG8_SB(b, h) + boff + n * 2048 + k * 1024); } while (0)
; #define PG8_MMA(ai, bj, At, Bt) do { __builtin_amdgcn_s_setprio(1); _Pragma("unroll") for (int m = 0; m < 4; ++m) _Pragma("unroll") for (int n = 0; n < 2; ++n) _Pragma("unroll") for (int k = 0; k < 2; ++k) \
;         acc[ai][bj][m][n] = __builtin_amdgcn_mfma_f32_16x16x32_bf16(Bt[n][k], At[m][k], acc[ai][bj][m][n], 0, 0, 0); __builtin_amdgcn_s_setprio(0); } while (0)
; #define PG8_WAIT_L(n) asm volatile("s_waitcnt lgkmcnt(" #n ")" ::: "memory")
; #define PG8_BAR __builtin_amdgcn_s_barrier()
; #define PG8_SCHED __builtin_amdgcn_sched_barrier(0)
; template <class Epi>
; DI void gemm_phase(const int TID, const int BID, LAS unsigned char* lds, const Gemm g, const Epi& E) {
;     ...
;         for (int t = 0; t < nt; t += 2) {
;             const bool last = (t == nt - 2);
;             const char* a1 = cA + (size_t)(t + 1) * kstep;
;             const char* a2 = last ? nA : cA + (size_t)(t + 2) * kstep; const char* b2 = last ? nB : cB + (size_t)(t + 2) * kstep;
;             const char* a3 = a2 + kstep; const char* b3 = b2 + kstep;
;             PG8_LDB(B0, 0, 0); PG8_SCHED; PG8_LDA(At, 0, 0); PG8_STAGE(PG8_SA(1, 1), a1 + hstep);
;             PG8_WAIT_L(8); PG8_BAR; PG8_WAIT_L(0); PG8_MMA(0, 0, At, B0); PG8_BAR; PG8_SCHED;
;             PG8_LDB(B1, 0, 1); PG8_STAGE(PG8_SB(0, 0), b2);
;             PG8_BAR; PG8_WAIT_L(0); PG8_MMA(0, 1, At, B1); PG8_BAR;
.LBB0_137:
	s_add_i32 s29, s58, 2
	s_add_u32 s60, s56, 0x80
	s_addc_u32 s59, s57, 0
	s_cmp_eq_u32 vcc_lo, s58
	s_cselect_b32 s58, s54, s60
	s_cselect_b32 s59, s55, s59
	s_cselect_b32 s61, s1, s18
	s_cselect_b32 s60, s0, vcc_hi
	v_lshl_add_u64 v[186:187], s[56:57], 0, v[178:179]
	s_add_i32 m0, s22, 0xc000
	global_load_lds_dwordx4 v[186:187], off
	v_lshl_add_u64 v[186:187], s[56:57], 0, v[180:181]
	s_add_i32 m0, s22, 0xe000
	s_nop 0
	global_load_lds_dwordx4 v[186:187], off
	v_add_u32_e32 v140, s19, v246
	ds_read_b128 v[128:131], v140
	ds_read_b128 v[132:135], v140 offset:1024
	ds_read_b128 v[136:139], v140 offset:2048
	ds_read_b128 v[140:143], v140 offset:3072
	ds_read_b128 v[144:147], v248
	ds_read_b128 v[148:151], v248 offset:1024
	ds_read_b128 v[152:155], v248 offset:2048
	ds_read_b128 v[156:159], v248 offset:3072
	ds_read_b128 v[160:163], v248 offset:4096
	ds_read_b128 v[164:167], v248 offset:5120
	ds_read_b128 v[170:173], v248 offset:6144
	ds_read_b128 v[182:185], v248 offset:7168
	v_add_u32_e32 v198, s24, v246
	ds_read_b128 v[186:189], v198
	ds_read_b128 v[190:193], v198 offset:1024
	ds_read_b128 v[194:197], v198 offset:2048
	ds_read_b128 v[198:201], v198 offset:3072
	s_waitcnt vmcnt(8)
	s_waitcnt lgkmcnt(0)
	s_barrier
	v_mfma_f32_16x16x32_bf16 v[124:127], v[128:131], v[144:147], v[124:127]
	v_mfma_f32_16x16x32_bf16 v[120:123], v[136:139], v[144:147], v[120:123]
	v_mfma_f32_16x16x32_bf16 v[108:111], v[128:131], v[152:155], v[108:111]
	v_mfma_f32_16x16x32_bf16 v[104:107], v[136:139], v[152:155], v[104:107]
	v_mfma_f32_16x16x32_bf16 v[92:95], v[128:131], v[160:163], v[92:95]
	v_mfma_f32_16x16x32_bf16 v[88:91], v[136:139], v[160:163], v[88:91]
	v_mfma_f32_16x16x32_bf16 v[76:79], v[128:131], v[170:173], v[76:79]
	v_mfma_f32_16x16x32_bf16 v[72:75], v[136:139], v[170:173], v[72:75]
	v_mfma_f32_16x16x32_bf16 v[124:127], v[132:135], v[148:151], v[124:127]
	v_mfma_f32_16x16x32_bf16 v[120:123], v[140:143], v[148:151], v[120:123]
	v_mfma_f32_16x16x32_bf16 v[108:111], v[132:135], v[156:159], v[108:111]
	v_mfma_f32_16x16x32_bf16 v[104:107], v[140:143], v[156:159], v[104:107]
	v_mfma_f32_16x16x32_bf16 v[92:95], v[132:135], v[164:167], v[92:95]
	v_mfma_f32_16x16x32_bf16 v[88:91], v[140:143], v[164:167], v[88:91]
	v_mfma_f32_16x16x32_bf16 v[76:79], v[132:135], v[182:185], v[76:79]
	v_mfma_f32_16x16x32_bf16 v[72:75], v[140:143], v[182:185], v[72:75]
	v_mfma_f32_16x16x32_bf16 v[116:119], v[186:189], v[144:147], v[116:119]
	v_mfma_f32_16x16x32_bf16 v[112:115], v[194:197], v[144:147], v[112:115]
	v_mfma_f32_16x16x32_bf16 v[100:103], v[186:189], v[152:155], v[100:103]
	v_mfma_f32_16x16x32_bf16 v[96:99], v[194:197], v[152:155], v[96:99]
	v_mfma_f32_16x16x32_bf16 v[84:87], v[186:189], v[160:163], v[84:87]
	v_mfma_f32_16x16x32_bf16 v[80:83], v[194:197], v[160:163], v[80:83]
	v_mfma_f32_16x16x32_bf16 v[68:71], v[186:189], v[170:173], v[68:71]
	v_mfma_f32_16x16x32_bf16 v[64:67], v[194:197], v[170:173], v[64:67]
	v_mfma_f32_16x16x32_bf16 v[116:119], v[190:193], v[148:151], v[116:119]
	v_mfma_f32_16x16x32_bf16 v[112:115], v[198:201], v[148:151], v[112:115]
	v_mfma_f32_16x16x32_bf16 v[100:103], v[190:193], v[156:159], v[100:103]
	v_mfma_f32_16x16x32_bf16 v[96:99], v[198:201], v[156:159], v[96:99]
	v_mfma_f32_16x16x32_bf16 v[84:87], v[190:193], v[164:167], v[84:87]
	v_mfma_f32_16x16x32_bf16 v[80:83], v[198:201], v[164:167], v[80:83]
	v_mfma_f32_16x16x32_bf16 v[68:71], v[190:193], v[182:185], v[68:71]
	v_mfma_f32_16x16x32_bf16 v[64:67], v[198:201], v[182:185], v[64:67]
	s_barrier
	s_mov_b32 m0, s20
	v_lshl_add_u64 v[202:203], s[60:61], 0, v[168:169]
	global_load_lds_dwordx4 v[202:203], off
	v_lshl_add_u64 v[204:205], s[60:61], 0, v[176:177]
	s_mov_b32 m0, s21
	s_nop 0
	global_load_lds_dwordx4 v[204:205], off
	s_mov_b32 m0, s22
	v_lshl_add_u64 v[206:207], s[58:59], 0, v[168:169]
	global_load_lds_dwordx4 v[206:207], off
	v_lshl_add_u64 v[208:209], s[58:59], 0, v[176:177]
	s_mov_b32 m0, s23
	s_nop 0
	global_load_lds_dwordx4 v[208:209], off
	s_add_u32 s60, s60, s6
	s_addc_u32 s61, s61, s7
	s_mov_b32 m0, s25
	v_lshl_add_u64 v[210:211], s[60:61], 0, v[168:169]
	global_load_lds_dwordx4 v[210:211], off
	v_lshl_add_u64 v[212:213], s[60:61], 0, v[176:177]
	s_mov_b32 m0, s26
	s_nop 0
	global_load_lds_dwordx4 v[212:213], off
	ds_read_b128 v[144:147], v248 offset:16384
	ds_read_b128 v[148:151], v248 offset:17408
	ds_read_b128 v[152:155], v248 offset:18432
	ds_read_b128 v[156:159], v248 offset:19456
	ds_read_b128 v[160:163], v248 offset:20480
	ds_read_b128 v[164:167], v248 offset:21504
	ds_read_b128 v[170:173], v248 offset:22528
	ds_read_b128 v[182:185], v248 offset:23552
	s_waitcnt vmcnt(8)
	s_waitcnt lgkmcnt(0)
	s_barrier
; #define PG8_STAGE(bufoff, gbase) do { _Pragma("unroll") for (int _i = 0; _i < 2; ++_i) \
;         __builtin_amdgcn_global_load_lds((const unsigned*)((const char*)(gbase) + voffA[_i]), (LAS unsigned*)(lds + (bufoff) + ldsw + _i * 8192), 16, 0, 0); } while (0)
; #define PG8_LDA(dst, b, h) do { _Pragma("unroll") for (int m = 0; m < 4; ++m) _Pragma("unroll") for (int k = 0; k < 2; ++k) dst[m][k] = *(const LAS bf16x8*)(lds + PG8_SA(b, h) + aoff + m * 2048 + k * 1024); } while (0)
; #define PG8_LDB(dst, b, h) do { _Pragma("unroll") for (int n = 0; n < 2; ++n) _Pragma("unroll") for (int k = 0; k < 2; ++k) dst[n][k] = *(const LAS bf16x8*)(lds + PG8_SB(b, h) + boff + n * 2048 + k * 1024); } while (0)
; #define PG8_MMA(ai, bj, At, Bt) do { __builtin_amdgcn_s_setprio(1); _Pragma("unroll") for (int m = 0; m < 4; ++m) _Pragma("unroll") for (int n = 0; n < 2; ++n) _Pragma("unroll") for (int k = 0; k < 2; ++k) \
;         acc[ai][bj][m][n] = __builtin_amdgcn_mfma_f32_16x16x32_bf16(Bt[n][k], At[m][k], acc[ai][bj][m][n], 0, 0, 0); __builtin_amdgcn_s_setprio(0); } while (0)
; #define PG8_WAIT_V(n) asm volatile("s_waitcnt vmcnt(" #n ")" ::: "memory")
; #define PG8_WAIT_L(n) asm volatile("s_waitcnt lgkmcnt(" #n ")" ::: "memory")
; #define PG8_BAR __builtin_amdgcn_s_barrier()
; #define PG8_SCHED __builtin_amdgcn_sched_barrier(0)
; template <class Epi>
; DI void gemm_phase(const int TID, const int BID, LAS unsigned char* lds, const Gemm g, const Epi& E) {
;     ...
;             PG8_BAR; PG8_WAIT_L(0); PG8_MMA(0, 1, At, B1); PG8_BAR;
;             PG8_LDA(At, 0, 1); PG8_STAGE(PG8_SA(0, 0), a2);
;             PG8_BAR; PG8_WAIT_L(0); PG8_MMA(1, 0, At, B0); PG8_BAR; PG8_SCHED;
;             PG8_STAGE(PG8_SB(0, 1), b2 + hstep);
;             PG8_WAIT_V(6); PG8_BAR; PG8_MMA(1, 1, At, B1); PG8_BAR;
;             PG8_LDB(B0, 1, 0); PG8_SCHED; PG8_LDA(At, 1, 0); PG8_STAGE(PG8_SA(0, 1), a2 + hstep);
;             PG8_WAIT_L(8); PG8_BAR; PG8_WAIT_L(0); PG8_MMA(0, 0, At, B0); PG8_BAR; PG8_SCHED;
	v_mfma_f32_16x16x32_bf16 v[60:63], v[128:131], v[144:147], v[60:63]
	v_mfma_f32_16x16x32_bf16 v[56:59], v[136:139], v[144:147], v[56:59]
	v_mfma_f32_16x16x32_bf16 v[44:47], v[128:131], v[152:155], v[44:47]
	v_mfma_f32_16x16x32_bf16 v[40:43], v[136:139], v[152:155], v[40:43]
	v_mfma_f32_16x16x32_bf16 v[28:31], v[128:131], v[160:163], v[28:31]
	v_mfma_f32_16x16x32_bf16 v[24:27], v[136:139], v[160:163], v[24:27]
	v_mfma_f32_16x16x32_bf16 v[12:15], v[128:131], v[170:173], v[12:15]
	v_mfma_f32_16x16x32_bf16 v[8:11], v[136:139], v[170:173], v[8:11]
	v_mfma_f32_16x16x32_bf16 v[60:63], v[132:135], v[148:151], v[60:63]
	v_mfma_f32_16x16x32_bf16 v[56:59], v[140:143], v[148:151], v[56:59]
	v_mfma_f32_16x16x32_bf16 v[44:47], v[132:135], v[156:159], v[44:47]
	v_mfma_f32_16x16x32_bf16 v[40:43], v[140:143], v[156:159], v[40:43]
	v_mfma_f32_16x16x32_bf16 v[28:31], v[132:135], v[164:167], v[28:31]
	v_mfma_f32_16x16x32_bf16 v[24:27], v[140:143], v[164:167], v[24:27]
	v_mfma_f32_16x16x32_bf16 v[12:15], v[132:135], v[182:185], v[12:15]
	v_mfma_f32_16x16x32_bf16 v[8:11], v[140:143], v[182:185], v[8:11]
	v_mfma_f32_16x16x32_bf16 v[52:55], v[186:189], v[144:147], v[52:55]
	v_mfma_f32_16x16x32_bf16 v[48:51], v[194:197], v[144:147], v[48:51]
	v_mfma_f32_16x16x32_bf16 v[36:39], v[186:189], v[152:155], v[36:39]
	v_mfma_f32_16x16x32_bf16 v[32:35], v[194:197], v[152:155], v[32:35]
	v_mfma_f32_16x16x32_bf16 v[20:23], v[186:189], v[160:163], v[20:23]
	v_mfma_f32_16x16x32_bf16 v[16:19], v[194:197], v[160:163], v[16:19]
	v_mfma_f32_16x16x32_bf16 v[4:7], v[186:189], v[170:173], v[4:7]
	v_mfma_f32_16x16x32_bf16 v[0:3], v[194:197], v[170:173], v[0:3]
	v_mfma_f32_16x16x32_bf16 v[52:55], v[190:193], v[148:151], v[52:55]
	v_mfma_f32_16x16x32_bf16 v[48:51], v[198:201], v[148:151], v[48:51]
	v_mfma_f32_16x16x32_bf16 v[36:39], v[190:193], v[156:159], v[36:39]
	v_mfma_f32_16x16x32_bf16 v[32:35], v[198:201], v[156:159], v[32:35]
	v_mfma_f32_16x16x32_bf16 v[20:23], v[190:193], v[164:167], v[20:23]
	v_mfma_f32_16x16x32_bf16 v[16:19], v[198:201], v[164:167], v[16:19]
	v_mfma_f32_16x16x32_bf16 v[4:7], v[190:193], v[182:185], v[4:7]
	v_mfma_f32_16x16x32_bf16 v[0:3], v[198:201], v[182:185], v[0:3]
	s_barrier
	s_add_u32 s58, s58, s6
	s_addc_u32 s59, s59, s7
	s_mov_b32 m0, s27
	v_lshl_add_u64 v[186:187], s[58:59], 0, v[168:169]
	global_load_lds_dwordx4 v[186:187], off
	v_lshl_add_u64 v[186:187], s[58:59], 0, v[176:177]
	s_mov_b32 m0, s28
	s_nop 0
	global_load_lds_dwordx4 v[186:187], off
	v_add_u32_e32 v140, s33, v246
	ds_read_b128 v[128:131], v140
	ds_read_b128 v[132:135], v140 offset:1024
	ds_read_b128 v[136:139], v140 offset:2048
	ds_read_b128 v[140:143], v140 offset:3072
	ds_read_b128 v[144:147], v248 offset:32768
	ds_read_b128 v[148:151], v248 offset:33792
	ds_read_b128 v[152:155], v248 offset:34816
	ds_read_b128 v[156:159], v248 offset:35840
	ds_read_b128 v[160:163], v248 offset:36864
	ds_read_b128 v[164:167], v248 offset:37888
	ds_read_b128 v[170:173], v248 offset:38912
	ds_read_b128 v[182:185], v248 offset:39936
	v_add_u32_e32 v198, s76, v246
	ds_read_b128 v[186:189], v198
	ds_read_b128 v[190:193], v198 offset:1024
	ds_read_b128 v[194:197], v198 offset:2048
	ds_read_b128 v[198:201], v198 offset:3072
	s_waitcnt vmcnt(8)
	s_waitcnt lgkmcnt(0)
	s_barrier
	v_mfma_f32_16x16x32_bf16 v[124:127], v[128:131], v[144:147], v[124:127]
	v_mfma_f32_16x16x32_bf16 v[120:123], v[136:139], v[144:147], v[120:123]
	v_mfma_f32_16x16x32_bf16 v[108:111], v[128:131], v[152:155], v[108:111]
	v_mfma_f32_16x16x32_bf16 v[104:107], v[136:139], v[152:155], v[104:107]
	v_mfma_f32_16x16x32_bf16 v[92:95], v[128:131], v[160:163], v[92:95]
	v_mfma_f32_16x16x32_bf16 v[88:91], v[136:139], v[160:163], v[88:91]
	v_mfma_f32_16x16x32_bf16 v[76:79], v[128:131], v[170:173], v[76:79]
	v_mfma_f32_16x16x32_bf16 v[72:75], v[136:139], v[170:173], v[72:75]
	v_mfma_f32_16x16x32_bf16 v[124:127], v[132:135], v[148:151], v[124:127]
	v_mfma_f32_16x16x32_bf16 v[120:123], v[140:143], v[148:151], v[120:123]
	v_mfma_f32_16x16x32_bf16 v[108:111], v[132:135], v[156:159], v[108:111]
	v_mfma_f32_16x16x32_bf16 v[104:107], v[140:143], v[156:159], v[104:107]
	v_mfma_f32_16x16x32_bf16 v[92:95], v[132:135], v[164:167], v[92:95]
	v_mfma_f32_16x16x32_bf16 v[88:91], v[140:143], v[164:167], v[88:91]
	v_mfma_f32_16x16x32_bf16 v[76:79], v[132:135], v[182:185], v[76:79]
	v_mfma_f32_16x16x32_bf16 v[72:75], v[140:143], v[182:185], v[72:75]
	v_mfma_f32_16x16x32_bf16 v[116:119], v[186:189], v[144:147], v[116:119]
	v_mfma_f32_16x16x32_bf16 v[112:115], v[194:197], v[144:147], v[112:115]
	v_mfma_f32_16x16x32_bf16 v[100:103], v[186:189], v[152:155], v[100:103]
	v_mfma_f32_16x16x32_bf16 v[96:99], v[194:197], v[152:155], v[96:99]
	v_mfma_f32_16x16x32_bf16 v[84:87], v[186:189], v[160:163], v[84:87]
	v_mfma_f32_16x16x32_bf16 v[80:83], v[194:197], v[160:163], v[80:83]
	v_mfma_f32_16x16x32_bf16 v[68:71], v[186:189], v[170:173], v[68:71]
	v_mfma_f32_16x16x32_bf16 v[64:67], v[194:197], v[170:173], v[64:67]
	v_mfma_f32_16x16x32_bf16 v[116:119], v[190:193], v[148:151], v[116:119]
	v_mfma_f32_16x16x32_bf16 v[112:115], v[198:201], v[148:151], v[112:115]
	v_mfma_f32_16x16x32_bf16 v[100:103], v[190:193], v[156:159], v[100:103]
	v_mfma_f32_16x16x32_bf16 v[96:99], v[198:201], v[156:159], v[96:99]
	v_mfma_f32_16x16x32_bf16 v[84:87], v[190:193], v[164:167], v[84:87]
	v_mfma_f32_16x16x32_bf16 v[80:83], v[198:201], v[164:167], v[80:83]
	v_mfma_f32_16x16x32_bf16 v[68:71], v[190:193], v[182:185], v[68:71]
	v_mfma_f32_16x16x32_bf16 v[64:67], v[198:201], v[182:185], v[64:67]
	s_barrier
; #define PG8_STAGE(bufoff, gbase) do { _Pragma("unroll") for (int _i = 0; _i < 2; ++_i) \
;         __builtin_amdgcn_global_load_lds((const unsigned*)((const char*)(gbase) + voffA[_i]), (LAS unsigned*)(lds + (bufoff) + ldsw + _i * 8192), 16, 0, 0); } while (0)
; #define PG8_LDA(dst, b, h) do { _Pragma("unroll") for (int m = 0; m < 4; ++m) _Pragma("unroll") for (int k = 0; k < 2; ++k) dst[m][k] = *(const LAS bf16x8*)(lds + PG8_SA(b, h) + aoff + m * 2048 + k * 1024); } while (0)
; #define PG8_LDB(dst, b, h) do { _Pragma("unroll") for (int n = 0; n < 2; ++n) _Pragma("unroll") for (int k = 0; k < 2; ++k) dst[n][k] = *(const LAS bf16x8*)(lds + PG8_SB(b, h) + boff + n * 2048 + k * 1024); } while (0)
; #define PG8_MMA(ai, bj, At, Bt) do { __builtin_amdgcn_s_setprio(1); _Pragma("unroll") for (int m = 0; m < 4; ++m) _Pragma("unroll") for (int n = 0; n < 2; ++n) _Pragma("unroll") for (int k = 0; k < 2; ++k) \
;         acc[ai][bj][m][n] = __builtin_amdgcn_mfma_f32_16x16x32_bf16(Bt[n][k], At[m][k], acc[ai][bj][m][n], 0, 0, 0); __builtin_amdgcn_s_setprio(0); } while (0)
; #define PG8_WAIT_V(n) asm volatile("s_waitcnt vmcnt(" #n ")" ::: "memory")
; #define PG8_WAIT_L(n) asm volatile("s_waitcnt lgkmcnt(" #n ")" ::: "memory")
; #define PG8_BAR __builtin_amdgcn_s_barrier()
; #define PG8_SCHED __builtin_amdgcn_sched_barrier(0)
; template <class Epi>
; DI void gemm_phase(const int TID, const int BID, LAS unsigned char* lds, const Gemm g, const Epi& E) {
;     ...
;             PG8_LDB(B1, 1, 1); PG8_STAGE(PG8_SB(1, 0), b3);
;             PG8_BAR; PG8_WAIT_L(0); PG8_MMA(0, 1, At, B1); PG8_BAR;
;             PG8_LDA(At, 1, 1); PG8_STAGE(PG8_SA(1, 0), a3);
;             PG8_BAR; PG8_WAIT_L(0); PG8_MMA(1, 0, At, B0); PG8_BAR; PG8_SCHED;
;             PG8_STAGE(PG8_SB(1, 1), b3 + hstep);
;             PG8_WAIT_V(6); PG8_BAR; PG8_MMA(1, 1, At, B1); PG8_BAR;
;         }
	s_mov_b32 m0, s64
	v_lshl_add_u64 v[202:203], v[202:203], 0, s[92:93]
	global_load_lds_dwordx4 v[202:203], off
	v_lshl_add_u64 v[202:203], v[204:205], 0, s[92:93]
	s_mov_b32 m0, s65
	s_nop 0
	global_load_lds_dwordx4 v[202:203], off
	s_mov_b32 m0, s66
	v_lshl_add_u64 v[202:203], v[206:207], 0, s[92:93]
	global_load_lds_dwordx4 v[202:203], off
	v_lshl_add_u64 v[202:203], v[208:209], 0, s[92:93]
	s_mov_b32 m0, s67
	s_nop 0
	global_load_lds_dwordx4 v[202:203], off
	s_mov_b32 m0, s77
	v_lshl_add_u64 v[202:203], v[210:211], 0, s[92:93]
	global_load_lds_dwordx4 v[202:203], off
	v_lshl_add_u64 v[202:203], v[212:213], 0, s[92:93]
	s_mov_b32 m0, s80
	s_nop 0
	global_load_lds_dwordx4 v[202:203], off
	ds_read_b128 v[144:147], v248 offset:49152
	ds_read_b128 v[148:151], v248 offset:50176
	ds_read_b128 v[152:155], v248 offset:51200
	ds_read_b128 v[156:159], v248 offset:52224
	ds_read_b128 v[160:163], v248 offset:53248
	ds_read_b128 v[164:167], v248 offset:54272
	ds_read_b128 v[170:173], v248 offset:55296
	ds_read_b128 v[182:185], v248 offset:56320
	s_waitcnt vmcnt(8)
	s_waitcnt lgkmcnt(0)
	s_barrier
	v_mfma_f32_16x16x32_bf16 v[60:63], v[128:131], v[144:147], v[60:63]
	v_mfma_f32_16x16x32_bf16 v[56:59], v[136:139], v[144:147], v[56:59]
	v_mfma_f32_16x16x32_bf16 v[44:47], v[128:131], v[152:155], v[44:47]
	v_mfma_f32_16x16x32_bf16 v[40:43], v[136:139], v[152:155], v[40:43]
	v_mfma_f32_16x16x32_bf16 v[28:31], v[128:131], v[160:163], v[28:31]
	v_mfma_f32_16x16x32_bf16 v[24:27], v[136:139], v[160:163], v[24:27]
	v_mfma_f32_16x16x32_bf16 v[12:15], v[128:131], v[170:173], v[12:15]
	v_mfma_f32_16x16x32_bf16 v[8:11], v[136:139], v[170:173], v[8:11]
	v_mfma_f32_16x16x32_bf16 v[60:63], v[132:135], v[148:151], v[60:63]
	v_mfma_f32_16x16x32_bf16 v[56:59], v[140:143], v[148:151], v[56:59]
	v_mfma_f32_16x16x32_bf16 v[44:47], v[132:135], v[156:159], v[44:47]
	v_mfma_f32_16x16x32_bf16 v[40:43], v[140:143], v[156:159], v[40:43]
	v_mfma_f32_16x16x32_bf16 v[28:31], v[132:135], v[164:167], v[28:31]
	v_mfma_f32_16x16x32_bf16 v[24:27], v[140:143], v[164:167], v[24:27]
	v_mfma_f32_16x16x32_bf16 v[12:15], v[132:135], v[182:185], v[12:15]
	v_mfma_f32_16x16x32_bf16 v[8:11], v[140:143], v[182:185], v[8:11]
	v_mfma_f32_16x16x32_bf16 v[52:55], v[186:189], v[144:147], v[52:55]
	v_mfma_f32_16x16x32_bf16 v[48:51], v[194:197], v[144:147], v[48:51]
	v_mfma_f32_16x16x32_bf16 v[36:39], v[186:189], v[152:155], v[36:39]
	v_mfma_f32_16x16x32_bf16 v[32:35], v[194:197], v[152:155], v[32:35]
	v_mfma_f32_16x16x32_bf16 v[20:23], v[186:189], v[160:163], v[20:23]
	v_mfma_f32_16x16x32_bf16 v[16:19], v[194:197], v[160:163], v[16:19]
	v_mfma_f32_16x16x32_bf16 v[4:7], v[186:189], v[170:173], v[4:7]
	v_mfma_f32_16x16x32_bf16 v[0:3], v[194:197], v[170:173], v[0:3]
	v_mfma_f32_16x16x32_bf16 v[52:55], v[190:193], v[148:151], v[52:55]
	v_mfma_f32_16x16x32_bf16 v[48:51], v[198:201], v[148:151], v[48:51]
	v_mfma_f32_16x16x32_bf16 v[36:39], v[190:193], v[156:159], v[36:39]
	v_mfma_f32_16x16x32_bf16 v[32:35], v[198:201], v[156:159], v[32:35]
	v_mfma_f32_16x16x32_bf16 v[20:23], v[190:193], v[164:167], v[20:23]
	v_mfma_f32_16x16x32_bf16 v[16:19], v[198:201], v[164:167], v[16:19]
	v_mfma_f32_16x16x32_bf16 v[4:7], v[190:193], v[182:185], v[4:7]
	v_mfma_f32_16x16x32_bf16 v[0:3], v[198:201], v[182:185], v[0:3]
	s_add_u32 s56, s56, 0x100
	s_addc_u32 s57, s57, 0
	s_add_u32 vcc_hi, vcc_hi, 0x100
	s_addc_u32 s18, s18, 0
	s_cmp_ge_i32 s29, s5
	s_mov_b32 s58, s29
	s_barrier
	s_cbranch_scc0 .LBB0_137
	s_branch .LBB0_141

; #define PG8_STAGE(bufoff, gbase) do { _Pragma("unroll") for (int _i = 0; _i < 2; ++_i) \
;         __builtin_amdgcn_global_load_lds((const unsigned*)((const char*)(gbase) + voffA[_i]), (LAS unsigned*)(lds + (bufoff) + ldsw + _i * 8192), 16, 0, 0); } while (0)
; #define PG8_LDA(dst, b, h) do { _Pragma("unroll") for (int m = 0; m < 4; ++m) _Pragma("unroll") for (int k = 0; k < 2; ++k) dst[m][k] = *(const LAS bf16x8*)(lds + PG8_SA(b, h) + aoff + m * 2048 + k * 1024); } while (0)
; #define PG8_LDB(dst, b, h) do { _Pragma("unroll") for (int n = 0; n < 2; ++n) _Pragma("unroll") for (int k = 0; k < 2; ++k) dst[n][k] = *(const LAS bf16x8*)(lds + PG8_SB(b, h) + boff + n * 2048 + k * 1024); } while (0)
; #define PG8_MMA(ai, bj, At, Bt) do { __builtin_amdgcn_s_setprio(1); _Pragma("unroll") for (int m = 0; m < 4; ++m) _Pragma("unroll") for (int n = 0; n < 2; ++n) _Pragma("unroll") for (int k = 0; k < 2; ++k) \
;         acc[ai][bj][m][n] = __builtin_amdgcn_mfma_f32_16x16x32_bf16(Bt[n][k], At[m][k], acc[ai][bj][m][n], 0, 0, 0); __builtin_amdgcn_s_setprio(0); } while (0)
; #define PG8_WAIT_L(n) asm volatile("s_waitcnt lgkmcnt(" #n ")" ::: "memory")
; #define PG8_BAR __builtin_amdgcn_s_barrier()
; #define PG8_SCHED __builtin_amdgcn_sched_barrier(0)
; template <class Epi>
; DI void gemm_phase(const int TID, const int BID, LAS unsigned char* lds, const Gemm g, const Epi& E) {
;     ...
;         for (int t = 0; t < nt; t += 2) {
;             const bool last = (t == nt - 2);
;             const char* a1 = cA + (size_t)(t + 1) * kstep;
;             const char* a2 = last ? nA : cA + (size_t)(t + 2) * kstep; const char* b2 = last ? nB : cB + (size_t)(t + 2) * kstep;
;             const char* a3 = a2 + kstep; const char* b3 = b2 + kstep;
;             PG8_LDB(B0, 0, 0); PG8_SCHED; PG8_LDA(At, 0, 0); PG8_STAGE(PG8_SA(1, 1), a1 + hstep);
;             PG8_WAIT_L(8); PG8_BAR; PG8_WAIT_L(0); PG8_MMA(0, 0, At, B0); PG8_BAR; PG8_SCHED;
;             PG8_LDB(B1, 0, 1); PG8_STAGE(PG8_SB(0, 0), b2);
;             PG8_BAR; PG8_WAIT_L(0); PG8_MMA(0, 1, At, B1); PG8_BAR;
.LBB0_164:
	v_add_u32_e32 v138, s16, v141
	ds_read_b128 v[134:137], v138
	ds_read_b128 v[144:147], v138 offset:1024
	ds_read_b128 v[148:151], v138 offset:2048
	ds_read_b128 v[152:155], v138 offset:3072
	s_add_i32 s80, s56, 2
	s_add_u32 s58, s54, 0x80
	s_addc_u32 s57, s55, 0
	s_cmp_eq_u32 s62, s56
	s_cselect_b32 s56, s12, s58
	s_cselect_b32 s57, s13, s57
	s_cselect_b32 s59, s53, s77
	s_cselect_b32 s58, s52, s76
	v_lshl_add_u64 v[138:139], s[54:55], 0, v[130:131]
	s_add_i32 m0, s19, 0xc000
	ds_read_b128 v[156:159], v143
	ds_read_b128 v[160:163], v143 offset:1024
	ds_read_b128 v[164:167], v143 offset:2048
	ds_read_b128 v[170:173], v143 offset:3072
	ds_read_b128 v[176:179], v143 offset:4096
	ds_read_b128 v[180:183], v143 offset:5120
	ds_read_b128 v[184:187], v143 offset:6144
	ds_read_b128 v[188:191], v143 offset:7168
	global_load_lds_dwordx4 v[138:139], off
	v_lshl_add_u64 v[138:139], s[54:55], 0, v[132:133]
	s_add_i32 m0, s19, 0xe000
	s_nop 0
	global_load_lds_dwordx4 v[138:139], off
	v_add_u32_e32 v138, s21, v141
	ds_read_b128 v[192:195], v138
	ds_read_b128 v[196:199], v138 offset:1024
	ds_read_b128 v[200:203], v138 offset:2048
	ds_read_b128 v[204:207], v138 offset:3072
	s_waitcnt vmcnt(8)
	s_waitcnt lgkmcnt(0)
	s_barrier
	v_mfma_f32_16x16x32_bf16 v[124:127], v[134:137], v[156:159], v[124:127]
	v_mfma_f32_16x16x32_bf16 v[120:123], v[148:151], v[156:159], v[120:123]
	v_mfma_f32_16x16x32_bf16 v[108:111], v[134:137], v[164:167], v[108:111]
	v_mfma_f32_16x16x32_bf16 v[104:107], v[148:151], v[164:167], v[104:107]
	v_mfma_f32_16x16x32_bf16 v[92:95], v[134:137], v[176:179], v[92:95]
	v_mfma_f32_16x16x32_bf16 v[88:91], v[148:151], v[176:179], v[88:91]
	v_mfma_f32_16x16x32_bf16 v[76:79], v[134:137], v[184:187], v[76:79]
	v_mfma_f32_16x16x32_bf16 v[72:75], v[148:151], v[184:187], v[72:75]
	v_mfma_f32_16x16x32_bf16 v[124:127], v[144:147], v[160:163], v[124:127]
	v_mfma_f32_16x16x32_bf16 v[120:123], v[152:155], v[160:163], v[120:123]
	v_mfma_f32_16x16x32_bf16 v[108:111], v[144:147], v[170:173], v[108:111]
	v_mfma_f32_16x16x32_bf16 v[104:107], v[152:155], v[170:173], v[104:107]
	v_mfma_f32_16x16x32_bf16 v[92:95], v[144:147], v[180:183], v[92:95]
	v_mfma_f32_16x16x32_bf16 v[88:91], v[152:155], v[180:183], v[88:91]
	v_mfma_f32_16x16x32_bf16 v[76:79], v[144:147], v[188:191], v[76:79]
	v_mfma_f32_16x16x32_bf16 v[72:75], v[152:155], v[188:191], v[72:75]
	v_mfma_f32_16x16x32_bf16 v[116:119], v[192:195], v[156:159], v[116:119]
	v_mfma_f32_16x16x32_bf16 v[112:115], v[200:203], v[156:159], v[112:115]
	v_mfma_f32_16x16x32_bf16 v[100:103], v[192:195], v[164:167], v[100:103]
	v_mfma_f32_16x16x32_bf16 v[96:99], v[200:203], v[164:167], v[96:99]
	v_mfma_f32_16x16x32_bf16 v[84:87], v[192:195], v[176:179], v[84:87]
	v_mfma_f32_16x16x32_bf16 v[80:83], v[200:203], v[176:179], v[80:83]
	v_mfma_f32_16x16x32_bf16 v[68:71], v[192:195], v[184:187], v[68:71]
	v_mfma_f32_16x16x32_bf16 v[64:67], v[200:203], v[184:187], v[64:67]
	v_mfma_f32_16x16x32_bf16 v[116:119], v[196:199], v[160:163], v[116:119]
	v_mfma_f32_16x16x32_bf16 v[112:115], v[204:207], v[160:163], v[112:115]
	v_mfma_f32_16x16x32_bf16 v[100:103], v[196:199], v[170:173], v[100:103]
	v_mfma_f32_16x16x32_bf16 v[96:99], v[204:207], v[170:173], v[96:99]
	v_mfma_f32_16x16x32_bf16 v[84:87], v[196:199], v[180:183], v[84:87]
	v_mfma_f32_16x16x32_bf16 v[80:83], v[204:207], v[180:183], v[80:83]
	v_mfma_f32_16x16x32_bf16 v[68:71], v[196:199], v[188:191], v[68:71]
	v_mfma_f32_16x16x32_bf16 v[64:67], v[204:207], v[188:191], v[64:67]
	s_barrier
	s_mov_b32 m0, s17
	v_lshl_add_u64 v[138:139], s[58:59], 0, v[168:169]
	global_load_lds_dwordx4 v[138:139], off
	v_lshl_add_u64 v[208:209], s[58:59], 0, v[128:129]
	s_mov_b32 m0, s18
	s_nop 0
	global_load_lds_dwordx4 v[208:209], off
	s_mov_b32 m0, s19
	v_lshl_add_u64 v[210:211], s[56:57], 0, v[168:169]
	global_load_lds_dwordx4 v[210:211], off
	v_lshl_add_u64 v[212:213], s[56:57], 0, v[128:129]
	s_mov_b32 m0, s20
	s_nop 0
	global_load_lds_dwordx4 v[212:213], off
	s_add_u32 s58, s58, s0
	s_addc_u32 s59, s59, s1
	s_mov_b32 m0, s22
	v_lshl_add_u64 v[214:215], s[58:59], 0, v[168:169]
	global_load_lds_dwordx4 v[214:215], off
	v_lshl_add_u64 v[216:217], s[58:59], 0, v[128:129]
	s_mov_b32 m0, s23
	s_nop 0
	global_load_lds_dwordx4 v[216:217], off
	ds_read_b128 v[156:159], v143 offset:16384
	ds_read_b128 v[160:163], v143 offset:17408
	ds_read_b128 v[164:167], v143 offset:18432
	ds_read_b128 v[170:173], v143 offset:19456
	ds_read_b128 v[176:179], v143 offset:20480
	ds_read_b128 v[180:183], v143 offset:21504
	ds_read_b128 v[184:187], v143 offset:22528
	ds_read_b128 v[188:191], v143 offset:23552
	s_waitcnt vmcnt(8)
	s_waitcnt lgkmcnt(0)
	s_barrier
; #define PG8_STAGE(bufoff, gbase) do { _Pragma("unroll") for (int _i = 0; _i < 2; ++_i) \
;         __builtin_amdgcn_global_load_lds((const unsigned*)((const char*)(gbase) + voffA[_i]), (LAS unsigned*)(lds + (bufoff) + ldsw + _i * 8192), 16, 0, 0); } while (0)
; #define PG8_LDA(dst, b, h) do { _Pragma("unroll") for (int m = 0; m < 4; ++m) _Pragma("unroll") for (int k = 0; k < 2; ++k) dst[m][k] = *(const LAS bf16x8*)(lds + PG8_SA(b, h) + aoff + m * 2048 + k * 1024); } while (0)
; #define PG8_LDB(dst, b, h) do { _Pragma("unroll") for (int n = 0; n < 2; ++n) _Pragma("unroll") for (int k = 0; k < 2; ++k) dst[n][k] = *(const LAS bf16x8*)(lds + PG8_SB(b, h) + boff + n * 2048 + k * 1024); } while (0)
; #define PG8_MMA(ai, bj, At, Bt) do { __builtin_amdgcn_s_setprio(1); _Pragma("unroll") for (int m = 0; m < 4; ++m) _Pragma("unroll") for (int n = 0; n < 2; ++n) _Pragma("unroll") for (int k = 0; k < 2; ++k) \
;         acc[ai][bj][m][n] = __builtin_amdgcn_mfma_f32_16x16x32_bf16(Bt[n][k], At[m][k], acc[ai][bj][m][n], 0, 0, 0); __builtin_amdgcn_s_setprio(0); } while (0)
; #define PG8_WAIT_V(n) asm volatile("s_waitcnt vmcnt(" #n ")" ::: "memory")
; #define PG8_WAIT_L(n) asm volatile("s_waitcnt lgkmcnt(" #n ")" ::: "memory")
; #define PG8_BAR __builtin_amdgcn_s_barrier()
; #define PG8_SCHED __builtin_amdgcn_sched_barrier(0)
; template <class Epi>
; DI void gemm_phase(const int TID, const int BID, LAS unsigned char* lds, const Gemm g, const Epi& E) {
;     ...
;             PG8_BAR; PG8_WAIT_L(0); PG8_MMA(0, 1, At, B1); PG8_BAR;
;             PG8_LDA(At, 0, 1); PG8_STAGE(PG8_SA(0, 0), a2);
;             PG8_BAR; PG8_WAIT_L(0); PG8_MMA(1, 0, At, B0); PG8_BAR; PG8_SCHED;
;             PG8_STAGE(PG8_SB(0, 1), b2 + hstep);
;             PG8_WAIT_V(6); PG8_BAR; PG8_MMA(1, 1, At, B1); PG8_BAR;
;             PG8_LDB(B0, 1, 0); PG8_SCHED; PG8_LDA(At, 1, 0); PG8_STAGE(PG8_SA(0, 1), a2 + hstep);
;             PG8_WAIT_L(8); PG8_BAR; PG8_WAIT_L(0); PG8_MMA(0, 0, At, B0); PG8_BAR; PG8_SCHED;
	v_mfma_f32_16x16x32_bf16 v[60:63], v[134:137], v[156:159], v[60:63]
	v_mfma_f32_16x16x32_bf16 v[56:59], v[148:151], v[156:159], v[56:59]
	v_mfma_f32_16x16x32_bf16 v[44:47], v[134:137], v[164:167], v[44:47]
	v_mfma_f32_16x16x32_bf16 v[40:43], v[148:151], v[164:167], v[40:43]
	v_mfma_f32_16x16x32_bf16 v[28:31], v[134:137], v[176:179], v[28:31]
	v_mfma_f32_16x16x32_bf16 v[24:27], v[148:151], v[176:179], v[24:27]
	v_mfma_f32_16x16x32_bf16 v[12:15], v[134:137], v[184:187], v[12:15]
	v_mfma_f32_16x16x32_bf16 v[8:11], v[148:151], v[184:187], v[8:11]
	v_mfma_f32_16x16x32_bf16 v[60:63], v[144:147], v[160:163], v[60:63]
	v_mfma_f32_16x16x32_bf16 v[56:59], v[152:155], v[160:163], v[56:59]
	v_mfma_f32_16x16x32_bf16 v[44:47], v[144:147], v[170:173], v[44:47]
	v_mfma_f32_16x16x32_bf16 v[40:43], v[152:155], v[170:173], v[40:43]
	v_mfma_f32_16x16x32_bf16 v[28:31], v[144:147], v[180:183], v[28:31]
	v_mfma_f32_16x16x32_bf16 v[24:27], v[152:155], v[180:183], v[24:27]
	v_mfma_f32_16x16x32_bf16 v[12:15], v[144:147], v[188:191], v[12:15]
	v_mfma_f32_16x16x32_bf16 v[8:11], v[152:155], v[188:191], v[8:11]
	v_mfma_f32_16x16x32_bf16 v[52:55], v[192:195], v[156:159], v[52:55]
	v_mfma_f32_16x16x32_bf16 v[48:51], v[200:203], v[156:159], v[48:51]
	v_mfma_f32_16x16x32_bf16 v[36:39], v[192:195], v[164:167], v[36:39]
	v_mfma_f32_16x16x32_bf16 v[32:35], v[200:203], v[164:167], v[32:35]
	v_mfma_f32_16x16x32_bf16 v[20:23], v[192:195], v[176:179], v[20:23]
	v_mfma_f32_16x16x32_bf16 v[16:19], v[200:203], v[176:179], v[16:19]
	v_mfma_f32_16x16x32_bf16 v[4:7], v[192:195], v[184:187], v[4:7]
	v_mfma_f32_16x16x32_bf16 v[0:3], v[200:203], v[184:187], v[0:3]
	v_mfma_f32_16x16x32_bf16 v[52:55], v[196:199], v[160:163], v[52:55]
	v_mfma_f32_16x16x32_bf16 v[48:51], v[204:207], v[160:163], v[48:51]
	v_mfma_f32_16x16x32_bf16 v[36:39], v[196:199], v[170:173], v[36:39]
	v_mfma_f32_16x16x32_bf16 v[32:35], v[204:207], v[170:173], v[32:35]
	v_mfma_f32_16x16x32_bf16 v[20:23], v[196:199], v[180:183], v[20:23]
	v_mfma_f32_16x16x32_bf16 v[16:19], v[204:207], v[180:183], v[16:19]
	v_mfma_f32_16x16x32_bf16 v[4:7], v[196:199], v[188:191], v[4:7]
	v_mfma_f32_16x16x32_bf16 v[0:3], v[204:207], v[188:191], v[0:3]
	s_barrier
	s_add_u32 s56, s56, s0
	s_addc_u32 s57, s57, s1
	s_mov_b32 m0, s24
	v_lshl_add_u64 v[192:193], s[56:57], 0, v[168:169]
	global_load_lds_dwordx4 v[192:193], off
	v_lshl_add_u64 v[192:193], s[56:57], 0, v[128:129]
	s_mov_b32 m0, s25
	s_nop 0
	global_load_lds_dwordx4 v[192:193], off
	v_add_u32_e32 v152, s27, v141
	ds_read_b128 v[134:137], v152
	ds_read_b128 v[144:147], v152 offset:1024
	ds_read_b128 v[148:151], v152 offset:2048
	ds_read_b128 v[152:155], v152 offset:3072
	ds_read_b128 v[156:159], v143 offset:32768
	ds_read_b128 v[160:163], v143 offset:33792
	ds_read_b128 v[164:167], v143 offset:34816
	ds_read_b128 v[170:173], v143 offset:35840
	ds_read_b128 v[176:179], v143 offset:36864
	ds_read_b128 v[180:183], v143 offset:37888
	ds_read_b128 v[184:187], v143 offset:38912
	ds_read_b128 v[188:191], v143 offset:39936
	v_add_u32_e32 v175, s33, v141
	ds_read_b128 v[192:195], v175
	ds_read_b128 v[196:199], v175 offset:1024
	ds_read_b128 v[200:203], v175 offset:2048
	ds_read_b128 v[204:207], v175 offset:3072
	s_waitcnt vmcnt(8)
	s_waitcnt lgkmcnt(0)
	s_barrier
	v_mfma_f32_16x16x32_bf16 v[124:127], v[134:137], v[156:159], v[124:127]
	v_mfma_f32_16x16x32_bf16 v[120:123], v[148:151], v[156:159], v[120:123]
	v_mfma_f32_16x16x32_bf16 v[108:111], v[134:137], v[164:167], v[108:111]
	v_mfma_f32_16x16x32_bf16 v[104:107], v[148:151], v[164:167], v[104:107]
	v_mfma_f32_16x16x32_bf16 v[92:95], v[134:137], v[176:179], v[92:95]
	v_mfma_f32_16x16x32_bf16 v[88:91], v[148:151], v[176:179], v[88:91]
	v_mfma_f32_16x16x32_bf16 v[76:79], v[134:137], v[184:187], v[76:79]
	v_mfma_f32_16x16x32_bf16 v[72:75], v[148:151], v[184:187], v[72:75]
	v_mfma_f32_16x16x32_bf16 v[124:127], v[144:147], v[160:163], v[124:127]
	v_mfma_f32_16x16x32_bf16 v[120:123], v[152:155], v[160:163], v[120:123]
	v_mfma_f32_16x16x32_bf16 v[108:111], v[144:147], v[170:173], v[108:111]
	v_mfma_f32_16x16x32_bf16 v[104:107], v[152:155], v[170:173], v[104:107]
	v_mfma_f32_16x16x32_bf16 v[92:95], v[144:147], v[180:183], v[92:95]
	v_mfma_f32_16x16x32_bf16 v[88:91], v[152:155], v[180:183], v[88:91]
	v_mfma_f32_16x16x32_bf16 v[76:79], v[144:147], v[188:191], v[76:79]
	v_mfma_f32_16x16x32_bf16 v[72:75], v[152:155], v[188:191], v[72:75]
	v_mfma_f32_16x16x32_bf16 v[116:119], v[192:195], v[156:159], v[116:119]
	v_mfma_f32_16x16x32_bf16 v[112:115], v[200:203], v[156:159], v[112:115]
	v_mfma_f32_16x16x32_bf16 v[100:103], v[192:195], v[164:167], v[100:103]
	v_mfma_f32_16x16x32_bf16 v[96:99], v[200:203], v[164:167], v[96:99]
	v_mfma_f32_16x16x32_bf16 v[84:87], v[192:195], v[176:179], v[84:87]
	v_mfma_f32_16x16x32_bf16 v[80:83], v[200:203], v[176:179], v[80:83]
	v_mfma_f32_16x16x32_bf16 v[68:71], v[192:195], v[184:187], v[68:71]
	v_mfma_f32_16x16x32_bf16 v[64:67], v[200:203], v[184:187], v[64:67]
	v_mfma_f32_16x16x32_bf16 v[116:119], v[196:199], v[160:163], v[116:119]
	v_mfma_f32_16x16x32_bf16 v[112:115], v[204:207], v[160:163], v[112:115]
	v_mfma_f32_16x16x32_bf16 v[100:103], v[196:199], v[170:173], v[100:103]
	v_mfma_f32_16x16x32_bf16 v[96:99], v[204:207], v[170:173], v[96:99]
	v_mfma_f32_16x16x32_bf16 v[84:87], v[196:199], v[180:183], v[84:87]
	v_mfma_f32_16x16x32_bf16 v[80:83], v[204:207], v[180:183], v[80:83]
	v_mfma_f32_16x16x32_bf16 v[68:71], v[196:199], v[188:191], v[68:71]
	v_mfma_f32_16x16x32_bf16 v[64:67], v[204:207], v[188:191], v[64:67]
	s_barrier
; #define PG8_STAGE(bufoff, gbase) do { _Pragma("unroll") for (int _i = 0; _i < 2; ++_i) \
;         __builtin_amdgcn_global_load_lds((const unsigned*)((const char*)(gbase) + voffA[_i]), (LAS unsigned*)(lds + (bufoff) + ldsw + _i * 8192), 16, 0, 0); } while (0)
; #define PG8_LDA(dst, b, h) do { _Pragma("unroll") for (int m = 0; m < 4; ++m) _Pragma("unroll") for (int k = 0; k < 2; ++k) dst[m][k] = *(const LAS bf16x8*)(lds + PG8_SA(b, h) + aoff + m * 2048 + k * 1024); } while (0)
; #define PG8_LDB(dst, b, h) do { _Pragma("unroll") for (int n = 0; n < 2; ++n) _Pragma("unroll") for (int k = 0; k < 2; ++k) dst[n][k] = *(const LAS bf16x8*)(lds + PG8_SB(b, h) + boff + n * 2048 + k * 1024); } while (0)
; #define PG8_MMA(ai, bj, At, Bt) do { __builtin_amdgcn_s_setprio(1); _Pragma("unroll") for (int m = 0; m < 4; ++m) _Pragma("unroll") for (int n = 0; n < 2; ++n) _Pragma("unroll") for (int k = 0; k < 2; ++k) \
;         acc[ai][bj][m][n] = __builtin_amdgcn_mfma_f32_16x16x32_bf16(Bt[n][k], At[m][k], acc[ai][bj][m][n], 0, 0, 0); __builtin_amdgcn_s_setprio(0); } while (0)
; #define PG8_WAIT_V(n) asm volatile("s_waitcnt vmcnt(" #n ")" ::: "memory")
; #define PG8_WAIT_L(n) asm volatile("s_waitcnt lgkmcnt(" #n ")" ::: "memory")
; #define PG8_BAR __builtin_amdgcn_s_barrier()
; #define PG8_SCHED __builtin_amdgcn_sched_barrier(0)
; template <class Epi>
; DI void gemm_phase(const int TID, const int BID, LAS unsigned char* lds, const Gemm g, const Epi& E) {
;     ...
;             PG8_LDB(B1, 1, 1); PG8_STAGE(PG8_SB(1, 0), b3);
;             PG8_BAR; PG8_WAIT_L(0); PG8_MMA(0, 1, At, B1); PG8_BAR;
;             PG8_LDA(At, 1, 1); PG8_STAGE(PG8_SA(1, 0), a3);
;             PG8_BAR; PG8_WAIT_L(0); PG8_MMA(1, 0, At, B0); PG8_BAR; PG8_SCHED;
;             PG8_STAGE(PG8_SB(1, 1), b3 + hstep);
;             PG8_WAIT_V(6); PG8_BAR; PG8_MMA(1, 1, At, B1); PG8_BAR;
;         }
	s_mov_b32 m0, s28
	v_lshl_add_u64 v[138:139], v[138:139], 0, s[92:93]
	global_load_lds_dwordx4 v[138:139], off
	v_lshl_add_u64 v[138:139], v[208:209], 0, s[92:93]
	s_mov_b32 m0, s29
	s_nop 0
	global_load_lds_dwordx4 v[138:139], off
	s_mov_b32 m0, s30
	v_lshl_add_u64 v[138:139], v[210:211], 0, s[92:93]
	global_load_lds_dwordx4 v[138:139], off
	v_lshl_add_u64 v[138:139], v[212:213], 0, s[92:93]
	s_mov_b32 m0, s31
	s_nop 0
	global_load_lds_dwordx4 v[138:139], off
	s_mov_b32 m0, s60
	v_lshl_add_u64 v[138:139], v[214:215], 0, s[92:93]
	global_load_lds_dwordx4 v[138:139], off
	v_lshl_add_u64 v[138:139], v[216:217], 0, s[92:93]
	s_mov_b32 m0, s61
	s_nop 0
	global_load_lds_dwordx4 v[138:139], off
	ds_read_b128 v[156:159], v143 offset:49152
	ds_read_b128 v[160:163], v143 offset:50176
	ds_read_b128 v[164:167], v143 offset:51200
	ds_read_b128 v[170:173], v143 offset:52224
	ds_read_b128 v[176:179], v143 offset:53248
	ds_read_b128 v[180:183], v143 offset:54272
	ds_read_b128 v[184:187], v143 offset:55296
	ds_read_b128 v[188:191], v143 offset:56320
	s_waitcnt vmcnt(8)
	s_waitcnt lgkmcnt(0)
	s_barrier
	v_mfma_f32_16x16x32_bf16 v[60:63], v[134:137], v[156:159], v[60:63]
	v_mfma_f32_16x16x32_bf16 v[56:59], v[148:151], v[156:159], v[56:59]
	v_mfma_f32_16x16x32_bf16 v[44:47], v[134:137], v[164:167], v[44:47]
	v_mfma_f32_16x16x32_bf16 v[40:43], v[148:151], v[164:167], v[40:43]
	v_mfma_f32_16x16x32_bf16 v[28:31], v[134:137], v[176:179], v[28:31]
	v_mfma_f32_16x16x32_bf16 v[24:27], v[148:151], v[176:179], v[24:27]
	v_mfma_f32_16x16x32_bf16 v[12:15], v[134:137], v[184:187], v[12:15]
	v_mfma_f32_16x16x32_bf16 v[8:11], v[148:151], v[184:187], v[8:11]
	v_mfma_f32_16x16x32_bf16 v[60:63], v[144:147], v[160:163], v[60:63]
	v_mfma_f32_16x16x32_bf16 v[56:59], v[152:155], v[160:163], v[56:59]
	v_mfma_f32_16x16x32_bf16 v[44:47], v[144:147], v[170:173], v[44:47]
	v_mfma_f32_16x16x32_bf16 v[40:43], v[152:155], v[170:173], v[40:43]
	v_mfma_f32_16x16x32_bf16 v[28:31], v[144:147], v[180:183], v[28:31]
	v_mfma_f32_16x16x32_bf16 v[24:27], v[152:155], v[180:183], v[24:27]
	v_mfma_f32_16x16x32_bf16 v[12:15], v[144:147], v[188:191], v[12:15]
	v_mfma_f32_16x16x32_bf16 v[8:11], v[152:155], v[188:191], v[8:11]
	v_mfma_f32_16x16x32_bf16 v[52:55], v[192:195], v[156:159], v[52:55]
	v_mfma_f32_16x16x32_bf16 v[48:51], v[200:203], v[156:159], v[48:51]
	v_mfma_f32_16x16x32_bf16 v[36:39], v[192:195], v[164:167], v[36:39]
	v_mfma_f32_16x16x32_bf16 v[32:35], v[200:203], v[164:167], v[32:35]
	v_mfma_f32_16x16x32_bf16 v[20:23], v[192:195], v[176:179], v[20:23]
	v_mfma_f32_16x16x32_bf16 v[16:19], v[200:203], v[176:179], v[16:19]
	v_mfma_f32_16x16x32_bf16 v[4:7], v[192:195], v[184:187], v[4:7]
	v_mfma_f32_16x16x32_bf16 v[0:3], v[200:203], v[184:187], v[0:3]
	v_mfma_f32_16x16x32_bf16 v[52:55], v[196:199], v[160:163], v[52:55]
	v_mfma_f32_16x16x32_bf16 v[48:51], v[204:207], v[160:163], v[48:51]
	v_mfma_f32_16x16x32_bf16 v[36:39], v[196:199], v[170:173], v[36:39]
	v_mfma_f32_16x16x32_bf16 v[32:35], v[204:207], v[170:173], v[32:35]
	v_mfma_f32_16x16x32_bf16 v[20:23], v[196:199], v[180:183], v[20:23]
	v_mfma_f32_16x16x32_bf16 v[16:19], v[204:207], v[180:183], v[16:19]
	v_mfma_f32_16x16x32_bf16 v[4:7], v[196:199], v[188:191], v[4:7]
	v_mfma_f32_16x16x32_bf16 v[0:3], v[204:207], v[188:191], v[0:3]
	s_add_u32 s54, s54, 0x100
	s_addc_u32 s55, s55, 0
	s_add_u32 s76, s76, 0x100
	s_addc_u32 s77, s77, 0
	s_cmp_ge_i32 s80, s26
	s_mov_b32 s56, s80
	s_barrier
	s_cbranch_scc0 .LBB0_164
	v_readlane_b32 s76, v255, 9
	v_readlane_b32 s77, v255, 10
	s_branch .LBB0_155

; #define PG8_STAGE(bufoff, gbase) do { _Pragma("unroll") for (int _i = 0; _i < 2; ++_i) \
;         __builtin_amdgcn_global_load_lds((const unsigned*)((const char*)(gbase) + voffA[_i]), (LAS unsigned*)(lds + (bufoff) + ldsw + _i * 8192), 16, 0, 0); } while (0)
; #define PG8_LDA(dst, b, h) do { _Pragma("unroll") for (int m = 0; m < 4; ++m) _Pragma("unroll") for (int k = 0; k < 2; ++k) dst[m][k] = *(const LAS bf16x8*)(lds + PG8_SA(b, h) + aoff + m * 2048 + k * 1024); } while (0)
; #define PG8_LDB(dst, b, h) do { _Pragma("unroll") for (int n = 0; n < 2; ++n) _Pragma("unroll") for (int k = 0; k < 2; ++k) dst[n][k] = *(const LAS bf16x8*)(lds + PG8_SB(b, h) + boff + n * 2048 + k * 1024); } while (0)
; #define PG8_MMA(ai, bj, At, Bt) do { __builtin_amdgcn_s_setprio(1); _Pragma("unroll") for (int m = 0; m < 4; ++m) _Pragma("unroll") for (int n = 0; n < 2; ++n) _Pragma("unroll") for (int k = 0; k < 2; ++k) \
;         acc[ai][bj][m][n] = __builtin_amdgcn_mfma_f32_16x16x32_bf16(Bt[n][k], At[m][k], acc[ai][bj][m][n], 0, 0, 0); __builtin_amdgcn_s_setprio(0); } while (0)
; #define PG8_WAIT_L(n) asm volatile("s_waitcnt lgkmcnt(" #n ")" ::: "memory")
; #define PG8_BAR __builtin_amdgcn_s_barrier()
; #define PG8_SCHED __builtin_amdgcn_sched_barrier(0)
; template <class Epi>
; DI void gemm_phase(const int TID, const int BID, LAS unsigned char* lds, const Gemm g, const Epi& E) {
;     ...
;         for (int t = 0; t < nt; t += 2) {
;             const bool last = (t == nt - 2);
;             const char* a1 = cA + (size_t)(t + 1) * kstep;
;             const char* a2 = last ? nA : cA + (size_t)(t + 2) * kstep; const char* b2 = last ? nB : cB + (size_t)(t + 2) * kstep;
;             const char* a3 = a2 + kstep; const char* b3 = b2 + kstep;
;             PG8_LDB(B0, 0, 0); PG8_SCHED; PG8_LDA(At, 0, 0); PG8_STAGE(PG8_SA(1, 1), a1 + hstep);
;             PG8_WAIT_L(8); PG8_BAR; PG8_WAIT_L(0); PG8_MMA(0, 0, At, B0); PG8_BAR; PG8_SCHED;
;             PG8_LDB(B1, 0, 1); PG8_STAGE(PG8_SB(0, 0), b2);
;             PG8_BAR; PG8_WAIT_L(0); PG8_MMA(0, 1, At, B1); PG8_BAR;
.LBB0_230:
	s_add_i32 s58, s54, 2
	s_add_u32 s56, s52, 0x80
	s_addc_u32 s55, s53, 0
	s_cmp_eq_u32 vcc_lo, s54
	s_cselect_b32 s54, s12, s56
	s_cselect_b32 s55, s13, s55
	s_cselect_b32 s57, s1, s29
	s_cselect_b32 s56, s0, vcc_hi
	v_lshl_add_u64 v[186:187], s[52:53], 0, v[178:179]
	s_add_i32 m0, s21, 0xc000
	global_load_lds_dwordx4 v[186:187], off
	v_lshl_add_u64 v[186:187], s[52:53], 0, v[180:181]
	s_add_i32 m0, s21, 0xe000
	s_nop 0
	global_load_lds_dwordx4 v[186:187], off
	v_add_u32_e32 v140, s18, v246
	ds_read_b128 v[128:131], v140
	ds_read_b128 v[132:135], v140 offset:1024
	ds_read_b128 v[136:139], v140 offset:2048
	ds_read_b128 v[140:143], v140 offset:3072
	ds_read_b128 v[144:147], v248
	ds_read_b128 v[148:151], v248 offset:1024
	ds_read_b128 v[152:155], v248 offset:2048
	ds_read_b128 v[156:159], v248 offset:3072
	ds_read_b128 v[160:163], v248 offset:4096
	ds_read_b128 v[164:167], v248 offset:5120
	ds_read_b128 v[170:173], v248 offset:6144
	ds_read_b128 v[182:185], v248 offset:7168
	v_add_u32_e32 v198, s23, v246
	ds_read_b128 v[186:189], v198
	ds_read_b128 v[190:193], v198 offset:1024
	ds_read_b128 v[194:197], v198 offset:2048
	ds_read_b128 v[198:201], v198 offset:3072
	s_waitcnt vmcnt(8)
	s_waitcnt lgkmcnt(0)
	s_barrier
	v_mfma_f32_16x16x32_bf16 v[124:127], v[128:131], v[144:147], v[124:127]
	v_mfma_f32_16x16x32_bf16 v[120:123], v[136:139], v[144:147], v[120:123]
	v_mfma_f32_16x16x32_bf16 v[108:111], v[128:131], v[152:155], v[108:111]
	v_mfma_f32_16x16x32_bf16 v[104:107], v[136:139], v[152:155], v[104:107]
	v_mfma_f32_16x16x32_bf16 v[92:95], v[128:131], v[160:163], v[92:95]
	v_mfma_f32_16x16x32_bf16 v[88:91], v[136:139], v[160:163], v[88:91]
	v_mfma_f32_16x16x32_bf16 v[76:79], v[128:131], v[170:173], v[76:79]
	v_mfma_f32_16x16x32_bf16 v[72:75], v[136:139], v[170:173], v[72:75]
	v_mfma_f32_16x16x32_bf16 v[124:127], v[132:135], v[148:151], v[124:127]
	v_mfma_f32_16x16x32_bf16 v[120:123], v[140:143], v[148:151], v[120:123]
	v_mfma_f32_16x16x32_bf16 v[108:111], v[132:135], v[156:159], v[108:111]
	v_mfma_f32_16x16x32_bf16 v[104:107], v[140:143], v[156:159], v[104:107]
	v_mfma_f32_16x16x32_bf16 v[92:95], v[132:135], v[164:167], v[92:95]
	v_mfma_f32_16x16x32_bf16 v[88:91], v[140:143], v[164:167], v[88:91]
	v_mfma_f32_16x16x32_bf16 v[76:79], v[132:135], v[182:185], v[76:79]
	v_mfma_f32_16x16x32_bf16 v[72:75], v[140:143], v[182:185], v[72:75]
	v_mfma_f32_16x16x32_bf16 v[116:119], v[186:189], v[144:147], v[116:119]
	v_mfma_f32_16x16x32_bf16 v[112:115], v[194:197], v[144:147], v[112:115]
	v_mfma_f32_16x16x32_bf16 v[100:103], v[186:189], v[152:155], v[100:103]
	v_mfma_f32_16x16x32_bf16 v[96:99], v[194:197], v[152:155], v[96:99]
	v_mfma_f32_16x16x32_bf16 v[84:87], v[186:189], v[160:163], v[84:87]
	v_mfma_f32_16x16x32_bf16 v[80:83], v[194:197], v[160:163], v[80:83]
	v_mfma_f32_16x16x32_bf16 v[68:71], v[186:189], v[170:173], v[68:71]
	v_mfma_f32_16x16x32_bf16 v[64:67], v[194:197], v[170:173], v[64:67]
	v_mfma_f32_16x16x32_bf16 v[116:119], v[190:193], v[148:151], v[116:119]
	v_mfma_f32_16x16x32_bf16 v[112:115], v[198:201], v[148:151], v[112:115]
	v_mfma_f32_16x16x32_bf16 v[100:103], v[190:193], v[156:159], v[100:103]
	v_mfma_f32_16x16x32_bf16 v[96:99], v[198:201], v[156:159], v[96:99]
	v_mfma_f32_16x16x32_bf16 v[84:87], v[190:193], v[164:167], v[84:87]
	v_mfma_f32_16x16x32_bf16 v[80:83], v[198:201], v[164:167], v[80:83]
	v_mfma_f32_16x16x32_bf16 v[68:71], v[190:193], v[182:185], v[68:71]
	v_mfma_f32_16x16x32_bf16 v[64:67], v[198:201], v[182:185], v[64:67]
	s_barrier
	s_mov_b32 m0, s19
	v_lshl_add_u64 v[202:203], s[56:57], 0, v[168:169]
	global_load_lds_dwordx4 v[202:203], off
	v_lshl_add_u64 v[204:205], s[56:57], 0, v[176:177]
	s_mov_b32 m0, s20
	s_nop 0
	global_load_lds_dwordx4 v[204:205], off
	s_mov_b32 m0, s21
	v_lshl_add_u64 v[206:207], s[54:55], 0, v[168:169]
	global_load_lds_dwordx4 v[206:207], off
	v_lshl_add_u64 v[208:209], s[54:55], 0, v[176:177]
	s_mov_b32 m0, s22
	s_nop 0
	global_load_lds_dwordx4 v[208:209], off
	s_add_u32 s56, s56, s2
	s_addc_u32 s57, s57, s3
	s_mov_b32 m0, s24
	v_lshl_add_u64 v[210:211], s[56:57], 0, v[168:169]
	global_load_lds_dwordx4 v[210:211], off
	v_lshl_add_u64 v[212:213], s[56:57], 0, v[176:177]
	s_mov_b32 m0, s25
	s_nop 0
	global_load_lds_dwordx4 v[212:213], off
	ds_read_b128 v[144:147], v248 offset:16384
	ds_read_b128 v[148:151], v248 offset:17408
	ds_read_b128 v[152:155], v248 offset:18432
	ds_read_b128 v[156:159], v248 offset:19456
	ds_read_b128 v[160:163], v248 offset:20480
	ds_read_b128 v[164:167], v248 offset:21504
	ds_read_b128 v[170:173], v248 offset:22528
	ds_read_b128 v[182:185], v248 offset:23552
	s_waitcnt vmcnt(8)
	s_waitcnt lgkmcnt(0)
	s_barrier
; #define PG8_STAGE(bufoff, gbase) do { _Pragma("unroll") for (int _i = 0; _i < 2; ++_i) \
;         __builtin_amdgcn_global_load_lds((const unsigned*)((const char*)(gbase) + voffA[_i]), (LAS unsigned*)(lds + (bufoff) + ldsw + _i * 8192), 16, 0, 0); } while (0)
; #define PG8_LDA(dst, b, h) do { _Pragma("unroll") for (int m = 0; m < 4; ++m) _Pragma("unroll") for (int k = 0; k < 2; ++k) dst[m][k] = *(const LAS bf16x8*)(lds + PG8_SA(b, h) + aoff + m * 2048 + k * 1024); } while (0)
; #define PG8_LDB(dst, b, h) do { _Pragma("unroll") for (int n = 0; n < 2; ++n) _Pragma("unroll") for (int k = 0; k < 2; ++k) dst[n][k] = *(const LAS bf16x8*)(lds + PG8_SB(b, h) + boff + n * 2048 + k * 1024); } while (0)
; #define PG8_MMA(ai, bj, At, Bt) do { __builtin_amdgcn_s_setprio(1); _Pragma("unroll") for (int m = 0; m < 4; ++m) _Pragma("unroll") for (int n = 0; n < 2; ++n) _Pragma("unroll") for (int k = 0; k < 2; ++k) \
;         acc[ai][bj][m][n] = __builtin_amdgcn_mfma_f32_16x16x32_bf16(Bt[n][k], At[m][k], acc[ai][bj][m][n], 0, 0, 0); __builtin_amdgcn_s_setprio(0); } while (0)
; #define PG8_WAIT_V(n) asm volatile("s_waitcnt vmcnt(" #n ")" ::: "memory")
; #define PG8_WAIT_L(n) asm volatile("s_waitcnt lgkmcnt(" #n ")" ::: "memory")
; #define PG8_BAR __builtin_amdgcn_s_barrier()
; #define PG8_SCHED __builtin_amdgcn_sched_barrier(0)
; template <class Epi>
; DI void gemm_phase(const int TID, const int BID, LAS unsigned char* lds, const Gemm g, const Epi& E) {
;     ...
;             PG8_BAR; PG8_WAIT_L(0); PG8_MMA(0, 1, At, B1); PG8_BAR;
;             PG8_LDA(At, 0, 1); PG8_STAGE(PG8_SA(0, 0), a2);
;             PG8_BAR; PG8_WAIT_L(0); PG8_MMA(1, 0, At, B0); PG8_BAR; PG8_SCHED;
;             PG8_STAGE(PG8_SB(0, 1), b2 + hstep);
;             PG8_WAIT_V(6); PG8_BAR; PG8_MMA(1, 1, At, B1); PG8_BAR;
;             PG8_LDB(B0, 1, 0); PG8_SCHED; PG8_LDA(At, 1, 0); PG8_STAGE(PG8_SA(0, 1), a2 + hstep);
;             PG8_WAIT_L(8); PG8_BAR; PG8_WAIT_L(0); PG8_MMA(0, 0, At, B0); PG8_BAR; PG8_SCHED;
	v_mfma_f32_16x16x32_bf16 v[60:63], v[128:131], v[144:147], v[60:63]
	v_mfma_f32_16x16x32_bf16 v[56:59], v[136:139], v[144:147], v[56:59]
	v_mfma_f32_16x16x32_bf16 v[44:47], v[128:131], v[152:155], v[44:47]
	v_mfma_f32_16x16x32_bf16 v[40:43], v[136:139], v[152:155], v[40:43]
	v_mfma_f32_16x16x32_bf16 v[28:31], v[128:131], v[160:163], v[28:31]
	v_mfma_f32_16x16x32_bf16 v[24:27], v[136:139], v[160:163], v[24:27]
	v_mfma_f32_16x16x32_bf16 v[12:15], v[128:131], v[170:173], v[12:15]
	v_mfma_f32_16x16x32_bf16 v[8:11], v[136:139], v[170:173], v[8:11]
	v_mfma_f32_16x16x32_bf16 v[60:63], v[132:135], v[148:151], v[60:63]
	v_mfma_f32_16x16x32_bf16 v[56:59], v[140:143], v[148:151], v[56:59]
	v_mfma_f32_16x16x32_bf16 v[44:47], v[132:135], v[156:159], v[44:47]
	v_mfma_f32_16x16x32_bf16 v[40:43], v[140:143], v[156:159], v[40:43]
	v_mfma_f32_16x16x32_bf16 v[28:31], v[132:135], v[164:167], v[28:31]
	v_mfma_f32_16x16x32_bf16 v[24:27], v[140:143], v[164:167], v[24:27]
	v_mfma_f32_16x16x32_bf16 v[12:15], v[132:135], v[182:185], v[12:15]
	v_mfma_f32_16x16x32_bf16 v[8:11], v[140:143], v[182:185], v[8:11]
	v_mfma_f32_16x16x32_bf16 v[52:55], v[186:189], v[144:147], v[52:55]
	v_mfma_f32_16x16x32_bf16 v[48:51], v[194:197], v[144:147], v[48:51]
	v_mfma_f32_16x16x32_bf16 v[36:39], v[186:189], v[152:155], v[36:39]
	v_mfma_f32_16x16x32_bf16 v[32:35], v[194:197], v[152:155], v[32:35]
	v_mfma_f32_16x16x32_bf16 v[20:23], v[186:189], v[160:163], v[20:23]
	v_mfma_f32_16x16x32_bf16 v[16:19], v[194:197], v[160:163], v[16:19]
	v_mfma_f32_16x16x32_bf16 v[4:7], v[186:189], v[170:173], v[4:7]
	v_mfma_f32_16x16x32_bf16 v[0:3], v[194:197], v[170:173], v[0:3]
	v_mfma_f32_16x16x32_bf16 v[52:55], v[190:193], v[148:151], v[52:55]
	v_mfma_f32_16x16x32_bf16 v[48:51], v[198:201], v[148:151], v[48:51]
	v_mfma_f32_16x16x32_bf16 v[36:39], v[190:193], v[156:159], v[36:39]
	v_mfma_f32_16x16x32_bf16 v[32:35], v[198:201], v[156:159], v[32:35]
	v_mfma_f32_16x16x32_bf16 v[20:23], v[190:193], v[164:167], v[20:23]
	v_mfma_f32_16x16x32_bf16 v[16:19], v[198:201], v[164:167], v[16:19]
	v_mfma_f32_16x16x32_bf16 v[4:7], v[190:193], v[182:185], v[4:7]
	v_mfma_f32_16x16x32_bf16 v[0:3], v[198:201], v[182:185], v[0:3]
	s_barrier
	s_add_u32 s54, s54, s2
	s_addc_u32 s55, s55, s3
	s_mov_b32 m0, s26
	v_lshl_add_u64 v[186:187], s[54:55], 0, v[168:169]
	global_load_lds_dwordx4 v[186:187], off
	v_lshl_add_u64 v[186:187], s[54:55], 0, v[176:177]
	s_mov_b32 m0, s27
	s_nop 0
	global_load_lds_dwordx4 v[186:187], off
	v_add_u32_e32 v140, s31, v246
	ds_read_b128 v[128:131], v140
	ds_read_b128 v[132:135], v140 offset:1024
	ds_read_b128 v[136:139], v140 offset:2048
	ds_read_b128 v[140:143], v140 offset:3072
	ds_read_b128 v[144:147], v248 offset:32768
	ds_read_b128 v[148:151], v248 offset:33792
	ds_read_b128 v[152:155], v248 offset:34816
	ds_read_b128 v[156:159], v248 offset:35840
	ds_read_b128 v[160:163], v248 offset:36864
	ds_read_b128 v[164:167], v248 offset:37888
	ds_read_b128 v[170:173], v248 offset:38912
	ds_read_b128 v[182:185], v248 offset:39936
	v_add_u32_e32 v198, s65, v246
	ds_read_b128 v[186:189], v198
	ds_read_b128 v[190:193], v198 offset:1024
	ds_read_b128 v[194:197], v198 offset:2048
	ds_read_b128 v[198:201], v198 offset:3072
	s_waitcnt vmcnt(8)
	s_waitcnt lgkmcnt(0)
	s_barrier
	v_mfma_f32_16x16x32_bf16 v[124:127], v[128:131], v[144:147], v[124:127]
	v_mfma_f32_16x16x32_bf16 v[120:123], v[136:139], v[144:147], v[120:123]
	v_mfma_f32_16x16x32_bf16 v[108:111], v[128:131], v[152:155], v[108:111]
	v_mfma_f32_16x16x32_bf16 v[104:107], v[136:139], v[152:155], v[104:107]
	v_mfma_f32_16x16x32_bf16 v[92:95], v[128:131], v[160:163], v[92:95]
	v_mfma_f32_16x16x32_bf16 v[88:91], v[136:139], v[160:163], v[88:91]
	v_mfma_f32_16x16x32_bf16 v[76:79], v[128:131], v[170:173], v[76:79]
	v_mfma_f32_16x16x32_bf16 v[72:75], v[136:139], v[170:173], v[72:75]
	v_mfma_f32_16x16x32_bf16 v[124:127], v[132:135], v[148:151], v[124:127]
	v_mfma_f32_16x16x32_bf16 v[120:123], v[140:143], v[148:151], v[120:123]
	v_mfma_f32_16x16x32_bf16 v[108:111], v[132:135], v[156:159], v[108:111]
	v_mfma_f32_16x16x32_bf16 v[104:107], v[140:143], v[156:159], v[104:107]
	v_mfma_f32_16x16x32_bf16 v[92:95], v[132:135], v[164:167], v[92:95]
	v_mfma_f32_16x16x32_bf16 v[88:91], v[140:143], v[164:167], v[88:91]
	v_mfma_f32_16x16x32_bf16 v[76:79], v[132:135], v[182:185], v[76:79]
	v_mfma_f32_16x16x32_bf16 v[72:75], v[140:143], v[182:185], v[72:75]
	v_mfma_f32_16x16x32_bf16 v[116:119], v[186:189], v[144:147], v[116:119]
	v_mfma_f32_16x16x32_bf16 v[112:115], v[194:197], v[144:147], v[112:115]
	v_mfma_f32_16x16x32_bf16 v[100:103], v[186:189], v[152:155], v[100:103]
	v_mfma_f32_16x16x32_bf16 v[96:99], v[194:197], v[152:155], v[96:99]
	v_mfma_f32_16x16x32_bf16 v[84:87], v[186:189], v[160:163], v[84:87]
	v_mfma_f32_16x16x32_bf16 v[80:83], v[194:197], v[160:163], v[80:83]
	v_mfma_f32_16x16x32_bf16 v[68:71], v[186:189], v[170:173], v[68:71]
	v_mfma_f32_16x16x32_bf16 v[64:67], v[194:197], v[170:173], v[64:67]
	v_mfma_f32_16x16x32_bf16 v[116:119], v[190:193], v[148:151], v[116:119]
	v_mfma_f32_16x16x32_bf16 v[112:115], v[198:201], v[148:151], v[112:115]
	v_mfma_f32_16x16x32_bf16 v[100:103], v[190:193], v[156:159], v[100:103]
	v_mfma_f32_16x16x32_bf16 v[96:99], v[198:201], v[156:159], v[96:99]
	v_mfma_f32_16x16x32_bf16 v[84:87], v[190:193], v[164:167], v[84:87]
	v_mfma_f32_16x16x32_bf16 v[80:83], v[198:201], v[164:167], v[80:83]
	v_mfma_f32_16x16x32_bf16 v[68:71], v[190:193], v[182:185], v[68:71]
	v_mfma_f32_16x16x32_bf16 v[64:67], v[198:201], v[182:185], v[64:67]
	s_barrier
; #define PG8_STAGE(bufoff, gbase) do { _Pragma("unroll") for (int _i = 0; _i < 2; ++_i) \
;         __builtin_amdgcn_global_load_lds((const unsigned*)((const char*)(gbase) + voffA[_i]), (LAS unsigned*)(lds + (bufoff) + ldsw + _i * 8192), 16, 0, 0); } while (0)
; #define PG8_LDA(dst, b, h) do { _Pragma("unroll") for (int m = 0; m < 4; ++m) _Pragma("unroll") for (int k = 0; k < 2; ++k) dst[m][k] = *(const LAS bf16x8*)(lds + PG8_SA(b, h) + aoff + m * 2048 + k * 1024); } while (0)
; #define PG8_LDB(dst, b, h) do { _Pragma("unroll") for (int n = 0; n < 2; ++n) _Pragma("unroll") for (int k = 0; k < 2; ++k) dst[n][k] = *(const LAS bf16x8*)(lds + PG8_SB(b, h) + boff + n * 2048 + k * 1024); } while (0)
; #define PG8_MMA(ai, bj, At, Bt) do { __builtin_amdgcn_s_setprio(1); _Pragma("unroll") for (int m = 0; m < 4; ++m) _Pragma("unroll") for (int n = 0; n < 2; ++n) _Pragma("unroll") for (int k = 0; k < 2; ++k) \
;         acc[ai][bj][m][n] = __builtin_amdgcn_mfma_f32_16x16x32_bf16(Bt[n][k], At[m][k], acc[ai][bj][m][n], 0, 0, 0); __builtin_amdgcn_s_setprio(0); } while (0)
; #define PG8_WAIT_V(n) asm volatile("s_waitcnt vmcnt(" #n ")" ::: "memory")
; #define PG8_WAIT_L(n) asm volatile("s_waitcnt lgkmcnt(" #n ")" ::: "memory")
; #define PG8_BAR __builtin_amdgcn_s_barrier()
; #define PG8_SCHED __builtin_amdgcn_sched_barrier(0)
; template <class Epi>
; DI void gemm_phase(const int TID, const int BID, LAS unsigned char* lds, const Gemm g, const Epi& E) {
;     ...
;             PG8_LDB(B1, 1, 1); PG8_STAGE(PG8_SB(1, 0), b3);
;             PG8_BAR; PG8_WAIT_L(0); PG8_MMA(0, 1, At, B1); PG8_BAR;
;             PG8_LDA(At, 1, 1); PG8_STAGE(PG8_SA(1, 0), a3);
;             PG8_BAR; PG8_WAIT_L(0); PG8_MMA(1, 0, At, B0); PG8_BAR; PG8_SCHED;
;             PG8_STAGE(PG8_SB(1, 1), b3 + hstep);
;             PG8_WAIT_V(6); PG8_BAR; PG8_MMA(1, 1, At, B1); PG8_BAR;
;         }
	s_mov_b32 m0, s33
	v_lshl_add_u64 v[202:203], v[202:203], 0, s[92:93]
	global_load_lds_dwordx4 v[202:203], off
	v_lshl_add_u64 v[202:203], v[204:205], 0, s[92:93]
	s_mov_b32 m0, s60
	s_nop 0
	global_load_lds_dwordx4 v[202:203], off
	s_mov_b32 m0, s61
	v_lshl_add_u64 v[202:203], v[206:207], 0, s[92:93]
	global_load_lds_dwordx4 v[202:203], off
	v_lshl_add_u64 v[202:203], v[208:209], 0, s[92:93]
	s_mov_b32 m0, s64
	s_nop 0
	global_load_lds_dwordx4 v[202:203], off
	s_mov_b32 m0, s66
	v_lshl_add_u64 v[202:203], v[210:211], 0, s[92:93]
	global_load_lds_dwordx4 v[202:203], off
	v_lshl_add_u64 v[202:203], v[212:213], 0, s[92:93]
	s_mov_b32 m0, s67
	s_nop 0
	global_load_lds_dwordx4 v[202:203], off
	ds_read_b128 v[144:147], v248 offset:49152
	ds_read_b128 v[148:151], v248 offset:50176
	ds_read_b128 v[152:155], v248 offset:51200
	ds_read_b128 v[156:159], v248 offset:52224
	ds_read_b128 v[160:163], v248 offset:53248
	ds_read_b128 v[164:167], v248 offset:54272
	ds_read_b128 v[170:173], v248 offset:55296
	ds_read_b128 v[182:185], v248 offset:56320
	s_waitcnt vmcnt(8)
	s_waitcnt lgkmcnt(0)
	s_barrier
	v_mfma_f32_16x16x32_bf16 v[60:63], v[128:131], v[144:147], v[60:63]
	v_mfma_f32_16x16x32_bf16 v[56:59], v[136:139], v[144:147], v[56:59]
	v_mfma_f32_16x16x32_bf16 v[44:47], v[128:131], v[152:155], v[44:47]
	v_mfma_f32_16x16x32_bf16 v[40:43], v[136:139], v[152:155], v[40:43]
	v_mfma_f32_16x16x32_bf16 v[28:31], v[128:131], v[160:163], v[28:31]
	v_mfma_f32_16x16x32_bf16 v[24:27], v[136:139], v[160:163], v[24:27]
	v_mfma_f32_16x16x32_bf16 v[12:15], v[128:131], v[170:173], v[12:15]
	v_mfma_f32_16x16x32_bf16 v[8:11], v[136:139], v[170:173], v[8:11]
	v_mfma_f32_16x16x32_bf16 v[60:63], v[132:135], v[148:151], v[60:63]
	v_mfma_f32_16x16x32_bf16 v[56:59], v[140:143], v[148:151], v[56:59]
	v_mfma_f32_16x16x32_bf16 v[44:47], v[132:135], v[156:159], v[44:47]
	v_mfma_f32_16x16x32_bf16 v[40:43], v[140:143], v[156:159], v[40:43]
	v_mfma_f32_16x16x32_bf16 v[28:31], v[132:135], v[164:167], v[28:31]
	v_mfma_f32_16x16x32_bf16 v[24:27], v[140:143], v[164:167], v[24:27]
	v_mfma_f32_16x16x32_bf16 v[12:15], v[132:135], v[182:185], v[12:15]
	v_mfma_f32_16x16x32_bf16 v[8:11], v[140:143], v[182:185], v[8:11]
	v_mfma_f32_16x16x32_bf16 v[52:55], v[186:189], v[144:147], v[52:55]
	v_mfma_f32_16x16x32_bf16 v[48:51], v[194:197], v[144:147], v[48:51]
	v_mfma_f32_16x16x32_bf16 v[36:39], v[186:189], v[152:155], v[36:39]
	v_mfma_f32_16x16x32_bf16 v[32:35], v[194:197], v[152:155], v[32:35]
	v_mfma_f32_16x16x32_bf16 v[20:23], v[186:189], v[160:163], v[20:23]
	v_mfma_f32_16x16x32_bf16 v[16:19], v[194:197], v[160:163], v[16:19]
	v_mfma_f32_16x16x32_bf16 v[4:7], v[186:189], v[170:173], v[4:7]
	v_mfma_f32_16x16x32_bf16 v[0:3], v[194:197], v[170:173], v[0:3]
	v_mfma_f32_16x16x32_bf16 v[52:55], v[190:193], v[148:151], v[52:55]
	v_mfma_f32_16x16x32_bf16 v[48:51], v[198:201], v[148:151], v[48:51]
	v_mfma_f32_16x16x32_bf16 v[36:39], v[190:193], v[156:159], v[36:39]
	v_mfma_f32_16x16x32_bf16 v[32:35], v[198:201], v[156:159], v[32:35]
	v_mfma_f32_16x16x32_bf16 v[20:23], v[190:193], v[164:167], v[20:23]
	v_mfma_f32_16x16x32_bf16 v[16:19], v[198:201], v[164:167], v[16:19]
	v_mfma_f32_16x16x32_bf16 v[4:7], v[190:193], v[182:185], v[4:7]
	v_mfma_f32_16x16x32_bf16 v[0:3], v[198:201], v[182:185], v[0:3]
	s_add_u32 s52, s52, 0x100
	s_addc_u32 s53, s53, 0
	s_add_u32 vcc_hi, vcc_hi, 0x100
	s_addc_u32 s29, s29, 0
	s_cmp_ge_i32 s58, s17
	s_mov_b32 s54, s58
	s_barrier
	s_cbranch_scc0 .LBB0_230
	s_branch .LBB0_234

; #define PG8_STAGE(bufoff, gbase) do { _Pragma("unroll") for (int _i = 0; _i < 2; ++_i) \
;         __builtin_amdgcn_global_load_lds((const unsigned*)((const char*)(gbase) + voffA[_i]), (LAS unsigned*)(lds + (bufoff) + ldsw + _i * 8192), 16, 0, 0); } while (0)
; #define PG8_LDA(dst, b, h) do { _Pragma("unroll") for (int m = 0; m < 4; ++m) _Pragma("unroll") for (int k = 0; k < 2; ++k) dst[m][k] = *(const LAS bf16x8*)(lds + PG8_SA(b, h) + aoff + m * 2048 + k * 1024); } while (0)
; #define PG8_LDB(dst, b, h) do { _Pragma("unroll") for (int n = 0; n < 2; ++n) _Pragma("unroll") for (int k = 0; k < 2; ++k) dst[n][k] = *(const LAS bf16x8*)(lds + PG8_SB(b, h) + boff + n * 2048 + k * 1024); } while (0)
; #define PG8_MMA(ai, bj, At, Bt) do { __builtin_amdgcn_s_setprio(1); _Pragma("unroll") for (int m = 0; m < 4; ++m) _Pragma("unroll") for (int n = 0; n < 2; ++n) _Pragma("unroll") for (int k = 0; k < 2; ++k) \
;         acc[ai][bj][m][n] = __builtin_amdgcn_mfma_f32_16x16x32_bf16(Bt[n][k], At[m][k], acc[ai][bj][m][n], 0, 0, 0); __builtin_amdgcn_s_setprio(0); } while (0)
; #define PG8_WAIT_L(n) asm volatile("s_waitcnt lgkmcnt(" #n ")" ::: "memory")
; #define PG8_BAR __builtin_amdgcn_s_barrier()
; #define PG8_SCHED __builtin_amdgcn_sched_barrier(0)
; template <class Epi>
; DI void gemm_phase(const int TID, const int BID, LAS unsigned char* lds, const Gemm g, const Epi& E) {
;     ...
;         for (int t = 0; t < nt; t += 2) {
;             const bool last = (t == nt - 2);
;             const char* a1 = cA + (size_t)(t + 1) * kstep;
;             const char* a2 = last ? nA : cA + (size_t)(t + 2) * kstep; const char* b2 = last ? nB : cB + (size_t)(t + 2) * kstep;
;             const char* a3 = a2 + kstep; const char* b3 = b2 + kstep;
;             PG8_LDB(B0, 0, 0); PG8_SCHED; PG8_LDA(At, 0, 0); PG8_STAGE(PG8_SA(1, 1), a1 + hstep);
;             PG8_WAIT_L(8); PG8_BAR; PG8_WAIT_L(0); PG8_MMA(0, 0, At, B0); PG8_BAR; PG8_SCHED;
;             PG8_LDB(B1, 0, 1); PG8_STAGE(PG8_SB(0, 0), b2);
;             PG8_BAR; PG8_WAIT_L(0); PG8_MMA(0, 1, At, B1); PG8_BAR;
.LBB0_271:
	s_add_i32 vcc_hi, s12, 2
	s_add_u32 s52, s0, 0x80
	s_addc_u32 s13, s1, 0
	s_cmp_eq_u32 s54, s12
	s_cselect_b32 s12, s8, s52
	s_cselect_b32 s13, s9, s13
	s_cselect_b32 s53, s11, vcc_lo
	s_cselect_b32 s52, s10, s55
	v_lshl_add_u64 v[170:171], s[0:1], 0, v[164:165]
	s_add_i32 m0, s21, 0xc000
	global_load_lds_dwordx4 v[170:171], off
	v_lshl_add_u64 v[170:171], s[0:1], 0, v[166:167]
	s_add_i32 m0, s21, 0xe000
	s_nop 0
	global_load_lds_dwordx4 v[170:171], off
	v_add_u32_e32 v140, s18, v222
	ds_read_b128 v[128:131], v140
	ds_read_b128 v[132:135], v140 offset:1024
	ds_read_b128 v[136:139], v140 offset:2048
	ds_read_b128 v[140:143], v140 offset:3072
	ds_read_b128 v[144:147], v224
	ds_read_b128 v[148:151], v224 offset:1024
	ds_read_b128 v[152:155], v224 offset:2048
	ds_read_b128 v[156:159], v224 offset:3072
	ds_read_b128 v[176:179], v224 offset:4096
	ds_read_b128 v[180:183], v224 offset:5120
	ds_read_b128 v[184:187], v224 offset:6144
	ds_read_b128 v[188:191], v224 offset:7168
	v_add_u32_e32 v168, s23, v222
	ds_read_b128 v[192:195], v168
	ds_read_b128 v[196:199], v168 offset:1024
	ds_read_b128 v[200:203], v168 offset:2048
	ds_read_b128 v[204:207], v168 offset:3072
	s_waitcnt vmcnt(8)
	s_waitcnt lgkmcnt(0)
	s_barrier
	v_mfma_f32_16x16x32_bf16 v[124:127], v[128:131], v[144:147], v[124:127]
	v_mfma_f32_16x16x32_bf16 v[120:123], v[136:139], v[144:147], v[120:123]
	v_mfma_f32_16x16x32_bf16 v[108:111], v[128:131], v[152:155], v[108:111]
	v_mfma_f32_16x16x32_bf16 v[104:107], v[136:139], v[152:155], v[104:107]
	v_mfma_f32_16x16x32_bf16 v[92:95], v[128:131], v[176:179], v[92:95]
	v_mfma_f32_16x16x32_bf16 v[88:91], v[136:139], v[176:179], v[88:91]
	v_mfma_f32_16x16x32_bf16 v[76:79], v[128:131], v[184:187], v[76:79]
	v_mfma_f32_16x16x32_bf16 v[72:75], v[136:139], v[184:187], v[72:75]
	v_mfma_f32_16x16x32_bf16 v[124:127], v[132:135], v[148:151], v[124:127]
	v_mfma_f32_16x16x32_bf16 v[120:123], v[140:143], v[148:151], v[120:123]
	v_mfma_f32_16x16x32_bf16 v[108:111], v[132:135], v[156:159], v[108:111]
	v_mfma_f32_16x16x32_bf16 v[104:107], v[140:143], v[156:159], v[104:107]
	v_mfma_f32_16x16x32_bf16 v[92:95], v[132:135], v[180:183], v[92:95]
	v_mfma_f32_16x16x32_bf16 v[88:91], v[140:143], v[180:183], v[88:91]
	v_mfma_f32_16x16x32_bf16 v[76:79], v[132:135], v[188:191], v[76:79]
	v_mfma_f32_16x16x32_bf16 v[72:75], v[140:143], v[188:191], v[72:75]
	v_mfma_f32_16x16x32_bf16 v[116:119], v[192:195], v[144:147], v[116:119]
	v_mfma_f32_16x16x32_bf16 v[112:115], v[200:203], v[144:147], v[112:115]
	v_mfma_f32_16x16x32_bf16 v[100:103], v[192:195], v[152:155], v[100:103]
	v_mfma_f32_16x16x32_bf16 v[96:99], v[200:203], v[152:155], v[96:99]
	v_mfma_f32_16x16x32_bf16 v[84:87], v[192:195], v[176:179], v[84:87]
	v_mfma_f32_16x16x32_bf16 v[80:83], v[200:203], v[176:179], v[80:83]
	v_mfma_f32_16x16x32_bf16 v[68:71], v[192:195], v[184:187], v[68:71]
	v_mfma_f32_16x16x32_bf16 v[64:67], v[200:203], v[184:187], v[64:67]
	v_mfma_f32_16x16x32_bf16 v[116:119], v[196:199], v[148:151], v[116:119]
	v_mfma_f32_16x16x32_bf16 v[112:115], v[204:207], v[148:151], v[112:115]
	v_mfma_f32_16x16x32_bf16 v[100:103], v[196:199], v[156:159], v[100:103]
	v_mfma_f32_16x16x32_bf16 v[96:99], v[204:207], v[156:159], v[96:99]
	v_mfma_f32_16x16x32_bf16 v[84:87], v[196:199], v[180:183], v[84:87]
	v_mfma_f32_16x16x32_bf16 v[80:83], v[204:207], v[180:183], v[80:83]
	v_mfma_f32_16x16x32_bf16 v[68:71], v[196:199], v[188:191], v[68:71]
	v_mfma_f32_16x16x32_bf16 v[64:67], v[204:207], v[188:191], v[64:67]
	s_barrier
	s_mov_b32 m0, s19
	v_lshl_add_u64 v[170:171], s[52:53], 0, v[160:161]
	global_load_lds_dwordx4 v[170:171], off
	v_lshl_add_u64 v[172:173], s[52:53], 0, v[162:163]
	s_mov_b32 m0, s20
	s_nop 0
	global_load_lds_dwordx4 v[172:173], off
	s_mov_b32 m0, s21
	v_lshl_add_u64 v[208:209], s[12:13], 0, v[160:161]
	global_load_lds_dwordx4 v[208:209], off
	v_lshl_add_u64 v[210:211], s[12:13], 0, v[162:163]
	s_mov_b32 m0, s22
	s_nop 0
	global_load_lds_dwordx4 v[210:211], off
	s_add_u32 s52, s52, s2
	s_addc_u32 s53, s53, s3
	s_mov_b32 m0, s24
	v_lshl_add_u64 v[212:213], s[52:53], 0, v[160:161]
	global_load_lds_dwordx4 v[212:213], off
	v_lshl_add_u64 v[214:215], s[52:53], 0, v[162:163]
	s_mov_b32 m0, s25
	s_nop 0
	global_load_lds_dwordx4 v[214:215], off
	ds_read_b128 v[144:147], v224 offset:16384
	ds_read_b128 v[148:151], v224 offset:17408
	ds_read_b128 v[152:155], v224 offset:18432
	ds_read_b128 v[156:159], v224 offset:19456
	ds_read_b128 v[176:179], v224 offset:20480
	ds_read_b128 v[180:183], v224 offset:21504
	ds_read_b128 v[184:187], v224 offset:22528
	ds_read_b128 v[188:191], v224 offset:23552
	s_waitcnt vmcnt(8)
	s_waitcnt lgkmcnt(0)
	s_barrier
; #define PG8_STAGE(bufoff, gbase) do { _Pragma("unroll") for (int _i = 0; _i < 2; ++_i) \
;         __builtin_amdgcn_global_load_lds((const unsigned*)((const char*)(gbase) + voffA[_i]), (LAS unsigned*)(lds + (bufoff) + ldsw + _i * 8192), 16, 0, 0); } while (0)
; #define PG8_LDA(dst, b, h) do { _Pragma("unroll") for (int m = 0; m < 4; ++m) _Pragma("unroll") for (int k = 0; k < 2; ++k) dst[m][k] = *(const LAS bf16x8*)(lds + PG8_SA(b, h) + aoff + m * 2048 + k * 1024); } while (0)
; #define PG8_LDB(dst, b, h) do { _Pragma("unroll") for (int n = 0; n < 2; ++n) _Pragma("unroll") for (int k = 0; k < 2; ++k) dst[n][k] = *(const LAS bf16x8*)(lds + PG8_SB(b, h) + boff + n * 2048 + k * 1024); } while (0)
; #define PG8_MMA(ai, bj, At, Bt) do { __builtin_amdgcn_s_setprio(1); _Pragma("unroll") for (int m = 0; m < 4; ++m) _Pragma("unroll") for (int n = 0; n < 2; ++n) _Pragma("unroll") for (int k = 0; k < 2; ++k) \
;         acc[ai][bj][m][n] = __builtin_amdgcn_mfma_f32_16x16x32_bf16(Bt[n][k], At[m][k], acc[ai][bj][m][n], 0, 0, 0); __builtin_amdgcn_s_setprio(0); } while (0)
; #define PG8_WAIT_V(n) asm volatile("s_waitcnt vmcnt(" #n ")" ::: "memory")
; #define PG8_WAIT_L(n) asm volatile("s_waitcnt lgkmcnt(" #n ")" ::: "memory")
; #define PG8_BAR __builtin_amdgcn_s_barrier()
; #define PG8_SCHED __builtin_amdgcn_sched_barrier(0)
; template <class Epi>
; DI void gemm_phase(const int TID, const int BID, LAS unsigned char* lds, const Gemm g, const Epi& E) {
;     ...
;             PG8_BAR; PG8_WAIT_L(0); PG8_MMA(0, 1, At, B1); PG8_BAR;
;             PG8_LDA(At, 0, 1); PG8_STAGE(PG8_SA(0, 0), a2);
;             PG8_BAR; PG8_WAIT_L(0); PG8_MMA(1, 0, At, B0); PG8_BAR; PG8_SCHED;
;             PG8_STAGE(PG8_SB(0, 1), b2 + hstep);
;             PG8_WAIT_V(6); PG8_BAR; PG8_MMA(1, 1, At, B1); PG8_BAR;
;             PG8_LDB(B0, 1, 0); PG8_SCHED; PG8_LDA(At, 1, 0); PG8_STAGE(PG8_SA(0, 1), a2 + hstep);
;             PG8_WAIT_L(8); PG8_BAR; PG8_WAIT_L(0); PG8_MMA(0, 0, At, B0); PG8_BAR; PG8_SCHED;
	v_mfma_f32_16x16x32_bf16 v[60:63], v[128:131], v[144:147], v[60:63]
	v_mfma_f32_16x16x32_bf16 v[56:59], v[136:139], v[144:147], v[56:59]
	v_mfma_f32_16x16x32_bf16 v[44:47], v[128:131], v[152:155], v[44:47]
	v_mfma_f32_16x16x32_bf16 v[40:43], v[136:139], v[152:155], v[40:43]
	v_mfma_f32_16x16x32_bf16 v[28:31], v[128:131], v[176:179], v[28:31]
	v_mfma_f32_16x16x32_bf16 v[24:27], v[136:139], v[176:179], v[24:27]
	v_mfma_f32_16x16x32_bf16 v[12:15], v[128:131], v[184:187], v[12:15]
	v_mfma_f32_16x16x32_bf16 v[8:11], v[136:139], v[184:187], v[8:11]
	v_mfma_f32_16x16x32_bf16 v[60:63], v[132:135], v[148:151], v[60:63]
	v_mfma_f32_16x16x32_bf16 v[56:59], v[140:143], v[148:151], v[56:59]
	v_mfma_f32_16x16x32_bf16 v[44:47], v[132:135], v[156:159], v[44:47]
	v_mfma_f32_16x16x32_bf16 v[40:43], v[140:143], v[156:159], v[40:43]
	v_mfma_f32_16x16x32_bf16 v[28:31], v[132:135], v[180:183], v[28:31]
	v_mfma_f32_16x16x32_bf16 v[24:27], v[140:143], v[180:183], v[24:27]
	v_mfma_f32_16x16x32_bf16 v[12:15], v[132:135], v[188:191], v[12:15]
	v_mfma_f32_16x16x32_bf16 v[8:11], v[140:143], v[188:191], v[8:11]
	v_mfma_f32_16x16x32_bf16 v[52:55], v[192:195], v[144:147], v[52:55]
	v_mfma_f32_16x16x32_bf16 v[48:51], v[200:203], v[144:147], v[48:51]
	v_mfma_f32_16x16x32_bf16 v[36:39], v[192:195], v[152:155], v[36:39]
	v_mfma_f32_16x16x32_bf16 v[32:35], v[200:203], v[152:155], v[32:35]
	v_mfma_f32_16x16x32_bf16 v[20:23], v[192:195], v[176:179], v[20:23]
	v_mfma_f32_16x16x32_bf16 v[16:19], v[200:203], v[176:179], v[16:19]
	v_mfma_f32_16x16x32_bf16 v[4:7], v[192:195], v[184:187], v[4:7]
	v_mfma_f32_16x16x32_bf16 v[0:3], v[200:203], v[184:187], v[0:3]
	v_mfma_f32_16x16x32_bf16 v[52:55], v[196:199], v[148:151], v[52:55]
	v_mfma_f32_16x16x32_bf16 v[48:51], v[204:207], v[148:151], v[48:51]
	v_mfma_f32_16x16x32_bf16 v[36:39], v[196:199], v[156:159], v[36:39]
	v_mfma_f32_16x16x32_bf16 v[32:35], v[204:207], v[156:159], v[32:35]
	v_mfma_f32_16x16x32_bf16 v[20:23], v[196:199], v[180:183], v[20:23]
	v_mfma_f32_16x16x32_bf16 v[16:19], v[204:207], v[180:183], v[16:19]
	v_mfma_f32_16x16x32_bf16 v[4:7], v[196:199], v[188:191], v[4:7]
	v_mfma_f32_16x16x32_bf16 v[0:3], v[204:207], v[188:191], v[0:3]
	s_barrier
	s_add_u32 s12, s12, s2
	s_addc_u32 s13, s13, s3
	s_mov_b32 m0, s26
	v_lshl_add_u64 v[192:193], s[12:13], 0, v[160:161]
	global_load_lds_dwordx4 v[192:193], off
	v_lshl_add_u64 v[192:193], s[12:13], 0, v[162:163]
	s_mov_b32 m0, s27
	s_nop 0
	global_load_lds_dwordx4 v[192:193], off
	v_add_u32_e32 v140, s31, v222
	ds_read_b128 v[128:131], v140
	ds_read_b128 v[132:135], v140 offset:1024
	ds_read_b128 v[136:139], v140 offset:2048
	ds_read_b128 v[140:143], v140 offset:3072
	ds_read_b128 v[144:147], v224 offset:32768
	ds_read_b128 v[148:151], v224 offset:33792
	ds_read_b128 v[152:155], v224 offset:34816
	ds_read_b128 v[156:159], v224 offset:35840
	ds_read_b128 v[176:179], v224 offset:36864
	ds_read_b128 v[180:183], v224 offset:37888
	ds_read_b128 v[184:187], v224 offset:38912
	ds_read_b128 v[188:191], v224 offset:39936
	v_add_u32_e32 v168, s61, v222
	ds_read_b128 v[192:195], v168
	ds_read_b128 v[196:199], v168 offset:1024
	ds_read_b128 v[200:203], v168 offset:2048
	ds_read_b128 v[204:207], v168 offset:3072
	s_waitcnt vmcnt(8)
	s_waitcnt lgkmcnt(0)
	s_barrier
	v_mfma_f32_16x16x32_bf16 v[124:127], v[128:131], v[144:147], v[124:127]
	v_mfma_f32_16x16x32_bf16 v[120:123], v[136:139], v[144:147], v[120:123]
	v_mfma_f32_16x16x32_bf16 v[108:111], v[128:131], v[152:155], v[108:111]
	v_mfma_f32_16x16x32_bf16 v[104:107], v[136:139], v[152:155], v[104:107]
	v_mfma_f32_16x16x32_bf16 v[92:95], v[128:131], v[176:179], v[92:95]
	v_mfma_f32_16x16x32_bf16 v[88:91], v[136:139], v[176:179], v[88:91]
	v_mfma_f32_16x16x32_bf16 v[76:79], v[128:131], v[184:187], v[76:79]
	v_mfma_f32_16x16x32_bf16 v[72:75], v[136:139], v[184:187], v[72:75]
	v_mfma_f32_16x16x32_bf16 v[124:127], v[132:135], v[148:151], v[124:127]
	v_mfma_f32_16x16x32_bf16 v[120:123], v[140:143], v[148:151], v[120:123]
	v_mfma_f32_16x16x32_bf16 v[108:111], v[132:135], v[156:159], v[108:111]
	v_mfma_f32_16x16x32_bf16 v[104:107], v[140:143], v[156:159], v[104:107]
	v_mfma_f32_16x16x32_bf16 v[92:95], v[132:135], v[180:183], v[92:95]
	v_mfma_f32_16x16x32_bf16 v[88:91], v[140:143], v[180:183], v[88:91]
	v_mfma_f32_16x16x32_bf16 v[76:79], v[132:135], v[188:191], v[76:79]
	v_mfma_f32_16x16x32_bf16 v[72:75], v[140:143], v[188:191], v[72:75]
	v_mfma_f32_16x16x32_bf16 v[116:119], v[192:195], v[144:147], v[116:119]
	v_mfma_f32_16x16x32_bf16 v[112:115], v[200:203], v[144:147], v[112:115]
	v_mfma_f32_16x16x32_bf16 v[100:103], v[192:195], v[152:155], v[100:103]
	v_mfma_f32_16x16x32_bf16 v[96:99], v[200:203], v[152:155], v[96:99]
	v_mfma_f32_16x16x32_bf16 v[84:87], v[192:195], v[176:179], v[84:87]
	v_mfma_f32_16x16x32_bf16 v[80:83], v[200:203], v[176:179], v[80:83]
	v_mfma_f32_16x16x32_bf16 v[68:71], v[192:195], v[184:187], v[68:71]
	v_mfma_f32_16x16x32_bf16 v[64:67], v[200:203], v[184:187], v[64:67]
	v_mfma_f32_16x16x32_bf16 v[116:119], v[196:199], v[148:151], v[116:119]
	v_mfma_f32_16x16x32_bf16 v[112:115], v[204:207], v[148:151], v[112:115]
	v_mfma_f32_16x16x32_bf16 v[100:103], v[196:199], v[156:159], v[100:103]
	v_mfma_f32_16x16x32_bf16 v[96:99], v[204:207], v[156:159], v[96:99]
	v_mfma_f32_16x16x32_bf16 v[84:87], v[196:199], v[180:183], v[84:87]
	v_mfma_f32_16x16x32_bf16 v[80:83], v[204:207], v[180:183], v[80:83]
	v_mfma_f32_16x16x32_bf16 v[68:71], v[196:199], v[188:191], v[68:71]
	v_mfma_f32_16x16x32_bf16 v[64:67], v[204:207], v[188:191], v[64:67]
	s_barrier
; #define PG8_STAGE(bufoff, gbase) do { _Pragma("unroll") for (int _i = 0; _i < 2; ++_i) \
;         __builtin_amdgcn_global_load_lds((const unsigned*)((const char*)(gbase) + voffA[_i]), (LAS unsigned*)(lds + (bufoff) + ldsw + _i * 8192), 16, 0, 0); } while (0)
; #define PG8_LDA(dst, b, h) do { _Pragma("unroll") for (int m = 0; m < 4; ++m) _Pragma("unroll") for (int k = 0; k < 2; ++k) dst[m][k] = *(const LAS bf16x8*)(lds + PG8_SA(b, h) + aoff + m * 2048 + k * 1024); } while (0)
; #define PG8_LDB(dst, b, h) do { _Pragma("unroll") for (int n = 0; n < 2; ++n) _Pragma("unroll") for (int k = 0; k < 2; ++k) dst[n][k] = *(const LAS bf16x8*)(lds + PG8_SB(b, h) + boff + n * 2048 + k * 1024); } while (0)
; #define PG8_MMA(ai, bj, At, Bt) do { __builtin_amdgcn_s_setprio(1); _Pragma("unroll") for (int m = 0; m < 4; ++m) _Pragma("unroll") for (int n = 0; n < 2; ++n) _Pragma("unroll") for (int k = 0; k < 2; ++k) \
;         acc[ai][bj][m][n] = __builtin_amdgcn_mfma_f32_16x16x32_bf16(Bt[n][k], At[m][k], acc[ai][bj][m][n], 0, 0, 0); __builtin_amdgcn_s_setprio(0); } while (0)
; #define PG8_WAIT_V(n) asm volatile("s_waitcnt vmcnt(" #n ")" ::: "memory")
; #define PG8_WAIT_L(n) asm volatile("s_waitcnt lgkmcnt(" #n ")" ::: "memory")
; #define PG8_BAR __builtin_amdgcn_s_barrier()
; #define PG8_SCHED __builtin_amdgcn_sched_barrier(0)
; template <class Epi>
; DI void gemm_phase(const int TID, const int BID, LAS unsigned char* lds, const Gemm g, const Epi& E) {
;     ...
;             PG8_LDB(B1, 1, 1); PG8_STAGE(PG8_SB(1, 0), b3);
;             PG8_BAR; PG8_WAIT_L(0); PG8_MMA(0, 1, At, B1); PG8_BAR;
;             PG8_LDA(At, 1, 1); PG8_STAGE(PG8_SA(1, 0), a3);
;             PG8_BAR; PG8_WAIT_L(0); PG8_MMA(1, 0, At, B0); PG8_BAR; PG8_SCHED;
;             PG8_STAGE(PG8_SB(1, 1), b3 + hstep);
;             PG8_WAIT_V(6); PG8_BAR; PG8_MMA(1, 1, At, B1); PG8_BAR;
;         }
	s_mov_b32 m0, s33
	v_lshl_add_u64 v[170:171], v[170:171], 0, s[92:93]
	global_load_lds_dwordx4 v[170:171], off
	v_lshl_add_u64 v[170:171], v[172:173], 0, s[92:93]
	s_mov_b32 m0, s56
	s_nop 0
	global_load_lds_dwordx4 v[170:171], off
	s_mov_b32 m0, s57
	v_lshl_add_u64 v[170:171], v[208:209], 0, s[92:93]
	global_load_lds_dwordx4 v[170:171], off
	v_lshl_add_u64 v[170:171], v[210:211], 0, s[92:93]
	s_mov_b32 m0, s60
	s_nop 0
	global_load_lds_dwordx4 v[170:171], off
	s_mov_b32 m0, s62
	v_lshl_add_u64 v[170:171], v[212:213], 0, s[92:93]
	global_load_lds_dwordx4 v[170:171], off
	v_lshl_add_u64 v[170:171], v[214:215], 0, s[92:93]
	s_mov_b32 m0, s63
	s_nop 0
	global_load_lds_dwordx4 v[170:171], off
	ds_read_b128 v[144:147], v224 offset:49152
	ds_read_b128 v[148:151], v224 offset:50176
	ds_read_b128 v[152:155], v224 offset:51200
	ds_read_b128 v[156:159], v224 offset:52224
	ds_read_b128 v[176:179], v224 offset:53248
	ds_read_b128 v[180:183], v224 offset:54272
	ds_read_b128 v[184:187], v224 offset:55296
	ds_read_b128 v[188:191], v224 offset:56320
	s_waitcnt vmcnt(8)
	s_waitcnt lgkmcnt(0)
	s_barrier
	v_mfma_f32_16x16x32_bf16 v[60:63], v[128:131], v[144:147], v[60:63]
	v_mfma_f32_16x16x32_bf16 v[56:59], v[136:139], v[144:147], v[56:59]
	v_mfma_f32_16x16x32_bf16 v[44:47], v[128:131], v[152:155], v[44:47]
	v_mfma_f32_16x16x32_bf16 v[40:43], v[136:139], v[152:155], v[40:43]
	v_mfma_f32_16x16x32_bf16 v[28:31], v[128:131], v[176:179], v[28:31]
	v_mfma_f32_16x16x32_bf16 v[24:27], v[136:139], v[176:179], v[24:27]
	v_mfma_f32_16x16x32_bf16 v[12:15], v[128:131], v[184:187], v[12:15]
	v_mfma_f32_16x16x32_bf16 v[8:11], v[136:139], v[184:187], v[8:11]
	v_mfma_f32_16x16x32_bf16 v[60:63], v[132:135], v[148:151], v[60:63]
	v_mfma_f32_16x16x32_bf16 v[56:59], v[140:143], v[148:151], v[56:59]
	v_mfma_f32_16x16x32_bf16 v[44:47], v[132:135], v[156:159], v[44:47]
	v_mfma_f32_16x16x32_bf16 v[40:43], v[140:143], v[156:159], v[40:43]
	v_mfma_f32_16x16x32_bf16 v[28:31], v[132:135], v[180:183], v[28:31]
	v_mfma_f32_16x16x32_bf16 v[24:27], v[140:143], v[180:183], v[24:27]
	v_mfma_f32_16x16x32_bf16 v[12:15], v[132:135], v[188:191], v[12:15]
	v_mfma_f32_16x16x32_bf16 v[8:11], v[140:143], v[188:191], v[8:11]
	v_mfma_f32_16x16x32_bf16 v[52:55], v[192:195], v[144:147], v[52:55]
	v_mfma_f32_16x16x32_bf16 v[48:51], v[200:203], v[144:147], v[48:51]
	v_mfma_f32_16x16x32_bf16 v[36:39], v[192:195], v[152:155], v[36:39]
	v_mfma_f32_16x16x32_bf16 v[32:35], v[200:203], v[152:155], v[32:35]
	v_mfma_f32_16x16x32_bf16 v[20:23], v[192:195], v[176:179], v[20:23]
	v_mfma_f32_16x16x32_bf16 v[16:19], v[200:203], v[176:179], v[16:19]
	v_mfma_f32_16x16x32_bf16 v[4:7], v[192:195], v[184:187], v[4:7]
	v_mfma_f32_16x16x32_bf16 v[0:3], v[200:203], v[184:187], v[0:3]
	v_mfma_f32_16x16x32_bf16 v[52:55], v[196:199], v[148:151], v[52:55]
	v_mfma_f32_16x16x32_bf16 v[48:51], v[204:207], v[148:151], v[48:51]
	v_mfma_f32_16x16x32_bf16 v[36:39], v[196:199], v[156:159], v[36:39]
	v_mfma_f32_16x16x32_bf16 v[32:35], v[204:207], v[156:159], v[32:35]
	v_mfma_f32_16x16x32_bf16 v[20:23], v[196:199], v[180:183], v[20:23]
	v_mfma_f32_16x16x32_bf16 v[16:19], v[204:207], v[180:183], v[16:19]
	v_mfma_f32_16x16x32_bf16 v[4:7], v[196:199], v[188:191], v[4:7]
	v_mfma_f32_16x16x32_bf16 v[0:3], v[204:207], v[188:191], v[0:3]
	s_add_u32 s0, s0, 0x100
	s_addc_u32 s1, s1, 0
	s_add_u32 s55, s55, 0x100
	s_addc_u32 vcc_lo, vcc_lo, 0
	s_cmp_ge_i32 vcc_hi, s80
	s_mov_b32 s12, vcc_hi
	s_barrier
	s_cbranch_scc0 .LBB0_271
	s_branch .LBB0_275

; #define PG8_STAGE(bufoff, gbase) do { _Pragma("unroll") for (int _i = 0; _i < 2; ++_i) \
;         __builtin_amdgcn_global_load_lds((const unsigned*)((const char*)(gbase) + voffA[_i]), (LAS unsigned*)(lds + (bufoff) + ldsw + _i * 8192), 16, 0, 0); } while (0)
; #define PG8_LDA(dst, b, h) do { _Pragma("unroll") for (int m = 0; m < 4; ++m) _Pragma("unroll") for (int k = 0; k < 2; ++k) dst[m][k] = *(const LAS bf16x8*)(lds + PG8_SA(b, h) + aoff + m * 2048 + k * 1024); } while (0)
; #define PG8_LDB(dst, b, h) do { _Pragma("unroll") for (int n = 0; n < 2; ++n) _Pragma("unroll") for (int k = 0; k < 2; ++k) dst[n][k] = *(const LAS bf16x8*)(lds + PG8_SB(b, h) + boff + n * 2048 + k * 1024); } while (0)
; #define PG8_MMA(ai, bj, At, Bt) do { __builtin_amdgcn_s_setprio(1); _Pragma("unroll") for (int m = 0; m < 4; ++m) _Pragma("unroll") for (int n = 0; n < 2; ++n) _Pragma("unroll") for (int k = 0; k < 2; ++k) \
;         acc[ai][bj][m][n] = __builtin_amdgcn_mfma_f32_16x16x32_bf16(Bt[n][k], At[m][k], acc[ai][bj][m][n], 0, 0, 0); __builtin_amdgcn_s_setprio(0); } while (0)
; #define PG8_WAIT_L(n) asm volatile("s_waitcnt lgkmcnt(" #n ")" ::: "memory")
; #define PG8_BAR __builtin_amdgcn_s_barrier()
; #define PG8_SCHED __builtin_amdgcn_sched_barrier(0)
; template <class Epi>
; DI void gemm_phase(const int TID, const int BID, LAS unsigned char* lds, const Gemm g, const Epi& E) {
;     ...
;         for (int t = 0; t < nt; t += 2) {
;             const bool last = (t == nt - 2);
;             const char* a1 = cA + (size_t)(t + 1) * kstep;
;             const char* a2 = last ? nA : cA + (size_t)(t + 2) * kstep; const char* b2 = last ? nB : cB + (size_t)(t + 2) * kstep;
;             const char* a3 = a2 + kstep; const char* b3 = b2 + kstep;
;             PG8_LDB(B0, 0, 0); PG8_SCHED; PG8_LDA(At, 0, 0); PG8_STAGE(PG8_SA(1, 1), a1 + hstep);
;             PG8_WAIT_L(8); PG8_BAR; PG8_WAIT_L(0); PG8_MMA(0, 0, At, B0); PG8_BAR; PG8_SCHED;
;             PG8_LDB(B1, 0, 1); PG8_STAGE(PG8_SB(0, 0), b2);
;             PG8_BAR; PG8_WAIT_L(0); PG8_MMA(0, 1, At, B1); PG8_BAR;
.LBB0_359:
	s_add_i32 s17, s8, 2
	s_add_u32 s10, s6, 0x80
	s_addc_u32 s9, s7, 0
	s_cmp_eq_u32 s16, s8
	s_cselect_b32 s8, s60, s10
	s_cselect_b32 s9, s61, s9
	s_cselect_b32 s11, s63, s13
	s_cselect_b32 s10, s62, s12
	v_lshl_add_u64 v[170:171], s[6:7], 0, v[176:177]
	s_add_i32 m0, s22, 0xc000
	global_load_lds_dwordx4 v[170:171], off
	v_lshl_add_u64 v[170:171], s[6:7], 0, v[178:179]
	s_add_i32 m0, s22, 0xe000
	s_nop 0
	global_load_lds_dwordx4 v[170:171], off
	v_add_u32_e32 v140, s19, v192
	ds_read_b128 v[128:131], v140
	ds_read_b128 v[132:135], v140 offset:1024
	ds_read_b128 v[136:139], v140 offset:2048
	ds_read_b128 v[140:143], v140 offset:3072
	ds_read_b128 v[144:147], v203
	ds_read_b128 v[148:151], v203 offset:1024
	ds_read_b128 v[152:155], v203 offset:2048
	ds_read_b128 v[204:207], v203 offset:3072
	ds_read_b128 v[208:211], v203 offset:4096
	ds_read_b128 v[212:215], v203 offset:5120
	ds_read_b128 v[216:219], v203 offset:6144
	ds_read_b128 v[220:223], v203 offset:7168
	v_add_u32_e32 v168, s24, v192
	ds_read_b128 v[224:227], v168
	ds_read_b128 v[228:231], v168 offset:1024
	ds_read_b128 v[246:249], v168 offset:2048
	ds_read_b128 v[232:235], v168 offset:3072
	s_waitcnt vmcnt(8)
	s_waitcnt lgkmcnt(0)
	s_barrier
	v_mfma_f32_16x16x32_bf16 v[124:127], v[128:131], v[144:147], v[124:127]
	v_mfma_f32_16x16x32_bf16 v[120:123], v[136:139], v[144:147], v[120:123]
	v_mfma_f32_16x16x32_bf16 v[108:111], v[128:131], v[152:155], v[108:111]
	v_mfma_f32_16x16x32_bf16 v[104:107], v[136:139], v[152:155], v[104:107]
	v_mfma_f32_16x16x32_bf16 v[92:95], v[128:131], v[208:211], v[92:95]
	v_mfma_f32_16x16x32_bf16 v[88:91], v[136:139], v[208:211], v[88:91]
	v_mfma_f32_16x16x32_bf16 v[76:79], v[128:131], v[216:219], v[76:79]
	v_mfma_f32_16x16x32_bf16 v[72:75], v[136:139], v[216:219], v[72:75]
	v_mfma_f32_16x16x32_bf16 v[124:127], v[132:135], v[148:151], v[124:127]
	v_mfma_f32_16x16x32_bf16 v[120:123], v[140:143], v[148:151], v[120:123]
	v_mfma_f32_16x16x32_bf16 v[108:111], v[132:135], v[204:207], v[108:111]
	v_mfma_f32_16x16x32_bf16 v[104:107], v[140:143], v[204:207], v[104:107]
	v_mfma_f32_16x16x32_bf16 v[92:95], v[132:135], v[212:215], v[92:95]
	v_mfma_f32_16x16x32_bf16 v[88:91], v[140:143], v[212:215], v[88:91]
	v_mfma_f32_16x16x32_bf16 v[76:79], v[132:135], v[220:223], v[76:79]
	v_mfma_f32_16x16x32_bf16 v[72:75], v[140:143], v[220:223], v[72:75]
	v_mfma_f32_16x16x32_bf16 v[116:119], v[224:227], v[144:147], v[116:119]
	v_mfma_f32_16x16x32_bf16 v[112:115], v[246:249], v[144:147], v[112:115]
	v_mfma_f32_16x16x32_bf16 v[100:103], v[224:227], v[152:155], v[100:103]
	v_mfma_f32_16x16x32_bf16 v[96:99], v[246:249], v[152:155], v[96:99]
	v_mfma_f32_16x16x32_bf16 v[84:87], v[224:227], v[208:211], v[84:87]
	v_mfma_f32_16x16x32_bf16 v[80:83], v[246:249], v[208:211], v[80:83]
	v_mfma_f32_16x16x32_bf16 v[68:71], v[224:227], v[216:219], v[68:71]
	v_mfma_f32_16x16x32_bf16 v[64:67], v[246:249], v[216:219], v[64:67]
	v_mfma_f32_16x16x32_bf16 v[116:119], v[228:231], v[148:151], v[116:119]
	v_mfma_f32_16x16x32_bf16 v[112:115], v[232:235], v[148:151], v[112:115]
	v_mfma_f32_16x16x32_bf16 v[100:103], v[228:231], v[204:207], v[100:103]
	v_mfma_f32_16x16x32_bf16 v[96:99], v[232:235], v[204:207], v[96:99]
	v_mfma_f32_16x16x32_bf16 v[84:87], v[228:231], v[212:215], v[84:87]
	v_mfma_f32_16x16x32_bf16 v[80:83], v[232:235], v[212:215], v[80:83]
	v_mfma_f32_16x16x32_bf16 v[68:71], v[228:231], v[220:223], v[68:71]
	v_mfma_f32_16x16x32_bf16 v[64:67], v[232:235], v[220:223], v[64:67]
	s_barrier
	s_mov_b32 m0, s20
	v_lshl_add_u64 v[170:171], s[10:11], 0, v[158:159]
	global_load_lds_dwordx4 v[170:171], off
	v_lshl_add_u64 v[172:173], s[10:11], 0, v[160:161]
	s_mov_b32 m0, s21
	s_nop 0
	global_load_lds_dwordx4 v[172:173], off
	s_mov_b32 m0, s22
	v_lshl_add_u64 v[180:181], s[8:9], 0, v[158:159]
	global_load_lds_dwordx4 v[180:181], off
	v_lshl_add_u64 v[236:237], s[8:9], 0, v[160:161]
	s_mov_b32 m0, s23
	s_nop 0
	global_load_lds_dwordx4 v[236:237], off
	s_add_u32 s10, s10, s52
	s_addc_u32 s11, s11, s53
	s_mov_b32 m0, s25
	v_lshl_add_u64 v[238:239], s[10:11], 0, v[158:159]
	global_load_lds_dwordx4 v[238:239], off
	v_lshl_add_u64 v[184:185], s[10:11], 0, v[160:161]
	s_mov_b32 m0, s26
	s_nop 0
	global_load_lds_dwordx4 v[184:185], off
	ds_read_b128 v[144:147], v203 offset:16384
	ds_read_b128 v[148:151], v203 offset:17408
	ds_read_b128 v[152:155], v203 offset:18432
	ds_read_b128 v[204:207], v203 offset:19456
	ds_read_b128 v[208:211], v203 offset:20480
	ds_read_b128 v[212:215], v203 offset:21504
	ds_read_b128 v[216:219], v203 offset:22528
	ds_read_b128 v[220:223], v203 offset:23552
	s_waitcnt vmcnt(8)
	s_waitcnt lgkmcnt(0)
	s_barrier
; #define PG8_STAGE(bufoff, gbase) do { _Pragma("unroll") for (int _i = 0; _i < 2; ++_i) \
;         __builtin_amdgcn_global_load_lds((const unsigned*)((const char*)(gbase) + voffA[_i]), (LAS unsigned*)(lds + (bufoff) + ldsw + _i * 8192), 16, 0, 0); } while (0)
; #define PG8_LDA(dst, b, h) do { _Pragma("unroll") for (int m = 0; m < 4; ++m) _Pragma("unroll") for (int k = 0; k < 2; ++k) dst[m][k] = *(const LAS bf16x8*)(lds + PG8_SA(b, h) + aoff + m * 2048 + k * 1024); } while (0)
; #define PG8_LDB(dst, b, h) do { _Pragma("unroll") for (int n = 0; n < 2; ++n) _Pragma("unroll") for (int k = 0; k < 2; ++k) dst[n][k] = *(const LAS bf16x8*)(lds + PG8_SB(b, h) + boff + n * 2048 + k * 1024); } while (0)
; #define PG8_MMA(ai, bj, At, Bt) do { __builtin_amdgcn_s_setprio(1); _Pragma("unroll") for (int m = 0; m < 4; ++m) _Pragma("unroll") for (int n = 0; n < 2; ++n) _Pragma("unroll") for (int k = 0; k < 2; ++k) \
;         acc[ai][bj][m][n] = __builtin_amdgcn_mfma_f32_16x16x32_bf16(Bt[n][k], At[m][k], acc[ai][bj][m][n], 0, 0, 0); __builtin_amdgcn_s_setprio(0); } while (0)
; #define PG8_WAIT_V(n) asm volatile("s_waitcnt vmcnt(" #n ")" ::: "memory")
; #define PG8_WAIT_L(n) asm volatile("s_waitcnt lgkmcnt(" #n ")" ::: "memory")
; #define PG8_BAR __builtin_amdgcn_s_barrier()
; #define PG8_SCHED __builtin_amdgcn_sched_barrier(0)
; template <class Epi>
; DI void gemm_phase(const int TID, const int BID, LAS unsigned char* lds, const Gemm g, const Epi& E) {
;     ...
;             PG8_BAR; PG8_WAIT_L(0); PG8_MMA(0, 1, At, B1); PG8_BAR;
;             PG8_LDA(At, 0, 1); PG8_STAGE(PG8_SA(0, 0), a2);
;             PG8_BAR; PG8_WAIT_L(0); PG8_MMA(1, 0, At, B0); PG8_BAR; PG8_SCHED;
;             PG8_STAGE(PG8_SB(0, 1), b2 + hstep);
;             PG8_WAIT_V(6); PG8_BAR; PG8_MMA(1, 1, At, B1); PG8_BAR;
;             PG8_LDB(B0, 1, 0); PG8_SCHED; PG8_LDA(At, 1, 0); PG8_STAGE(PG8_SA(0, 1), a2 + hstep);
;             PG8_WAIT_L(8); PG8_BAR; PG8_WAIT_L(0); PG8_MMA(0, 0, At, B0); PG8_BAR; PG8_SCHED;
	v_mfma_f32_16x16x32_bf16 v[60:63], v[128:131], v[144:147], v[60:63]
	v_mfma_f32_16x16x32_bf16 v[56:59], v[136:139], v[144:147], v[56:59]
	v_mfma_f32_16x16x32_bf16 v[44:47], v[128:131], v[152:155], v[44:47]
	v_mfma_f32_16x16x32_bf16 v[40:43], v[136:139], v[152:155], v[40:43]
	v_mfma_f32_16x16x32_bf16 v[28:31], v[128:131], v[208:211], v[28:31]
	v_mfma_f32_16x16x32_bf16 v[24:27], v[136:139], v[208:211], v[24:27]
	v_mfma_f32_16x16x32_bf16 v[12:15], v[128:131], v[216:219], v[12:15]
	v_mfma_f32_16x16x32_bf16 v[8:11], v[136:139], v[216:219], v[8:11]
	v_mfma_f32_16x16x32_bf16 v[60:63], v[132:135], v[148:151], v[60:63]
	v_mfma_f32_16x16x32_bf16 v[56:59], v[140:143], v[148:151], v[56:59]
	v_mfma_f32_16x16x32_bf16 v[44:47], v[132:135], v[204:207], v[44:47]
	v_mfma_f32_16x16x32_bf16 v[40:43], v[140:143], v[204:207], v[40:43]
	v_mfma_f32_16x16x32_bf16 v[28:31], v[132:135], v[212:215], v[28:31]
	v_mfma_f32_16x16x32_bf16 v[24:27], v[140:143], v[212:215], v[24:27]
	v_mfma_f32_16x16x32_bf16 v[12:15], v[132:135], v[220:223], v[12:15]
	v_mfma_f32_16x16x32_bf16 v[8:11], v[140:143], v[220:223], v[8:11]
	v_mfma_f32_16x16x32_bf16 v[52:55], v[224:227], v[144:147], v[52:55]
	v_mfma_f32_16x16x32_bf16 v[48:51], v[246:249], v[144:147], v[48:51]
	v_mfma_f32_16x16x32_bf16 v[36:39], v[224:227], v[152:155], v[36:39]
	v_mfma_f32_16x16x32_bf16 v[32:35], v[246:249], v[152:155], v[32:35]
	v_mfma_f32_16x16x32_bf16 v[20:23], v[224:227], v[208:211], v[20:23]
	v_mfma_f32_16x16x32_bf16 v[16:19], v[246:249], v[208:211], v[16:19]
	v_mfma_f32_16x16x32_bf16 v[4:7], v[224:227], v[216:219], v[4:7]
	v_mfma_f32_16x16x32_bf16 v[0:3], v[246:249], v[216:219], v[0:3]
	v_mfma_f32_16x16x32_bf16 v[52:55], v[228:231], v[148:151], v[52:55]
	v_mfma_f32_16x16x32_bf16 v[48:51], v[232:235], v[148:151], v[48:51]
	v_mfma_f32_16x16x32_bf16 v[36:39], v[228:231], v[204:207], v[36:39]
	v_mfma_f32_16x16x32_bf16 v[32:35], v[232:235], v[204:207], v[32:35]
	v_mfma_f32_16x16x32_bf16 v[20:23], v[228:231], v[212:215], v[20:23]
	v_mfma_f32_16x16x32_bf16 v[16:19], v[232:235], v[212:215], v[16:19]
	v_mfma_f32_16x16x32_bf16 v[4:7], v[228:231], v[220:223], v[4:7]
	v_mfma_f32_16x16x32_bf16 v[0:3], v[232:235], v[220:223], v[0:3]
	s_barrier
	s_add_u32 s8, s8, s52
	s_addc_u32 s9, s9, s53
	s_mov_b32 m0, s27
	v_lshl_add_u64 v[224:225], s[8:9], 0, v[158:159]
	global_load_lds_dwordx4 v[224:225], off
	v_lshl_add_u64 v[224:225], s[8:9], 0, v[160:161]
	s_mov_b32 m0, s28
	s_nop 0
	global_load_lds_dwordx4 v[224:225], off
	v_add_u32_e32 v140, s29, v192
	ds_read_b128 v[128:131], v140
	ds_read_b128 v[132:135], v140 offset:1024
	ds_read_b128 v[136:139], v140 offset:2048
	ds_read_b128 v[140:143], v140 offset:3072
	ds_read_b128 v[144:147], v203 offset:32768
	ds_read_b128 v[148:151], v203 offset:33792
	ds_read_b128 v[152:155], v203 offset:34816
	ds_read_b128 v[204:207], v203 offset:35840
	ds_read_b128 v[208:211], v203 offset:36864
	ds_read_b128 v[212:215], v203 offset:37888
	ds_read_b128 v[216:219], v203 offset:38912
	ds_read_b128 v[220:223], v203 offset:39936
	v_add_u32_e32 v168, s77, v192
	ds_read_b128 v[224:227], v168
	ds_read_b128 v[228:231], v168 offset:1024
	ds_read_b128 v[232:235], v168 offset:2048
	ds_read_b128 v[246:249], v168 offset:3072
	s_waitcnt vmcnt(8)
	s_waitcnt lgkmcnt(0)
	s_barrier
	v_mfma_f32_16x16x32_bf16 v[124:127], v[128:131], v[144:147], v[124:127]
	v_mfma_f32_16x16x32_bf16 v[120:123], v[136:139], v[144:147], v[120:123]
	v_mfma_f32_16x16x32_bf16 v[108:111], v[128:131], v[152:155], v[108:111]
	v_mfma_f32_16x16x32_bf16 v[104:107], v[136:139], v[152:155], v[104:107]
	v_mfma_f32_16x16x32_bf16 v[92:95], v[128:131], v[208:211], v[92:95]
	v_mfma_f32_16x16x32_bf16 v[88:91], v[136:139], v[208:211], v[88:91]
	v_mfma_f32_16x16x32_bf16 v[76:79], v[128:131], v[216:219], v[76:79]
	v_mfma_f32_16x16x32_bf16 v[72:75], v[136:139], v[216:219], v[72:75]
	v_mfma_f32_16x16x32_bf16 v[124:127], v[132:135], v[148:151], v[124:127]
	v_mfma_f32_16x16x32_bf16 v[120:123], v[140:143], v[148:151], v[120:123]
	v_mfma_f32_16x16x32_bf16 v[108:111], v[132:135], v[204:207], v[108:111]
	v_mfma_f32_16x16x32_bf16 v[104:107], v[140:143], v[204:207], v[104:107]
	v_mfma_f32_16x16x32_bf16 v[92:95], v[132:135], v[212:215], v[92:95]
	v_mfma_f32_16x16x32_bf16 v[88:91], v[140:143], v[212:215], v[88:91]
	v_mfma_f32_16x16x32_bf16 v[76:79], v[132:135], v[220:223], v[76:79]
	v_mfma_f32_16x16x32_bf16 v[72:75], v[140:143], v[220:223], v[72:75]
	v_mfma_f32_16x16x32_bf16 v[116:119], v[224:227], v[144:147], v[116:119]
	v_mfma_f32_16x16x32_bf16 v[112:115], v[232:235], v[144:147], v[112:115]
	v_mfma_f32_16x16x32_bf16 v[100:103], v[224:227], v[152:155], v[100:103]
	v_mfma_f32_16x16x32_bf16 v[96:99], v[232:235], v[152:155], v[96:99]
	v_mfma_f32_16x16x32_bf16 v[84:87], v[224:227], v[208:211], v[84:87]
	v_mfma_f32_16x16x32_bf16 v[80:83], v[232:235], v[208:211], v[80:83]
	v_mfma_f32_16x16x32_bf16 v[68:71], v[224:227], v[216:219], v[68:71]
	v_mfma_f32_16x16x32_bf16 v[64:67], v[232:235], v[216:219], v[64:67]
	v_mfma_f32_16x16x32_bf16 v[116:119], v[228:231], v[148:151], v[116:119]
	v_mfma_f32_16x16x32_bf16 v[112:115], v[246:249], v[148:151], v[112:115]
	v_mfma_f32_16x16x32_bf16 v[100:103], v[228:231], v[204:207], v[100:103]
	v_mfma_f32_16x16x32_bf16 v[96:99], v[246:249], v[204:207], v[96:99]
	v_mfma_f32_16x16x32_bf16 v[84:87], v[228:231], v[212:215], v[84:87]
	v_mfma_f32_16x16x32_bf16 v[80:83], v[246:249], v[212:215], v[80:83]
	v_mfma_f32_16x16x32_bf16 v[68:71], v[228:231], v[220:223], v[68:71]
	v_mfma_f32_16x16x32_bf16 v[64:67], v[246:249], v[220:223], v[64:67]
	s_barrier
; #define PG8_STAGE(bufoff, gbase) do { _Pragma("unroll") for (int _i = 0; _i < 2; ++_i) \
;         __builtin_amdgcn_global_load_lds((const unsigned*)((const char*)(gbase) + voffA[_i]), (LAS unsigned*)(lds + (bufoff) + ldsw + _i * 8192), 16, 0, 0); } while (0)
; #define PG8_LDA(dst, b, h) do { _Pragma("unroll") for (int m = 0; m < 4; ++m) _Pragma("unroll") for (int k = 0; k < 2; ++k) dst[m][k] = *(const LAS bf16x8*)(lds + PG8_SA(b, h) + aoff + m * 2048 + k * 1024); } while (0)
; #define PG8_LDB(dst, b, h) do { _Pragma("unroll") for (int n = 0; n < 2; ++n) _Pragma("unroll") for (int k = 0; k < 2; ++k) dst[n][k] = *(const LAS bf16x8*)(lds + PG8_SB(b, h) + boff + n * 2048 + k * 1024); } while (0)
; #define PG8_MMA(ai, bj, At, Bt) do { __builtin_amdgcn_s_setprio(1); _Pragma("unroll") for (int m = 0; m < 4; ++m) _Pragma("unroll") for (int n = 0; n < 2; ++n) _Pragma("unroll") for (int k = 0; k < 2; ++k) \
;         acc[ai][bj][m][n] = __builtin_amdgcn_mfma_f32_16x16x32_bf16(Bt[n][k], At[m][k], acc[ai][bj][m][n], 0, 0, 0); __builtin_amdgcn_s_setprio(0); } while (0)
; #define PG8_WAIT_V(n) asm volatile("s_waitcnt vmcnt(" #n ")" ::: "memory")
; #define PG8_WAIT_L(n) asm volatile("s_waitcnt lgkmcnt(" #n ")" ::: "memory")
; #define PG8_BAR __builtin_amdgcn_s_barrier()
; #define PG8_SCHED __builtin_amdgcn_sched_barrier(0)
; template <class Epi>
; DI void gemm_phase(const int TID, const int BID, LAS unsigned char* lds, const Gemm g, const Epi& E) {
;     ...
;             PG8_LDB(B1, 1, 1); PG8_STAGE(PG8_SB(1, 0), b3);
;             PG8_BAR; PG8_WAIT_L(0); PG8_MMA(0, 1, At, B1); PG8_BAR;
;             PG8_LDA(At, 1, 1); PG8_STAGE(PG8_SA(1, 0), a3);
;             PG8_BAR; PG8_WAIT_L(0); PG8_MMA(1, 0, At, B0); PG8_BAR; PG8_SCHED;
;             PG8_STAGE(PG8_SB(1, 1), b3 + hstep);
;             PG8_WAIT_V(6); PG8_BAR; PG8_MMA(1, 1, At, B1); PG8_BAR;
;         }
	s_mov_b32 m0, s30
	v_lshl_add_u64 v[170:171], v[170:171], 0, s[92:93]
	global_load_lds_dwordx4 v[170:171], off
	v_lshl_add_u64 v[170:171], v[172:173], 0, s[92:93]
	s_mov_b32 m0, s31
	s_nop 0
	global_load_lds_dwordx4 v[170:171], off
	s_mov_b32 m0, s33
	v_lshl_add_u64 v[170:171], v[180:181], 0, s[92:93]
	global_load_lds_dwordx4 v[170:171], off
	v_lshl_add_u64 v[170:171], v[236:237], 0, s[92:93]
	s_mov_b32 m0, s76
	s_nop 0
	global_load_lds_dwordx4 v[170:171], off
	s_mov_b32 m0, s80
	v_lshl_add_u64 v[170:171], v[238:239], 0, s[92:93]
	global_load_lds_dwordx4 v[170:171], off
	v_lshl_add_u64 v[170:171], v[184:185], 0, s[92:93]
	s_mov_b32 m0, s81
	s_nop 0
	global_load_lds_dwordx4 v[170:171], off
	ds_read_b128 v[144:147], v203 offset:49152
	ds_read_b128 v[148:151], v203 offset:50176
	ds_read_b128 v[152:155], v203 offset:51200
	ds_read_b128 v[204:207], v203 offset:52224
	ds_read_b128 v[208:211], v203 offset:53248
	ds_read_b128 v[212:215], v203 offset:54272
	ds_read_b128 v[216:219], v203 offset:55296
	ds_read_b128 v[220:223], v203 offset:56320
	s_waitcnt vmcnt(8)
	s_waitcnt lgkmcnt(0)
	s_barrier
	v_mfma_f32_16x16x32_bf16 v[60:63], v[128:131], v[144:147], v[60:63]
	v_mfma_f32_16x16x32_bf16 v[56:59], v[136:139], v[144:147], v[56:59]
	v_mfma_f32_16x16x32_bf16 v[44:47], v[128:131], v[152:155], v[44:47]
	v_mfma_f32_16x16x32_bf16 v[40:43], v[136:139], v[152:155], v[40:43]
	v_mfma_f32_16x16x32_bf16 v[28:31], v[128:131], v[208:211], v[28:31]
	v_mfma_f32_16x16x32_bf16 v[24:27], v[136:139], v[208:211], v[24:27]
	v_mfma_f32_16x16x32_bf16 v[12:15], v[128:131], v[216:219], v[12:15]
	v_mfma_f32_16x16x32_bf16 v[8:11], v[136:139], v[216:219], v[8:11]
	v_mfma_f32_16x16x32_bf16 v[60:63], v[132:135], v[148:151], v[60:63]
	v_mfma_f32_16x16x32_bf16 v[56:59], v[140:143], v[148:151], v[56:59]
	v_mfma_f32_16x16x32_bf16 v[44:47], v[132:135], v[204:207], v[44:47]
	v_mfma_f32_16x16x32_bf16 v[40:43], v[140:143], v[204:207], v[40:43]
	v_mfma_f32_16x16x32_bf16 v[28:31], v[132:135], v[212:215], v[28:31]
	v_mfma_f32_16x16x32_bf16 v[24:27], v[140:143], v[212:215], v[24:27]
	v_mfma_f32_16x16x32_bf16 v[12:15], v[132:135], v[220:223], v[12:15]
	v_mfma_f32_16x16x32_bf16 v[8:11], v[140:143], v[220:223], v[8:11]
	v_mfma_f32_16x16x32_bf16 v[52:55], v[224:227], v[144:147], v[52:55]
	v_mfma_f32_16x16x32_bf16 v[48:51], v[232:235], v[144:147], v[48:51]
	v_mfma_f32_16x16x32_bf16 v[36:39], v[224:227], v[152:155], v[36:39]
	v_mfma_f32_16x16x32_bf16 v[32:35], v[232:235], v[152:155], v[32:35]
	v_mfma_f32_16x16x32_bf16 v[20:23], v[224:227], v[208:211], v[20:23]
	v_mfma_f32_16x16x32_bf16 v[16:19], v[232:235], v[208:211], v[16:19]
	v_mfma_f32_16x16x32_bf16 v[4:7], v[224:227], v[216:219], v[4:7]
	v_mfma_f32_16x16x32_bf16 v[0:3], v[232:235], v[216:219], v[0:3]
	v_mfma_f32_16x16x32_bf16 v[52:55], v[228:231], v[148:151], v[52:55]
	v_mfma_f32_16x16x32_bf16 v[48:51], v[246:249], v[148:151], v[48:51]
	v_mfma_f32_16x16x32_bf16 v[36:39], v[228:231], v[204:207], v[36:39]
	v_mfma_f32_16x16x32_bf16 v[32:35], v[246:249], v[204:207], v[32:35]
	v_mfma_f32_16x16x32_bf16 v[20:23], v[228:231], v[212:215], v[20:23]
	v_mfma_f32_16x16x32_bf16 v[16:19], v[246:249], v[212:215], v[16:19]
	v_mfma_f32_16x16x32_bf16 v[4:7], v[228:231], v[220:223], v[4:7]
	v_mfma_f32_16x16x32_bf16 v[0:3], v[246:249], v[220:223], v[0:3]
	s_add_u32 s6, s6, 0x100
	s_addc_u32 s7, s7, 0
	s_add_u32 s12, s12, 0x100
	s_addc_u32 s13, s13, 0
	s_cmp_ge_i32 s17, s18
	s_mov_b32 s8, s17
	s_barrier
	s_cbranch_scc0 .LBB0_359

; #define PG8_STAGE(bufoff, gbase) do { _Pragma("unroll") for (int _i = 0; _i < 2; ++_i) \
;         __builtin_amdgcn_global_load_lds((const unsigned*)((const char*)(gbase) + voffA[_i]), (LAS unsigned*)(lds + (bufoff) + ldsw + _i * 8192), 16, 0, 0); } while (0)
; #define PG8_LDA(dst, b, h) do { _Pragma("unroll") for (int m = 0; m < 4; ++m) _Pragma("unroll") for (int k = 0; k < 2; ++k) dst[m][k] = *(const LAS bf16x8*)(lds + PG8_SA(b, h) + aoff + m * 2048 + k * 1024); } while (0)
; #define PG8_LDB(dst, b, h) do { _Pragma("unroll") for (int n = 0; n < 2; ++n) _Pragma("unroll") for (int k = 0; k < 2; ++k) dst[n][k] = *(const LAS bf16x8*)(lds + PG8_SB(b, h) + boff + n * 2048 + k * 1024); } while (0)
; #define PG8_MMA(ai, bj, At, Bt) do { __builtin_amdgcn_s_setprio(1); _Pragma("unroll") for (int m = 0; m < 4; ++m) _Pragma("unroll") for (int n = 0; n < 2; ++n) _Pragma("unroll") for (int k = 0; k < 2; ++k) \
;         acc[ai][bj][m][n] = __builtin_amdgcn_mfma_f32_16x16x32_bf16(Bt[n][k], At[m][k], acc[ai][bj][m][n], 0, 0, 0); __builtin_amdgcn_s_setprio(0); } while (0)
; #define PG8_WAIT_L(n) asm volatile("s_waitcnt lgkmcnt(" #n ")" ::: "memory")
; #define PG8_BAR __builtin_amdgcn_s_barrier()
; #define PG8_SCHED __builtin_amdgcn_sched_barrier(0)
; template <class Epi>
; DI void gemm_phase(const int TID, const int BID, LAS unsigned char* lds, const Gemm g, const Epi& E) {
;     ...
;         for (int t = 0; t < nt; t += 2) {
;             const bool last = (t == nt - 2);
;             const char* a1 = cA + (size_t)(t + 1) * kstep;
;             const char* a2 = last ? nA : cA + (size_t)(t + 2) * kstep; const char* b2 = last ? nB : cB + (size_t)(t + 2) * kstep;
;             const char* a3 = a2 + kstep; const char* b3 = b2 + kstep;
;             PG8_LDB(B0, 0, 0); PG8_SCHED; PG8_LDA(At, 0, 0); PG8_STAGE(PG8_SA(1, 1), a1 + hstep);
;             PG8_WAIT_L(8); PG8_BAR; PG8_WAIT_L(0); PG8_MMA(0, 0, At, B0); PG8_BAR; PG8_SCHED;
;             PG8_LDB(B1, 0, 1); PG8_STAGE(PG8_SB(0, 0), b2);
;             PG8_BAR; PG8_WAIT_L(0); PG8_MMA(0, 1, At, B1); PG8_BAR;
.LBB0_491:
	s_add_i32 s16, s60, 2
	s_add_u32 s62, s4, 0x80
	s_addc_u32 s61, s5, 0
	s_cmp_eq_u32 s76, s60
	s_cselect_b32 s60, s56, s62
	s_cselect_b32 s61, s57, s61
	s_cselect_b32 s63, s59, vcc_hi
	s_cselect_b32 s62, s58, vcc_lo
	v_lshl_add_u64 v[156:157], s[4:5], 0, v[188:189]
	s_add_i32 m0, s21, 0xc000
	global_load_lds_dwordx4 v[156:157], off
	v_lshl_add_u64 v[156:157], s[4:5], 0, v[190:191]
	s_add_i32 m0, s21, 0xe000
	s_nop 0
	global_load_lds_dwordx4 v[156:157], off
	v_add_u32_e32 v140, s18, v192
	ds_read_b128 v[128:131], v140
	ds_read_b128 v[132:135], v140 offset:1024
	ds_read_b128 v[136:139], v140 offset:2048
	ds_read_b128 v[140:143], v140 offset:3072
	ds_read_b128 v[144:147], v175
	ds_read_b128 v[148:151], v175 offset:1024
	ds_read_b128 v[152:155], v175 offset:2048
	ds_read_b128 v[196:199], v175 offset:3072
	ds_read_b128 v[200:203], v175 offset:4096
	ds_read_b128 v[204:207], v175 offset:5120
	ds_read_b128 v[208:211], v175 offset:6144
	ds_read_b128 v[212:215], v175 offset:7168
	v_add_u32_e32 v156, s23, v192
	ds_read_b128 v[216:219], v156
	ds_read_b128 v[220:223], v156 offset:1024
	ds_read_b128 v[224:227], v156 offset:2048
	ds_read_b128 v[228:231], v156 offset:3072
	s_waitcnt vmcnt(8)
	s_waitcnt lgkmcnt(0)
	s_barrier
	v_mfma_f32_16x16x32_bf16 v[124:127], v[128:131], v[144:147], v[124:127]
	v_mfma_f32_16x16x32_bf16 v[120:123], v[136:139], v[144:147], v[120:123]
	v_mfma_f32_16x16x32_bf16 v[108:111], v[128:131], v[152:155], v[108:111]
	v_mfma_f32_16x16x32_bf16 v[104:107], v[136:139], v[152:155], v[104:107]
	v_mfma_f32_16x16x32_bf16 v[92:95], v[128:131], v[200:203], v[92:95]
	v_mfma_f32_16x16x32_bf16 v[88:91], v[136:139], v[200:203], v[88:91]
	v_mfma_f32_16x16x32_bf16 v[76:79], v[128:131], v[208:211], v[76:79]
	v_mfma_f32_16x16x32_bf16 v[72:75], v[136:139], v[208:211], v[72:75]
	v_mfma_f32_16x16x32_bf16 v[124:127], v[132:135], v[148:151], v[124:127]
	v_mfma_f32_16x16x32_bf16 v[120:123], v[140:143], v[148:151], v[120:123]
	v_mfma_f32_16x16x32_bf16 v[108:111], v[132:135], v[196:199], v[108:111]
	v_mfma_f32_16x16x32_bf16 v[104:107], v[140:143], v[196:199], v[104:107]
	v_mfma_f32_16x16x32_bf16 v[92:95], v[132:135], v[204:207], v[92:95]
	v_mfma_f32_16x16x32_bf16 v[88:91], v[140:143], v[204:207], v[88:91]
	v_mfma_f32_16x16x32_bf16 v[76:79], v[132:135], v[212:215], v[76:79]
	v_mfma_f32_16x16x32_bf16 v[72:75], v[140:143], v[212:215], v[72:75]
	v_mfma_f32_16x16x32_bf16 v[116:119], v[216:219], v[144:147], v[116:119]
	v_mfma_f32_16x16x32_bf16 v[112:115], v[224:227], v[144:147], v[112:115]
	v_mfma_f32_16x16x32_bf16 v[100:103], v[216:219], v[152:155], v[100:103]
	v_mfma_f32_16x16x32_bf16 v[96:99], v[224:227], v[152:155], v[96:99]
	v_mfma_f32_16x16x32_bf16 v[84:87], v[216:219], v[200:203], v[84:87]
	v_mfma_f32_16x16x32_bf16 v[80:83], v[224:227], v[200:203], v[80:83]
	v_mfma_f32_16x16x32_bf16 v[68:71], v[216:219], v[208:211], v[68:71]
	v_mfma_f32_16x16x32_bf16 v[64:67], v[224:227], v[208:211], v[64:67]
	v_mfma_f32_16x16x32_bf16 v[116:119], v[220:223], v[148:151], v[116:119]
	v_mfma_f32_16x16x32_bf16 v[112:115], v[228:231], v[148:151], v[112:115]
	v_mfma_f32_16x16x32_bf16 v[100:103], v[220:223], v[196:199], v[100:103]
	v_mfma_f32_16x16x32_bf16 v[96:99], v[228:231], v[196:199], v[96:99]
	v_mfma_f32_16x16x32_bf16 v[84:87], v[220:223], v[204:207], v[84:87]
	v_mfma_f32_16x16x32_bf16 v[80:83], v[228:231], v[204:207], v[80:83]
	v_mfma_f32_16x16x32_bf16 v[68:71], v[220:223], v[212:215], v[68:71]
	v_mfma_f32_16x16x32_bf16 v[64:67], v[228:231], v[212:215], v[64:67]
	s_barrier
	s_mov_b32 m0, s19
	v_lshl_add_u64 v[156:157], s[62:63], 0, v[160:161]
	global_load_lds_dwordx4 v[156:157], off
	v_lshl_add_u64 v[170:171], s[62:63], 0, v[158:159]
	s_mov_b32 m0, s20
	s_nop 0
	global_load_lds_dwordx4 v[170:171], off
	s_mov_b32 m0, s21
	v_lshl_add_u64 v[172:173], s[60:61], 0, v[160:161]
	global_load_lds_dwordx4 v[172:173], off
	v_lshl_add_u64 v[232:233], s[60:61], 0, v[158:159]
	s_mov_b32 m0, s22
	s_nop 0
	global_load_lds_dwordx4 v[232:233], off
	s_add_u32 s62, s62, s6
	s_addc_u32 s63, s63, s7
	s_mov_b32 m0, s24
	v_lshl_add_u64 v[234:235], s[62:63], 0, v[160:161]
	global_load_lds_dwordx4 v[234:235], off
	v_lshl_add_u64 v[236:237], s[62:63], 0, v[158:159]
	s_mov_b32 m0, s25
	s_nop 0
	global_load_lds_dwordx4 v[236:237], off
	ds_read_b128 v[144:147], v175 offset:16384
	ds_read_b128 v[148:151], v175 offset:17408
	ds_read_b128 v[152:155], v175 offset:18432
	ds_read_b128 v[196:199], v175 offset:19456
	ds_read_b128 v[200:203], v175 offset:20480
	ds_read_b128 v[204:207], v175 offset:21504
	ds_read_b128 v[208:211], v175 offset:22528
	ds_read_b128 v[212:215], v175 offset:23552
	s_waitcnt vmcnt(8)
	s_waitcnt lgkmcnt(0)
	s_barrier
; #define PG8_STAGE(bufoff, gbase) do { _Pragma("unroll") for (int _i = 0; _i < 2; ++_i) \
;         __builtin_amdgcn_global_load_lds((const unsigned*)((const char*)(gbase) + voffA[_i]), (LAS unsigned*)(lds + (bufoff) + ldsw + _i * 8192), 16, 0, 0); } while (0)
; #define PG8_LDA(dst, b, h) do { _Pragma("unroll") for (int m = 0; m < 4; ++m) _Pragma("unroll") for (int k = 0; k < 2; ++k) dst[m][k] = *(const LAS bf16x8*)(lds + PG8_SA(b, h) + aoff + m * 2048 + k * 1024); } while (0)
; #define PG8_LDB(dst, b, h) do { _Pragma("unroll") for (int n = 0; n < 2; ++n) _Pragma("unroll") for (int k = 0; k < 2; ++k) dst[n][k] = *(const LAS bf16x8*)(lds + PG8_SB(b, h) + boff + n * 2048 + k * 1024); } while (0)
; template <class Epi>
; DI void gemm_phase(const int TID, const int BID, LAS unsigned char* lds, const Gemm g, const Epi& E) {
;     ...
;         for (int t = 0; t < nt; t += 2) {
;             const bool last = (t == nt - 2);
;             const char* a1 = cA + (size_t)(t + 1) * kstep;
;             const char* a2 = last ? nA : cA + (size_t)(t + 2) * kstep; const char* b2 = last ? nB : cB + (size_t)(t + 2) * kstep;
;             const char* a3 = a2 + kstep; const char* b3 = b2 + kstep;
;             PG8_LDB(B0, 0, 0); PG8_SCHED; PG8_LDA(At, 0, 0); PG8_STAGE(PG8_SA(1, 1), a1 + hstep);
;             PG8_WAIT_L(8); PG8_BAR; PG8_WAIT_L(0); PG8_MMA(0, 0, At, B0); PG8_BAR; PG8_SCHED;
;             PG8_LDB(B1, 0, 1); PG8_STAGE(PG8_SB(0, 0), b2);
;             PG8_BAR; PG8_WAIT_L(0); PG8_MMA(0, 1, At, B1); PG8_BAR;
;             PG8_LDA(At, 0, 1); PG8_STAGE(PG8_SA(0, 0), a2);
;             PG8_BAR; PG8_WAIT_L(0); PG8_MMA(1, 0, At, B0); PG8_BAR; PG8_SCHED;
;             PG8_STAGE(PG8_SB(0, 1), b2 + hstep);
;             PG8_WAIT_V(6); PG8_BAR; PG8_MMA(1, 1, At, B1); PG8_BAR;
;             PG8_LDB(B0, 1, 0); PG8_SCHED; PG8_LDA(At, 1, 0); PG8_STAGE(PG8_SA(0, 1), a2 + hstep);
;             PG8_WAIT_L(8); PG8_BAR; PG8_WAIT_L(0); PG8_MMA(0, 0, At, B0); PG8_BAR; PG8_SCHED;
;             PG8_LDB(B1, 1, 1); PG8_STAGE(PG8_SB(1, 0), b3);
;             PG8_BAR; PG8_WAIT_L(0); PG8_MMA(0, 1, At, B1); PG8_BAR;
;             PG8_LDA(At, 1, 1); PG8_STAGE(PG8_SA(1, 0), a3);
;             PG8_BAR; PG8_WAIT_L(0); PG8_MMA(1, 0, At, B0); PG8_BAR; PG8_SCHED;
;             PG8_STAGE(PG8_SB(1, 1), b3 + hstep);
;             PG8_WAIT_V(6); PG8_BAR; PG8_MMA(1, 1, At, B1); PG8_BAR;
	v_mfma_f32_16x16x32_bf16 v[60:63], v[128:131], v[144:147], v[60:63]
	v_mfma_f32_16x16x32_bf16 v[56:59], v[136:139], v[144:147], v[56:59]
	v_mfma_f32_16x16x32_bf16 v[44:47], v[128:131], v[152:155], v[44:47]
	v_mfma_f32_16x16x32_bf16 v[40:43], v[136:139], v[152:155], v[40:43]
	v_mfma_f32_16x16x32_bf16 v[28:31], v[128:131], v[200:203], v[28:31]
	v_mfma_f32_16x16x32_bf16 v[24:27], v[136:139], v[200:203], v[24:27]
	v_mfma_f32_16x16x32_bf16 v[12:15], v[128:131], v[208:211], v[12:15]
	v_mfma_f32_16x16x32_bf16 v[8:11], v[136:139], v[208:211], v[8:11]
	v_mfma_f32_16x16x32_bf16 v[60:63], v[132:135], v[148:151], v[60:63]
	v_mfma_f32_16x16x32_bf16 v[56:59], v[140:143], v[148:151], v[56:59]
	v_mfma_f32_16x16x32_bf16 v[44:47], v[132:135], v[196:199], v[44:47]
	v_mfma_f32_16x16x32_bf16 v[40:43], v[140:143], v[196:199], v[40:43]
	v_mfma_f32_16x16x32_bf16 v[28:31], v[132:135], v[204:207], v[28:31]
	v_mfma_f32_16x16x32_bf16 v[24:27], v[140:143], v[204:207], v[24:27]
	v_mfma_f32_16x16x32_bf16 v[12:15], v[132:135], v[212:215], v[12:15]
	v_mfma_f32_16x16x32_bf16 v[8:11], v[140:143], v[212:215], v[8:11]
	v_mfma_f32_16x16x32_bf16 v[52:55], v[216:219], v[144:147], v[52:55]
	v_mfma_f32_16x16x32_bf16 v[48:51], v[224:227], v[144:147], v[48:51]
	v_mfma_f32_16x16x32_bf16 v[36:39], v[216:219], v[152:155], v[36:39]
	v_mfma_f32_16x16x32_bf16 v[32:35], v[224:227], v[152:155], v[32:35]
	v_mfma_f32_16x16x32_bf16 v[20:23], v[216:219], v[200:203], v[20:23]
	v_mfma_f32_16x16x32_bf16 v[16:19], v[224:227], v[200:203], v[16:19]
	v_mfma_f32_16x16x32_bf16 v[4:7], v[216:219], v[208:211], v[4:7]
	v_mfma_f32_16x16x32_bf16 v[0:3], v[224:227], v[208:211], v[0:3]
	v_mfma_f32_16x16x32_bf16 v[52:55], v[220:223], v[148:151], v[52:55]
	v_mfma_f32_16x16x32_bf16 v[48:51], v[228:231], v[148:151], v[48:51]
	v_mfma_f32_16x16x32_bf16 v[36:39], v[220:223], v[196:199], v[36:39]
	v_mfma_f32_16x16x32_bf16 v[32:35], v[228:231], v[196:199], v[32:35]
	v_mfma_f32_16x16x32_bf16 v[20:23], v[220:223], v[204:207], v[20:23]
	v_mfma_f32_16x16x32_bf16 v[16:19], v[228:231], v[204:207], v[16:19]
	v_mfma_f32_16x16x32_bf16 v[4:7], v[220:223], v[212:215], v[4:7]
	v_mfma_f32_16x16x32_bf16 v[0:3], v[228:231], v[212:215], v[0:3]
	s_barrier
	s_add_u32 s60, s60, s6
	s_addc_u32 s61, s61, s7
	s_mov_b32 m0, s26
	v_lshl_add_u64 v[216:217], s[60:61], 0, v[160:161]
	global_load_lds_dwordx4 v[216:217], off
	v_lshl_add_u64 v[216:217], s[60:61], 0, v[158:159]
	s_mov_b32 m0, s27
	s_nop 0
	global_load_lds_dwordx4 v[216:217], off
	v_add_u32_e32 v140, s28, v192
	ds_read_b128 v[128:131], v140
	ds_read_b128 v[132:135], v140 offset:1024
	ds_read_b128 v[136:139], v140 offset:2048
	ds_read_b128 v[140:143], v140 offset:3072
	ds_read_b128 v[144:147], v175 offset:32768
	ds_read_b128 v[148:151], v175 offset:33792
	ds_read_b128 v[152:155], v175 offset:34816
	ds_read_b128 v[196:199], v175 offset:35840
	ds_read_b128 v[200:203], v175 offset:36864
	ds_read_b128 v[204:207], v175 offset:37888
	ds_read_b128 v[208:211], v175 offset:38912
	ds_read_b128 v[212:215], v175 offset:39936
	v_add_u32_e32 v195, s64, v192
	ds_read_b128 v[216:219], v195
	ds_read_b128 v[220:223], v195 offset:1024
	ds_read_b128 v[224:227], v195 offset:2048
	ds_read_b128 v[228:231], v195 offset:3072
	s_waitcnt vmcnt(8)
	s_waitcnt lgkmcnt(0)
	s_barrier
	v_mfma_f32_16x16x32_bf16 v[124:127], v[128:131], v[144:147], v[124:127]
	v_mfma_f32_16x16x32_bf16 v[120:123], v[136:139], v[144:147], v[120:123]
	v_mfma_f32_16x16x32_bf16 v[108:111], v[128:131], v[152:155], v[108:111]
	v_mfma_f32_16x16x32_bf16 v[104:107], v[136:139], v[152:155], v[104:107]
	v_mfma_f32_16x16x32_bf16 v[92:95], v[128:131], v[200:203], v[92:95]
	v_mfma_f32_16x16x32_bf16 v[88:91], v[136:139], v[200:203], v[88:91]
	v_mfma_f32_16x16x32_bf16 v[76:79], v[128:131], v[208:211], v[76:79]
	v_mfma_f32_16x16x32_bf16 v[72:75], v[136:139], v[208:211], v[72:75]
	v_mfma_f32_16x16x32_bf16 v[124:127], v[132:135], v[148:151], v[124:127]
	v_mfma_f32_16x16x32_bf16 v[120:123], v[140:143], v[148:151], v[120:123]
	v_mfma_f32_16x16x32_bf16 v[108:111], v[132:135], v[196:199], v[108:111]
	v_mfma_f32_16x16x32_bf16 v[104:107], v[140:143], v[196:199], v[104:107]
	v_mfma_f32_16x16x32_bf16 v[92:95], v[132:135], v[204:207], v[92:95]
	v_mfma_f32_16x16x32_bf16 v[88:91], v[140:143], v[204:207], v[88:91]
	v_mfma_f32_16x16x32_bf16 v[76:79], v[132:135], v[212:215], v[76:79]
	v_mfma_f32_16x16x32_bf16 v[72:75], v[140:143], v[212:215], v[72:75]
	v_mfma_f32_16x16x32_bf16 v[116:119], v[216:219], v[144:147], v[116:119]
	v_mfma_f32_16x16x32_bf16 v[112:115], v[224:227], v[144:147], v[112:115]
	v_mfma_f32_16x16x32_bf16 v[100:103], v[216:219], v[152:155], v[100:103]
	v_mfma_f32_16x16x32_bf16 v[96:99], v[224:227], v[152:155], v[96:99]
	v_mfma_f32_16x16x32_bf16 v[84:87], v[216:219], v[200:203], v[84:87]
	v_mfma_f32_16x16x32_bf16 v[80:83], v[224:227], v[200:203], v[80:83]
	v_mfma_f32_16x16x32_bf16 v[68:71], v[216:219], v[208:211], v[68:71]
	v_mfma_f32_16x16x32_bf16 v[64:67], v[224:227], v[208:211], v[64:67]
	v_mfma_f32_16x16x32_bf16 v[116:119], v[220:223], v[148:151], v[116:119]
	v_mfma_f32_16x16x32_bf16 v[112:115], v[228:231], v[148:151], v[112:115]
	v_mfma_f32_16x16x32_bf16 v[100:103], v[220:223], v[196:199], v[100:103]
	v_mfma_f32_16x16x32_bf16 v[96:99], v[228:231], v[196:199], v[96:99]
	v_mfma_f32_16x16x32_bf16 v[84:87], v[220:223], v[204:207], v[84:87]
	v_mfma_f32_16x16x32_bf16 v[80:83], v[228:231], v[204:207], v[80:83]
	v_mfma_f32_16x16x32_bf16 v[68:71], v[220:223], v[212:215], v[68:71]
	v_mfma_f32_16x16x32_bf16 v[64:67], v[228:231], v[212:215], v[64:67]
	s_barrier
; #define PG8_STAGE(bufoff, gbase) do { _Pragma("unroll") for (int _i = 0; _i < 2; ++_i) \
;         __builtin_amdgcn_global_load_lds((const unsigned*)((const char*)(gbase) + voffA[_i]), (LAS unsigned*)(lds + (bufoff) + ldsw + _i * 8192), 16, 0, 0); } while (0)
; #define PG8_LDA(dst, b, h) do { _Pragma("unroll") for (int m = 0; m < 4; ++m) _Pragma("unroll") for (int k = 0; k < 2; ++k) dst[m][k] = *(const LAS bf16x8*)(lds + PG8_SA(b, h) + aoff + m * 2048 + k * 1024); } while (0)
; #define PG8_LDB(dst, b, h) do { _Pragma("unroll") for (int n = 0; n < 2; ++n) _Pragma("unroll") for (int k = 0; k < 2; ++k) dst[n][k] = *(const LAS bf16x8*)(lds + PG8_SB(b, h) + boff + n * 2048 + k * 1024); } while (0)
; template <class Epi>
; DI void gemm_phase(const int TID, const int BID, LAS unsigned char* lds, const Gemm g, const Epi& E) {
;     ...
;         for (int t = 0; t < nt; t += 2) {
;             const bool last = (t == nt - 2);
;             const char* a1 = cA + (size_t)(t + 1) * kstep;
;             const char* a2 = last ? nA : cA + (size_t)(t + 2) * kstep; const char* b2 = last ? nB : cB + (size_t)(t + 2) * kstep;
;             const char* a3 = a2 + kstep; const char* b3 = b2 + kstep;
;             PG8_LDB(B0, 0, 0); PG8_SCHED; PG8_LDA(At, 0, 0); PG8_STAGE(PG8_SA(1, 1), a1 + hstep);
;             PG8_WAIT_L(8); PG8_BAR; PG8_WAIT_L(0); PG8_MMA(0, 0, At, B0); PG8_BAR; PG8_SCHED;
;             PG8_LDB(B1, 0, 1); PG8_STAGE(PG8_SB(0, 0), b2);
;             PG8_BAR; PG8_WAIT_L(0); PG8_MMA(0, 1, At, B1); PG8_BAR;
;             PG8_LDA(At, 0, 1); PG8_STAGE(PG8_SA(0, 0), a2);
;             PG8_BAR; PG8_WAIT_L(0); PG8_MMA(1, 0, At, B0); PG8_BAR; PG8_SCHED;
;             PG8_STAGE(PG8_SB(0, 1), b2 + hstep);
;             PG8_WAIT_V(6); PG8_BAR; PG8_MMA(1, 1, At, B1); PG8_BAR;
;             PG8_LDB(B0, 1, 0); PG8_SCHED; PG8_LDA(At, 1, 0); PG8_STAGE(PG8_SA(0, 1), a2 + hstep);
;             PG8_WAIT_L(8); PG8_BAR; PG8_WAIT_L(0); PG8_MMA(0, 0, At, B0); PG8_BAR; PG8_SCHED;
;             PG8_LDB(B1, 1, 1); PG8_STAGE(PG8_SB(1, 0), b3);
;             PG8_BAR; PG8_WAIT_L(0); PG8_MMA(0, 1, At, B1); PG8_BAR;
;             PG8_LDA(At, 1, 1); PG8_STAGE(PG8_SA(1, 0), a3);
;             PG8_BAR; PG8_WAIT_L(0); PG8_MMA(1, 0, At, B0); PG8_BAR; PG8_SCHED;
;             PG8_STAGE(PG8_SB(1, 1), b3 + hstep);
;             PG8_WAIT_V(6); PG8_BAR; PG8_MMA(1, 1, At, B1); PG8_BAR;
	s_mov_b32 m0, s29
	v_lshl_add_u64 v[156:157], v[156:157], 0, s[92:93]
	global_load_lds_dwordx4 v[156:157], off
	v_lshl_add_u64 v[156:157], v[170:171], 0, s[92:93]
	s_mov_b32 m0, s30
	s_nop 0
	global_load_lds_dwordx4 v[156:157], off
	s_mov_b32 m0, s31
	v_lshl_add_u64 v[156:157], v[172:173], 0, s[92:93]
	global_load_lds_dwordx4 v[156:157], off
	v_lshl_add_u64 v[156:157], v[232:233], 0, s[92:93]
	s_mov_b32 m0, s33
	s_nop 0
	global_load_lds_dwordx4 v[156:157], off
	s_mov_b32 m0, s65
	v_lshl_add_u64 v[156:157], v[234:235], 0, s[92:93]
	global_load_lds_dwordx4 v[156:157], off
	v_lshl_add_u64 v[156:157], v[236:237], 0, s[92:93]
	s_mov_b32 m0, s66
	s_nop 0
	global_load_lds_dwordx4 v[156:157], off
	ds_read_b128 v[144:147], v175 offset:49152
	ds_read_b128 v[148:151], v175 offset:50176
	ds_read_b128 v[152:155], v175 offset:51200
	ds_read_b128 v[196:199], v175 offset:52224
	ds_read_b128 v[200:203], v175 offset:53248
	ds_read_b128 v[204:207], v175 offset:54272
	ds_read_b128 v[208:211], v175 offset:55296
	ds_read_b128 v[212:215], v175 offset:56320
	s_waitcnt vmcnt(8)
	s_waitcnt lgkmcnt(0)
	s_barrier
	v_mfma_f32_16x16x32_bf16 v[60:63], v[128:131], v[144:147], v[60:63]
	v_mfma_f32_16x16x32_bf16 v[56:59], v[136:139], v[144:147], v[56:59]
	v_mfma_f32_16x16x32_bf16 v[44:47], v[128:131], v[152:155], v[44:47]
	v_mfma_f32_16x16x32_bf16 v[40:43], v[136:139], v[152:155], v[40:43]
	v_mfma_f32_16x16x32_bf16 v[28:31], v[128:131], v[200:203], v[28:31]
	v_mfma_f32_16x16x32_bf16 v[24:27], v[136:139], v[200:203], v[24:27]
	v_mfma_f32_16x16x32_bf16 v[12:15], v[128:131], v[208:211], v[12:15]
	v_mfma_f32_16x16x32_bf16 v[8:11], v[136:139], v[208:211], v[8:11]
	v_mfma_f32_16x16x32_bf16 v[60:63], v[132:135], v[148:151], v[60:63]
	v_mfma_f32_16x16x32_bf16 v[56:59], v[140:143], v[148:151], v[56:59]
	v_mfma_f32_16x16x32_bf16 v[44:47], v[132:135], v[196:199], v[44:47]
	v_mfma_f32_16x16x32_bf16 v[40:43], v[140:143], v[196:199], v[40:43]
	v_mfma_f32_16x16x32_bf16 v[28:31], v[132:135], v[204:207], v[28:31]
	v_mfma_f32_16x16x32_bf16 v[24:27], v[140:143], v[204:207], v[24:27]
	v_mfma_f32_16x16x32_bf16 v[12:15], v[132:135], v[212:215], v[12:15]
	v_mfma_f32_16x16x32_bf16 v[8:11], v[140:143], v[212:215], v[8:11]
	v_mfma_f32_16x16x32_bf16 v[52:55], v[216:219], v[144:147], v[52:55]
	v_mfma_f32_16x16x32_bf16 v[48:51], v[224:227], v[144:147], v[48:51]
	v_mfma_f32_16x16x32_bf16 v[36:39], v[216:219], v[152:155], v[36:39]
	v_mfma_f32_16x16x32_bf16 v[32:35], v[224:227], v[152:155], v[32:35]
	v_mfma_f32_16x16x32_bf16 v[20:23], v[216:219], v[200:203], v[20:23]
	v_mfma_f32_16x16x32_bf16 v[16:19], v[224:227], v[200:203], v[16:19]
	v_mfma_f32_16x16x32_bf16 v[4:7], v[216:219], v[208:211], v[4:7]
	v_mfma_f32_16x16x32_bf16 v[0:3], v[224:227], v[208:211], v[0:3]
	v_mfma_f32_16x16x32_bf16 v[52:55], v[220:223], v[148:151], v[52:55]
	v_mfma_f32_16x16x32_bf16 v[48:51], v[228:231], v[148:151], v[48:51]
	v_mfma_f32_16x16x32_bf16 v[36:39], v[220:223], v[196:199], v[36:39]
	v_mfma_f32_16x16x32_bf16 v[32:35], v[228:231], v[196:199], v[32:35]
	v_mfma_f32_16x16x32_bf16 v[20:23], v[220:223], v[204:207], v[20:23]
	v_mfma_f32_16x16x32_bf16 v[16:19], v[228:231], v[204:207], v[16:19]
	v_mfma_f32_16x16x32_bf16 v[4:7], v[220:223], v[212:215], v[4:7]
	v_mfma_f32_16x16x32_bf16 v[0:3], v[228:231], v[212:215], v[0:3]
	s_add_u32 s4, s4, 0x100
	s_addc_u32 s5, s5, 0
	s_add_u32 vcc_lo, vcc_lo, 0x100
	s_addc_u32 vcc_hi, vcc_hi, 0
	s_cmp_ge_i32 s16, s67
	s_mov_b32 s60, s16
	s_barrier
	s_cbranch_scc0 .LBB0_491

; #define PG8_STAGE(bufoff, gbase) do { _Pragma("unroll") for (int _i = 0; _i < 2; ++_i) \
;         __builtin_amdgcn_global_load_lds((const unsigned*)((const char*)(gbase) + voffA[_i]), (LAS unsigned*)(lds + (bufoff) + ldsw + _i * 8192), 16, 0, 0); } while (0)
; #define PG8_WAIT_V(n) asm volatile("s_waitcnt vmcnt(" #n ")" ::: "memory")
; #define PG8_WAIT_L(n) asm volatile("s_waitcnt lgkmcnt(" #n ")" ::: "memory")
; template <class Epi>
; DI void gemm_phase(const int TID, const int BID, LAS unsigned char* lds, const Gemm g, const Epi& E) {
;     ...
;         const bool has_next = S.next(ui + 1, nxt);
;         const char* nA = has_next ? (const char*)g.A + (size_t)nxt.pm * tstep + (size_t)nxt.k0 * 2 : cA; const char* nB = has_next ? (const char*)g.Bt + (size_t)nxt.pn * tstep + (size_t)nxt.k0 * 2 : cB;
;         const int nt = cur.nt;
;         for (int t = 0; t < nt; t += 2) {
;             const bool last = (t == nt - 2);
;             const char* a1 = cA + (size_t)(t + 1) * kstep;
;             const char* a2 = last ? nA : cA + (size_t)(t + 2) * kstep; const char* b2 = last ? nB : cB + (size_t)(t + 2) * kstep;
;             const char* a3 = a2 + kstep; const char* b3 = b2 + kstep;
;             PG8_LDB(B0, 0, 0); PG8_SCHED; PG8_LDA(At, 0, 0); PG8_STAGE(PG8_SA(1, 1), a1 + hstep);
;             PG8_WAIT_L(8); PG8_BAR; PG8_WAIT_L(0); PG8_MMA(0, 0, At, B0); PG8_BAR; PG8_SCHED;
;             PG8_LDB(B1, 0, 1); PG8_STAGE(PG8_SB(0, 0), b2);
;             PG8_BAR; PG8_WAIT_L(0); PG8_MMA(0, 1, At, B1); PG8_BAR;
;             PG8_LDA(At, 0, 1); PG8_STAGE(PG8_SA(0, 0), a2);
;             PG8_BAR; PG8_WAIT_L(0); PG8_MMA(1, 0, At, B0); PG8_BAR; PG8_SCHED;
;             PG8_STAGE(PG8_SB(0, 1), b2 + hstep);
;             PG8_WAIT_V(6); PG8_BAR; PG8_MMA(1, 1, At, B1); PG8_BAR;
;             PG8_LDB(B0, 1, 0); PG8_SCHED; PG8_LDA(At, 1, 0); PG8_STAGE(PG8_SA(0, 1), a2 + hstep);
;             PG8_WAIT_L(8); PG8_BAR; PG8_WAIT_L(0); PG8_MMA(0, 0, At, B0); PG8_BAR; PG8_SCHED;
;             PG8_LDB(B1, 1, 1); PG8_STAGE(PG8_SB(1, 0), b3);
;             PG8_BAR; PG8_WAIT_L(0); PG8_MMA(0, 1, At, B1); PG8_BAR;
;             PG8_LDA(At, 1, 1); PG8_STAGE(PG8_SA(1, 0), a3);
;             PG8_BAR; PG8_WAIT_L(0); PG8_MMA(1, 0, At, B0); PG8_BAR; PG8_SCHED;
;             PG8_STAGE(PG8_SB(1, 1), b3 + hstep);
;             PG8_WAIT_V(6); PG8_BAR; PG8_MMA(1, 1, At, B1); PG8_BAR;
.LBB0_568:
	s_add_i32 s31, s30, 2
	s_add_u32 s56, s4, 0x80
	s_addc_u32 s57, s5, 0
	s_cmp_eq_u32 s22, s30
	s_cselect_b32 s57, s53, s57
	s_cselect_b32 s56, s52, s56
	s_cselect_b32 s59, s55, s29
	s_cselect_b32 s58, s54, s28
	v_lshl_add_u64 v[170:171], s[4:5], 0, v[152:153]
	s_add_i32 m0, s62, 0xc000
	global_load_lds_dwordx4 v[170:171], off
	v_lshl_add_u64 v[170:171], s[4:5], 0, v[154:155]
	s_add_i32 m0, s62, 0xe000
	s_nop 0
	global_load_lds_dwordx4 v[170:171], off
	v_add_u32_e32 v168, s65, v161
	ds_read_b128 v[156:159], v168
	ds_read_b128 v[176:179], v168 offset:1024
	ds_read_b128 v[180:183], v168 offset:2048
	ds_read_b128 v[184:187], v168 offset:3072
	ds_read_b128 v[188:191], v175
	ds_read_b128 v[192:195], v175 offset:1024
	ds_read_b128 v[196:199], v175 offset:2048
	ds_read_b128 v[200:203], v175 offset:3072
	ds_read_b128 v[204:207], v175 offset:4096
	ds_read_b128 v[208:211], v175 offset:5120
	ds_read_b128 v[212:215], v175 offset:6144
	ds_read_b128 v[216:219], v175 offset:7168
	v_add_u32_e32 v168, s64, v161
	ds_read_b128 v[220:223], v168
	ds_read_b128 v[224:227], v168 offset:1024
	ds_read_b128 v[228:231], v168 offset:2048
	ds_read_b128 v[246:249], v168 offset:3072
	s_waitcnt vmcnt(8)
	s_waitcnt lgkmcnt(0)
	s_barrier
	v_mfma_f32_16x16x32_bf16 v[124:127], v[156:159], v[188:191], v[124:127]
	v_mfma_f32_16x16x32_bf16 v[120:123], v[180:183], v[188:191], v[120:123]
	v_mfma_f32_16x16x32_bf16 v[116:119], v[156:159], v[196:199], v[116:119]
	v_mfma_f32_16x16x32_bf16 v[112:115], v[180:183], v[196:199], v[112:115]
	v_mfma_f32_16x16x32_bf16 v[108:111], v[156:159], v[204:207], v[108:111]
	v_mfma_f32_16x16x32_bf16 v[104:107], v[180:183], v[204:207], v[104:107]
	v_mfma_f32_16x16x32_bf16 v[100:103], v[156:159], v[212:215], v[100:103]
	v_mfma_f32_16x16x32_bf16 v[96:99], v[180:183], v[212:215], v[96:99]
	v_mfma_f32_16x16x32_bf16 v[124:127], v[176:179], v[192:195], v[124:127]
	v_mfma_f32_16x16x32_bf16 v[120:123], v[184:187], v[192:195], v[120:123]
	v_mfma_f32_16x16x32_bf16 v[116:119], v[176:179], v[200:203], v[116:119]
	v_mfma_f32_16x16x32_bf16 v[112:115], v[184:187], v[200:203], v[112:115]
	v_mfma_f32_16x16x32_bf16 v[108:111], v[176:179], v[208:211], v[108:111]
	v_mfma_f32_16x16x32_bf16 v[104:107], v[184:187], v[208:211], v[104:107]
	v_mfma_f32_16x16x32_bf16 v[100:103], v[176:179], v[216:219], v[100:103]
	v_mfma_f32_16x16x32_bf16 v[96:99], v[184:187], v[216:219], v[96:99]
	v_mfma_f32_16x16x32_bf16 v[56:59], v[220:223], v[188:191], v[56:59]
	v_mfma_f32_16x16x32_bf16 v[60:63], v[228:231], v[188:191], v[60:63]
	v_mfma_f32_16x16x32_bf16 v[52:55], v[220:223], v[196:199], v[52:55]
	v_mfma_f32_16x16x32_bf16 v[48:51], v[228:231], v[196:199], v[48:51]
	v_mfma_f32_16x16x32_bf16 v[44:47], v[220:223], v[204:207], v[44:47]
	v_mfma_f32_16x16x32_bf16 v[40:43], v[228:231], v[204:207], v[40:43]
	v_mfma_f32_16x16x32_bf16 v[36:39], v[220:223], v[212:215], v[36:39]
	v_mfma_f32_16x16x32_bf16 v[32:35], v[228:231], v[212:215], v[32:35]
	v_mfma_f32_16x16x32_bf16 v[56:59], v[224:227], v[192:195], v[56:59]
	v_mfma_f32_16x16x32_bf16 v[60:63], v[246:249], v[192:195], v[60:63]
	v_mfma_f32_16x16x32_bf16 v[52:55], v[224:227], v[200:203], v[52:55]
	v_mfma_f32_16x16x32_bf16 v[48:51], v[246:249], v[200:203], v[48:51]
	v_mfma_f32_16x16x32_bf16 v[44:47], v[224:227], v[208:211], v[44:47]
	v_mfma_f32_16x16x32_bf16 v[40:43], v[246:249], v[208:211], v[40:43]
	v_mfma_f32_16x16x32_bf16 v[36:39], v[224:227], v[216:219], v[36:39]
	v_mfma_f32_16x16x32_bf16 v[32:35], v[246:249], v[216:219], v[32:35]
	s_barrier
	s_mov_b32 m0, s66
	v_lshl_add_u64 v[170:171], s[58:59], 0, v[128:129]
	global_load_lds_dwordx4 v[170:171], off
	v_lshl_add_u64 v[172:173], s[58:59], 0, v[130:131]
	s_mov_b32 m0, s67
	s_nop 0
	global_load_lds_dwordx4 v[172:173], off
	s_mov_b32 m0, s62
	v_lshl_add_u64 v[232:233], s[56:57], 0, v[128:129]
	global_load_lds_dwordx4 v[232:233], off
	v_lshl_add_u64 v[234:235], s[56:57], 0, v[130:131]
	s_mov_b32 m0, s63
	s_nop 0
	global_load_lds_dwordx4 v[234:235], off
	s_add_u32 s58, s58, s6
	s_addc_u32 s59, s59, s7
	s_mov_b32 m0, s10
	v_lshl_add_u64 v[236:237], s[58:59], 0, v[128:129]
	global_load_lds_dwordx4 v[236:237], off
	v_lshl_add_u64 v[238:239], s[58:59], 0, v[130:131]
	s_mov_b32 m0, s11
	s_nop 0
	global_load_lds_dwordx4 v[238:239], off
	ds_read_b128 v[188:191], v175 offset:16384
	ds_read_b128 v[192:195], v175 offset:17408
	ds_read_b128 v[196:199], v175 offset:18432
	ds_read_b128 v[200:203], v175 offset:19456
	ds_read_b128 v[204:207], v175 offset:20480
	ds_read_b128 v[208:211], v175 offset:21504
	ds_read_b128 v[212:215], v175 offset:22528
	ds_read_b128 v[216:219], v175 offset:23552
	s_waitcnt vmcnt(8)
	s_waitcnt lgkmcnt(0)
	s_barrier
; #define PG8_STAGE(bufoff, gbase) do { _Pragma("unroll") for (int _i = 0; _i < 2; ++_i) \
;         __builtin_amdgcn_global_load_lds((const unsigned*)((const char*)(gbase) + voffA[_i]), (LAS unsigned*)(lds + (bufoff) + ldsw + _i * 8192), 16, 0, 0); } while (0)
; #define PG8_LDA(dst, b, h) do { _Pragma("unroll") for (int m = 0; m < 4; ++m) _Pragma("unroll") for (int k = 0; k < 2; ++k) dst[m][k] = *(const LAS bf16x8*)(lds + PG8_SA(b, h) + aoff + m * 2048 + k * 1024); } while (0)
; #define PG8_LDB(dst, b, h) do { _Pragma("unroll") for (int n = 0; n < 2; ++n) _Pragma("unroll") for (int k = 0; k < 2; ++k) dst[n][k] = *(const LAS bf16x8*)(lds + PG8_SB(b, h) + boff + n * 2048 + k * 1024); } while (0)
; template <class Epi>
; DI void gemm_phase(const int TID, const int BID, LAS unsigned char* lds, const Gemm g, const Epi& E) {
;     ...
;         for (int t = 0; t < nt; t += 2) {
;             const bool last = (t == nt - 2);
;             const char* a1 = cA + (size_t)(t + 1) * kstep;
;             const char* a2 = last ? nA : cA + (size_t)(t + 2) * kstep; const char* b2 = last ? nB : cB + (size_t)(t + 2) * kstep;
;             const char* a3 = a2 + kstep; const char* b3 = b2 + kstep;
;             PG8_LDB(B0, 0, 0); PG8_SCHED; PG8_LDA(At, 0, 0); PG8_STAGE(PG8_SA(1, 1), a1 + hstep);
;             PG8_WAIT_L(8); PG8_BAR; PG8_WAIT_L(0); PG8_MMA(0, 0, At, B0); PG8_BAR; PG8_SCHED;
;             PG8_LDB(B1, 0, 1); PG8_STAGE(PG8_SB(0, 0), b2);
;             PG8_BAR; PG8_WAIT_L(0); PG8_MMA(0, 1, At, B1); PG8_BAR;
;             PG8_LDA(At, 0, 1); PG8_STAGE(PG8_SA(0, 0), a2);
;             PG8_BAR; PG8_WAIT_L(0); PG8_MMA(1, 0, At, B0); PG8_BAR; PG8_SCHED;
;             PG8_STAGE(PG8_SB(0, 1), b2 + hstep);
;             PG8_WAIT_V(6); PG8_BAR; PG8_MMA(1, 1, At, B1); PG8_BAR;
;             PG8_LDB(B0, 1, 0); PG8_SCHED; PG8_LDA(At, 1, 0); PG8_STAGE(PG8_SA(0, 1), a2 + hstep);
;             PG8_WAIT_L(8); PG8_BAR; PG8_WAIT_L(0); PG8_MMA(0, 0, At, B0); PG8_BAR; PG8_SCHED;
;             PG8_LDB(B1, 1, 1); PG8_STAGE(PG8_SB(1, 0), b3);
;             PG8_BAR; PG8_WAIT_L(0); PG8_MMA(0, 1, At, B1); PG8_BAR;
;             PG8_LDA(At, 1, 1); PG8_STAGE(PG8_SA(1, 0), a3);
;             PG8_BAR; PG8_WAIT_L(0); PG8_MMA(1, 0, At, B0); PG8_BAR; PG8_SCHED;
;             PG8_STAGE(PG8_SB(1, 1), b3 + hstep);
;             PG8_WAIT_V(6); PG8_BAR; PG8_MMA(1, 1, At, B1); PG8_BAR;
	v_mfma_f32_16x16x32_bf16 v[92:95], v[156:159], v[188:191], v[92:95]
	v_mfma_f32_16x16x32_bf16 v[88:91], v[180:183], v[188:191], v[88:91]
	v_mfma_f32_16x16x32_bf16 v[84:87], v[156:159], v[196:199], v[84:87]
	v_mfma_f32_16x16x32_bf16 v[80:83], v[180:183], v[196:199], v[80:83]
	v_mfma_f32_16x16x32_bf16 v[76:79], v[156:159], v[204:207], v[76:79]
	v_mfma_f32_16x16x32_bf16 v[72:75], v[180:183], v[204:207], v[72:75]
	v_mfma_f32_16x16x32_bf16 v[68:71], v[156:159], v[212:215], v[68:71]
	v_mfma_f32_16x16x32_bf16 v[64:67], v[180:183], v[212:215], v[64:67]
	v_mfma_f32_16x16x32_bf16 v[92:95], v[176:179], v[192:195], v[92:95]
	v_mfma_f32_16x16x32_bf16 v[88:91], v[184:187], v[192:195], v[88:91]
	v_mfma_f32_16x16x32_bf16 v[84:87], v[176:179], v[200:203], v[84:87]
	v_mfma_f32_16x16x32_bf16 v[80:83], v[184:187], v[200:203], v[80:83]
	v_mfma_f32_16x16x32_bf16 v[76:79], v[176:179], v[208:211], v[76:79]
	v_mfma_f32_16x16x32_bf16 v[72:75], v[184:187], v[208:211], v[72:75]
	v_mfma_f32_16x16x32_bf16 v[68:71], v[176:179], v[216:219], v[68:71]
	v_mfma_f32_16x16x32_bf16 v[64:67], v[184:187], v[216:219], v[64:67]
	v_mfma_f32_16x16x32_bf16 v[28:31], v[220:223], v[188:191], v[28:31]
	v_mfma_f32_16x16x32_bf16 v[24:27], v[228:231], v[188:191], v[24:27]
	v_mfma_f32_16x16x32_bf16 v[20:23], v[220:223], v[196:199], v[20:23]
	v_mfma_f32_16x16x32_bf16 v[16:19], v[228:231], v[196:199], v[16:19]
	v_mfma_f32_16x16x32_bf16 v[12:15], v[220:223], v[204:207], v[12:15]
	v_mfma_f32_16x16x32_bf16 v[8:11], v[228:231], v[204:207], v[8:11]
	v_mfma_f32_16x16x32_bf16 v[4:7], v[220:223], v[212:215], v[4:7]
	v_mfma_f32_16x16x32_bf16 v[0:3], v[228:231], v[212:215], v[0:3]
	v_mfma_f32_16x16x32_bf16 v[28:31], v[224:227], v[192:195], v[28:31]
	v_mfma_f32_16x16x32_bf16 v[24:27], v[246:249], v[192:195], v[24:27]
	v_mfma_f32_16x16x32_bf16 v[20:23], v[224:227], v[200:203], v[20:23]
	v_mfma_f32_16x16x32_bf16 v[16:19], v[246:249], v[200:203], v[16:19]
	v_mfma_f32_16x16x32_bf16 v[12:15], v[224:227], v[208:211], v[12:15]
	v_mfma_f32_16x16x32_bf16 v[8:11], v[246:249], v[208:211], v[8:11]
	v_mfma_f32_16x16x32_bf16 v[4:7], v[224:227], v[216:219], v[4:7]
	v_mfma_f32_16x16x32_bf16 v[0:3], v[246:249], v[216:219], v[0:3]
	s_barrier
	s_add_u32 s56, s56, s6
	s_addc_u32 s57, s57, s7
	s_mov_b32 m0, s33
	v_lshl_add_u64 v[220:221], s[56:57], 0, v[128:129]
	global_load_lds_dwordx4 v[220:221], off
	v_lshl_add_u64 v[220:221], s[56:57], 0, v[130:131]
	s_mov_b32 m0, s15
	s_nop 0
	global_load_lds_dwordx4 v[220:221], off
	v_add_u32_e32 v168, s76, v161
	ds_read_b128 v[156:159], v168
	ds_read_b128 v[176:179], v168 offset:1024
	ds_read_b128 v[180:183], v168 offset:2048
	ds_read_b128 v[184:187], v168 offset:3072
	ds_read_b128 v[188:191], v175 offset:32768
	ds_read_b128 v[192:195], v175 offset:33792
	ds_read_b128 v[196:199], v175 offset:34816
	ds_read_b128 v[200:203], v175 offset:35840
	ds_read_b128 v[204:207], v175 offset:36864
	ds_read_b128 v[208:211], v175 offset:37888
	ds_read_b128 v[212:215], v175 offset:38912
	ds_read_b128 v[216:219], v175 offset:39936
	v_add_u32_e32 v168, s9, v161
	ds_read_b128 v[220:223], v168
	ds_read_b128 v[224:227], v168 offset:1024
	ds_read_b128 v[228:231], v168 offset:2048
	ds_read_b128 v[246:249], v168 offset:3072
	s_waitcnt vmcnt(8)
	s_waitcnt lgkmcnt(0)
	s_barrier
	v_mfma_f32_16x16x32_bf16 v[124:127], v[156:159], v[188:191], v[124:127]
	v_mfma_f32_16x16x32_bf16 v[120:123], v[180:183], v[188:191], v[120:123]
	v_mfma_f32_16x16x32_bf16 v[116:119], v[156:159], v[196:199], v[116:119]
	v_mfma_f32_16x16x32_bf16 v[112:115], v[180:183], v[196:199], v[112:115]
	v_mfma_f32_16x16x32_bf16 v[108:111], v[156:159], v[204:207], v[108:111]
	v_mfma_f32_16x16x32_bf16 v[104:107], v[180:183], v[204:207], v[104:107]
	v_mfma_f32_16x16x32_bf16 v[100:103], v[156:159], v[212:215], v[100:103]
	v_mfma_f32_16x16x32_bf16 v[96:99], v[180:183], v[212:215], v[96:99]
	v_mfma_f32_16x16x32_bf16 v[124:127], v[176:179], v[192:195], v[124:127]
	v_mfma_f32_16x16x32_bf16 v[120:123], v[184:187], v[192:195], v[120:123]
	v_mfma_f32_16x16x32_bf16 v[116:119], v[176:179], v[200:203], v[116:119]
	v_mfma_f32_16x16x32_bf16 v[112:115], v[184:187], v[200:203], v[112:115]
	v_mfma_f32_16x16x32_bf16 v[108:111], v[176:179], v[208:211], v[108:111]
	v_mfma_f32_16x16x32_bf16 v[104:107], v[184:187], v[208:211], v[104:107]
	v_mfma_f32_16x16x32_bf16 v[100:103], v[176:179], v[216:219], v[100:103]
	v_mfma_f32_16x16x32_bf16 v[96:99], v[184:187], v[216:219], v[96:99]
	v_mfma_f32_16x16x32_bf16 v[56:59], v[220:223], v[188:191], v[56:59]
	v_mfma_f32_16x16x32_bf16 v[60:63], v[228:231], v[188:191], v[60:63]
	v_mfma_f32_16x16x32_bf16 v[52:55], v[220:223], v[196:199], v[52:55]
	v_mfma_f32_16x16x32_bf16 v[48:51], v[228:231], v[196:199], v[48:51]
	v_mfma_f32_16x16x32_bf16 v[44:47], v[220:223], v[204:207], v[44:47]
	v_mfma_f32_16x16x32_bf16 v[40:43], v[228:231], v[204:207], v[40:43]
	v_mfma_f32_16x16x32_bf16 v[36:39], v[220:223], v[212:215], v[36:39]
	v_mfma_f32_16x16x32_bf16 v[32:35], v[228:231], v[212:215], v[32:35]
	v_mfma_f32_16x16x32_bf16 v[56:59], v[224:227], v[192:195], v[56:59]
	v_mfma_f32_16x16x32_bf16 v[60:63], v[246:249], v[192:195], v[60:63]
	v_mfma_f32_16x16x32_bf16 v[52:55], v[224:227], v[200:203], v[52:55]
	v_mfma_f32_16x16x32_bf16 v[48:51], v[246:249], v[200:203], v[48:51]
	v_mfma_f32_16x16x32_bf16 v[44:47], v[224:227], v[208:211], v[44:47]
	v_mfma_f32_16x16x32_bf16 v[40:43], v[246:249], v[208:211], v[40:43]
	v_mfma_f32_16x16x32_bf16 v[36:39], v[224:227], v[216:219], v[36:39]
	v_mfma_f32_16x16x32_bf16 v[32:35], v[246:249], v[216:219], v[32:35]
	s_barrier
; #define PG8_STAGE(bufoff, gbase) do { _Pragma("unroll") for (int _i = 0; _i < 2; ++_i) \
;         __builtin_amdgcn_global_load_lds((const unsigned*)((const char*)(gbase) + voffA[_i]), (LAS unsigned*)(lds + (bufoff) + ldsw + _i * 8192), 16, 0, 0); } while (0)
; #define PG8_LDA(dst, b, h) do { _Pragma("unroll") for (int m = 0; m < 4; ++m) _Pragma("unroll") for (int k = 0; k < 2; ++k) dst[m][k] = *(const LAS bf16x8*)(lds + PG8_SA(b, h) + aoff + m * 2048 + k * 1024); } while (0)
; #define PG8_LDB(dst, b, h) do { _Pragma("unroll") for (int n = 0; n < 2; ++n) _Pragma("unroll") for (int k = 0; k < 2; ++k) dst[n][k] = *(const LAS bf16x8*)(lds + PG8_SB(b, h) + boff + n * 2048 + k * 1024); } while (0)
; template <class Epi>
; DI void gemm_phase(const int TID, const int BID, LAS unsigned char* lds, const Gemm g, const Epi& E) {
;     ...
;         for (int t = 0; t < nt; t += 2) {
;             const bool last = (t == nt - 2);
;             const char* a1 = cA + (size_t)(t + 1) * kstep;
;             const char* a2 = last ? nA : cA + (size_t)(t + 2) * kstep; const char* b2 = last ? nB : cB + (size_t)(t + 2) * kstep;
;             const char* a3 = a2 + kstep; const char* b3 = b2 + kstep;
;             PG8_LDB(B0, 0, 0); PG8_SCHED; PG8_LDA(At, 0, 0); PG8_STAGE(PG8_SA(1, 1), a1 + hstep);
;             PG8_WAIT_L(8); PG8_BAR; PG8_WAIT_L(0); PG8_MMA(0, 0, At, B0); PG8_BAR; PG8_SCHED;
;             PG8_LDB(B1, 0, 1); PG8_STAGE(PG8_SB(0, 0), b2);
;             PG8_BAR; PG8_WAIT_L(0); PG8_MMA(0, 1, At, B1); PG8_BAR;
;             PG8_LDA(At, 0, 1); PG8_STAGE(PG8_SA(0, 0), a2);
;             PG8_BAR; PG8_WAIT_L(0); PG8_MMA(1, 0, At, B0); PG8_BAR; PG8_SCHED;
;             PG8_STAGE(PG8_SB(0, 1), b2 + hstep);
;             PG8_WAIT_V(6); PG8_BAR; PG8_MMA(1, 1, At, B1); PG8_BAR;
;             PG8_LDB(B0, 1, 0); PG8_SCHED; PG8_LDA(At, 1, 0); PG8_STAGE(PG8_SA(0, 1), a2 + hstep);
;             PG8_WAIT_L(8); PG8_BAR; PG8_WAIT_L(0); PG8_MMA(0, 0, At, B0); PG8_BAR; PG8_SCHED;
;             PG8_LDB(B1, 1, 1); PG8_STAGE(PG8_SB(1, 0), b3);
;             PG8_BAR; PG8_WAIT_L(0); PG8_MMA(0, 1, At, B1); PG8_BAR;
;             PG8_LDA(At, 1, 1); PG8_STAGE(PG8_SA(1, 0), a3);
;             PG8_BAR; PG8_WAIT_L(0); PG8_MMA(1, 0, At, B0); PG8_BAR; PG8_SCHED;
;             PG8_STAGE(PG8_SB(1, 1), b3 + hstep);
;             PG8_WAIT_V(6); PG8_BAR; PG8_MMA(1, 1, At, B1); PG8_BAR;
	s_mov_b32 m0, s77
	v_lshl_add_u64 v[170:171], v[170:171], 0, s[92:93]
	global_load_lds_dwordx4 v[170:171], off
	v_lshl_add_u64 v[170:171], v[172:173], 0, s[92:93]
	s_mov_b32 m0, s80
	s_nop 0
	global_load_lds_dwordx4 v[170:171], off
	s_mov_b32 m0, s81
	v_lshl_add_u64 v[170:171], v[232:233], 0, s[92:93]
	global_load_lds_dwordx4 v[170:171], off
	v_lshl_add_u64 v[170:171], v[234:235], 0, s[92:93]
	s_mov_b32 m0, s8
	s_nop 0
	global_load_lds_dwordx4 v[170:171], off
	s_mov_b32 m0, s16
	v_lshl_add_u64 v[170:171], v[236:237], 0, s[92:93]
	global_load_lds_dwordx4 v[170:171], off
	v_lshl_add_u64 v[170:171], v[238:239], 0, s[92:93]
	s_mov_b32 m0, s17
	s_nop 0
	global_load_lds_dwordx4 v[170:171], off
	ds_read_b128 v[188:191], v175 offset:49152
	ds_read_b128 v[192:195], v175 offset:50176
	ds_read_b128 v[196:199], v175 offset:51200
	ds_read_b128 v[200:203], v175 offset:52224
	ds_read_b128 v[204:207], v175 offset:53248
	ds_read_b128 v[208:211], v175 offset:54272
	ds_read_b128 v[212:215], v175 offset:55296
	ds_read_b128 v[216:219], v175 offset:56320
	s_waitcnt vmcnt(8)
	s_waitcnt lgkmcnt(0)
	s_barrier
	v_mfma_f32_16x16x32_bf16 v[92:95], v[156:159], v[188:191], v[92:95]
	v_mfma_f32_16x16x32_bf16 v[88:91], v[180:183], v[188:191], v[88:91]
	v_mfma_f32_16x16x32_bf16 v[84:87], v[156:159], v[196:199], v[84:87]
	v_mfma_f32_16x16x32_bf16 v[80:83], v[180:183], v[196:199], v[80:83]
	v_mfma_f32_16x16x32_bf16 v[76:79], v[156:159], v[204:207], v[76:79]
	v_mfma_f32_16x16x32_bf16 v[72:75], v[180:183], v[204:207], v[72:75]
	v_mfma_f32_16x16x32_bf16 v[68:71], v[156:159], v[212:215], v[68:71]
	v_mfma_f32_16x16x32_bf16 v[64:67], v[180:183], v[212:215], v[64:67]
	v_mfma_f32_16x16x32_bf16 v[92:95], v[176:179], v[192:195], v[92:95]
	v_mfma_f32_16x16x32_bf16 v[88:91], v[184:187], v[192:195], v[88:91]
	v_mfma_f32_16x16x32_bf16 v[84:87], v[176:179], v[200:203], v[84:87]
	v_mfma_f32_16x16x32_bf16 v[80:83], v[184:187], v[200:203], v[80:83]
	v_mfma_f32_16x16x32_bf16 v[76:79], v[176:179], v[208:211], v[76:79]
	v_mfma_f32_16x16x32_bf16 v[72:75], v[184:187], v[208:211], v[72:75]
	v_mfma_f32_16x16x32_bf16 v[68:71], v[176:179], v[216:219], v[68:71]
	v_mfma_f32_16x16x32_bf16 v[64:67], v[184:187], v[216:219], v[64:67]
	v_mfma_f32_16x16x32_bf16 v[28:31], v[220:223], v[188:191], v[28:31]
	v_mfma_f32_16x16x32_bf16 v[24:27], v[228:231], v[188:191], v[24:27]
	v_mfma_f32_16x16x32_bf16 v[20:23], v[220:223], v[196:199], v[20:23]
	v_mfma_f32_16x16x32_bf16 v[16:19], v[228:231], v[196:199], v[16:19]
	v_mfma_f32_16x16x32_bf16 v[12:15], v[220:223], v[204:207], v[12:15]
	v_mfma_f32_16x16x32_bf16 v[8:11], v[228:231], v[204:207], v[8:11]
	v_mfma_f32_16x16x32_bf16 v[4:7], v[220:223], v[212:215], v[4:7]
	v_mfma_f32_16x16x32_bf16 v[0:3], v[228:231], v[212:215], v[0:3]
	v_mfma_f32_16x16x32_bf16 v[28:31], v[224:227], v[192:195], v[28:31]
	v_mfma_f32_16x16x32_bf16 v[24:27], v[246:249], v[192:195], v[24:27]
	v_mfma_f32_16x16x32_bf16 v[20:23], v[224:227], v[200:203], v[20:23]
	v_mfma_f32_16x16x32_bf16 v[16:19], v[246:249], v[200:203], v[16:19]
	v_mfma_f32_16x16x32_bf16 v[12:15], v[224:227], v[208:211], v[12:15]
	v_mfma_f32_16x16x32_bf16 v[8:11], v[246:249], v[208:211], v[8:11]
	v_mfma_f32_16x16x32_bf16 v[4:7], v[224:227], v[216:219], v[4:7]
	v_mfma_f32_16x16x32_bf16 v[0:3], v[246:249], v[216:219], v[0:3]
	s_add_u32 s4, s4, 0x100
	s_addc_u32 s5, s5, 0
	s_add_u32 s28, s28, 0x100
	s_addc_u32 s29, s29, 0
	s_cmp_ge_i32 s31, s21
	s_mov_b32 s30, s31
	s_barrier
	s_cbranch_scc0 .LBB0_568
	v_readlane_b32 s31, v255, 8

; #define PG8_STAGE(bufoff, gbase) do { _Pragma("unroll") for (int _i = 0; _i < 2; ++_i) \
;         __builtin_amdgcn_global_load_lds((const unsigned*)((const char*)(gbase) + voffA[_i]), (LAS unsigned*)(lds + (bufoff) + ldsw + _i * 8192), 16, 0, 0); } while (0)
; #define PG8_WAIT_V(n) asm volatile("s_waitcnt vmcnt(" #n ")" ::: "memory")
; #define PG8_WAIT_L(n) asm volatile("s_waitcnt lgkmcnt(" #n ")" ::: "memory")
; template <class Epi>
; DI void gemm_phase(const int TID, const int BID, LAS unsigned char* lds, const Gemm g, const Epi& E) {
;     ...
;         const bool has_next = S.next(ui + 1, nxt);
;         const char* nA = has_next ? (const char*)g.A + (size_t)nxt.pm * tstep + (size_t)nxt.k0 * 2 : cA; const char* nB = has_next ? (const char*)g.Bt + (size_t)nxt.pn * tstep + (size_t)nxt.k0 * 2 : cB;
;         const int nt = cur.nt;
;         for (int t = 0; t < nt; t += 2) {
;             const bool last = (t == nt - 2);
;             const char* a1 = cA + (size_t)(t + 1) * kstep;
;             const char* a2 = last ? nA : cA + (size_t)(t + 2) * kstep; const char* b2 = last ? nB : cB + (size_t)(t + 2) * kstep;
;             const char* a3 = a2 + kstep; const char* b3 = b2 + kstep;
;             PG8_LDB(B0, 0, 0); PG8_SCHED; PG8_LDA(At, 0, 0); PG8_STAGE(PG8_SA(1, 1), a1 + hstep);
;             PG8_WAIT_L(8); PG8_BAR; PG8_WAIT_L(0); PG8_MMA(0, 0, At, B0); PG8_BAR; PG8_SCHED;
;             PG8_LDB(B1, 0, 1); PG8_STAGE(PG8_SB(0, 0), b2);
;             PG8_BAR; PG8_WAIT_L(0); PG8_MMA(0, 1, At, B1); PG8_BAR;
;             PG8_LDA(At, 0, 1); PG8_STAGE(PG8_SA(0, 0), a2);
;             PG8_BAR; PG8_WAIT_L(0); PG8_MMA(1, 0, At, B0); PG8_BAR; PG8_SCHED;
;             PG8_STAGE(PG8_SB(0, 1), b2 + hstep);
;             PG8_WAIT_V(6); PG8_BAR; PG8_MMA(1, 1, At, B1); PG8_BAR;
;             PG8_LDB(B0, 1, 0); PG8_SCHED; PG8_LDA(At, 1, 0); PG8_STAGE(PG8_SA(0, 1), a2 + hstep);
;             PG8_WAIT_L(8); PG8_BAR; PG8_WAIT_L(0); PG8_MMA(0, 0, At, B0); PG8_BAR; PG8_SCHED;
;             PG8_LDB(B1, 1, 1); PG8_STAGE(PG8_SB(1, 0), b3);
;             PG8_BAR; PG8_WAIT_L(0); PG8_MMA(0, 1, At, B1); PG8_BAR;
;             PG8_LDA(At, 1, 1); PG8_STAGE(PG8_SA(1, 0), a3);
;             PG8_BAR; PG8_WAIT_L(0); PG8_MMA(1, 0, At, B0); PG8_BAR; PG8_SCHED;
;             PG8_STAGE(PG8_SB(1, 1), b3 + hstep);
;             PG8_WAIT_V(6); PG8_BAR; PG8_MMA(1, 1, At, B1); PG8_BAR;
.LBB0_746:
	s_add_i32 s24, s23, 2
	s_add_u32 s4, s2, 0x80
	s_addc_u32 s5, s3, 0
	s_cmp_eq_u32 s0, s23
	s_cselect_b32 s5, s55, s5
	s_cselect_b32 s4, s54, s4
	s_cselect_b32 s59, s57, s20
	s_cselect_b32 s58, s56, s19
	v_lshl_add_u64 v[170:171], s[2:3], 0, v[176:177]
	s_add_i32 m0, s84, 0xc000
	global_load_lds_dwordx4 v[170:171], off
	v_lshl_add_u64 v[170:171], s[2:3], 0, v[178:179]
	s_add_i32 m0, s84, 0xe000
	s_nop 0
	global_load_lds_dwordx4 v[170:171], off
	v_add_u32_e32 v76, s65, v175
	ds_read_b128 v[64:67], v76
	ds_read_b128 v[68:71], v76 offset:1024
	ds_read_b128 v[72:75], v76 offset:2048
	ds_read_b128 v[76:79], v76 offset:3072
	ds_read_b128 v[188:191], v187
	ds_read_b128 v[192:195], v187 offset:1024
	ds_read_b128 v[196:199], v187 offset:2048
	ds_read_b128 v[200:203], v187 offset:3072
	ds_read_b128 v[204:207], v187 offset:4096
	ds_read_b128 v[208:211], v187 offset:5120
	ds_read_b128 v[212:215], v187 offset:6144
	ds_read_b128 v[216:219], v187 offset:7168
	v_add_u32_e32 v168, s63, v175
	ds_read_b128 v[220:223], v168
	ds_read_b128 v[224:227], v168 offset:1024
	ds_read_b128 v[228:231], v168 offset:2048
	ds_read_b128 v[246:249], v168 offset:3072
	s_waitcnt vmcnt(8)
	s_waitcnt lgkmcnt(0)
	s_barrier
	v_mfma_f32_16x16x32_bf16 v[140:143], v[64:67], v[188:191], v[140:143]
	v_mfma_f32_16x16x32_bf16 v[136:139], v[72:75], v[188:191], v[136:139]
	v_mfma_f32_16x16x32_bf16 v[124:127], v[64:67], v[196:199], v[124:127]
	v_mfma_f32_16x16x32_bf16 v[120:123], v[72:75], v[196:199], v[120:123]
	v_mfma_f32_16x16x32_bf16 v[108:111], v[64:67], v[204:207], v[108:111]
	v_mfma_f32_16x16x32_bf16 v[104:107], v[72:75], v[204:207], v[104:107]
	v_mfma_f32_16x16x32_bf16 v[92:95], v[64:67], v[212:215], v[92:95]
	v_mfma_f32_16x16x32_bf16 v[88:91], v[72:75], v[212:215], v[88:91]
	v_mfma_f32_16x16x32_bf16 v[140:143], v[68:71], v[192:195], v[140:143]
	v_mfma_f32_16x16x32_bf16 v[136:139], v[76:79], v[192:195], v[136:139]
	v_mfma_f32_16x16x32_bf16 v[124:127], v[68:71], v[200:203], v[124:127]
	v_mfma_f32_16x16x32_bf16 v[120:123], v[76:79], v[200:203], v[120:123]
	v_mfma_f32_16x16x32_bf16 v[108:111], v[68:71], v[208:211], v[108:111]
	v_mfma_f32_16x16x32_bf16 v[104:107], v[76:79], v[208:211], v[104:107]
	v_mfma_f32_16x16x32_bf16 v[92:95], v[68:71], v[216:219], v[92:95]
	v_mfma_f32_16x16x32_bf16 v[88:91], v[76:79], v[216:219], v[88:91]
	v_mfma_f32_16x16x32_bf16 v[132:135], v[220:223], v[188:191], v[132:135]
	v_mfma_f32_16x16x32_bf16 v[128:131], v[228:231], v[188:191], v[128:131]
	v_mfma_f32_16x16x32_bf16 v[116:119], v[220:223], v[196:199], v[116:119]
	v_mfma_f32_16x16x32_bf16 v[112:115], v[228:231], v[196:199], v[112:115]
	v_mfma_f32_16x16x32_bf16 v[100:103], v[220:223], v[204:207], v[100:103]
	v_mfma_f32_16x16x32_bf16 v[96:99], v[228:231], v[204:207], v[96:99]
	v_mfma_f32_16x16x32_bf16 v[84:87], v[220:223], v[212:215], v[84:87]
	v_mfma_f32_16x16x32_bf16 v[80:83], v[228:231], v[212:215], v[80:83]
	v_mfma_f32_16x16x32_bf16 v[132:135], v[224:227], v[192:195], v[132:135]
	v_mfma_f32_16x16x32_bf16 v[128:131], v[246:249], v[192:195], v[128:131]
	v_mfma_f32_16x16x32_bf16 v[116:119], v[224:227], v[200:203], v[116:119]
	v_mfma_f32_16x16x32_bf16 v[112:115], v[246:249], v[200:203], v[112:115]
	v_mfma_f32_16x16x32_bf16 v[100:103], v[224:227], v[208:211], v[100:103]
	v_mfma_f32_16x16x32_bf16 v[96:99], v[246:249], v[208:211], v[96:99]
	v_mfma_f32_16x16x32_bf16 v[84:87], v[224:227], v[216:219], v[84:87]
	v_mfma_f32_16x16x32_bf16 v[80:83], v[246:249], v[216:219], v[80:83]
	s_barrier
	s_mov_b32 m0, s66
	v_lshl_add_u64 v[170:171], s[58:59], 0, v[144:145]
	global_load_lds_dwordx4 v[170:171], off
	v_lshl_add_u64 v[172:173], s[58:59], 0, v[146:147]
	s_mov_b32 m0, s67
	s_nop 0
	global_load_lds_dwordx4 v[172:173], off
	s_mov_b32 m0, s84
	v_lshl_add_u64 v[232:233], s[4:5], 0, v[144:145]
	global_load_lds_dwordx4 v[232:233], off
	v_lshl_add_u64 v[234:235], s[4:5], 0, v[146:147]
	s_mov_b32 m0, s62
	s_nop 0
	global_load_lds_dwordx4 v[234:235], off
	s_add_u32 s26, s58, s6
	s_addc_u32 s27, s59, s7
	s_mov_b32 m0, s64
	v_lshl_add_u64 v[236:237], s[26:27], 0, v[144:145]
	global_load_lds_dwordx4 v[236:237], off
	v_lshl_add_u64 v[238:239], s[26:27], 0, v[146:147]
	s_mov_b32 m0, s10
	s_nop 0
	global_load_lds_dwordx4 v[238:239], off
	ds_read_b128 v[188:191], v187 offset:16384
	ds_read_b128 v[192:195], v187 offset:17408
	ds_read_b128 v[196:199], v187 offset:18432
	ds_read_b128 v[200:203], v187 offset:19456
	ds_read_b128 v[204:207], v187 offset:20480
	ds_read_b128 v[208:211], v187 offset:21504
	ds_read_b128 v[212:215], v187 offset:22528
	ds_read_b128 v[216:219], v187 offset:23552
	s_waitcnt vmcnt(8)
	s_waitcnt lgkmcnt(0)
	s_barrier
; #define PG8_STAGE(bufoff, gbase) do { _Pragma("unroll") for (int _i = 0; _i < 2; ++_i) \
;         __builtin_amdgcn_global_load_lds((const unsigned*)((const char*)(gbase) + voffA[_i]), (LAS unsigned*)(lds + (bufoff) + ldsw + _i * 8192), 16, 0, 0); } while (0)
; #define PG8_LDA(dst, b, h) do { _Pragma("unroll") for (int m = 0; m < 4; ++m) _Pragma("unroll") for (int k = 0; k < 2; ++k) dst[m][k] = *(const LAS bf16x8*)(lds + PG8_SA(b, h) + aoff + m * 2048 + k * 1024); } while (0)
; #define PG8_LDB(dst, b, h) do { _Pragma("unroll") for (int n = 0; n < 2; ++n) _Pragma("unroll") for (int k = 0; k < 2; ++k) dst[n][k] = *(const LAS bf16x8*)(lds + PG8_SB(b, h) + boff + n * 2048 + k * 1024); } while (0)
; template <class Epi>
; DI void gemm_phase(const int TID, const int BID, LAS unsigned char* lds, const Gemm g, const Epi& E) {
;     ...
;         for (int t = 0; t < nt; t += 2) {
;             const bool last = (t == nt - 2);
;             const char* a1 = cA + (size_t)(t + 1) * kstep;
;             const char* a2 = last ? nA : cA + (size_t)(t + 2) * kstep; const char* b2 = last ? nB : cB + (size_t)(t + 2) * kstep;
;             const char* a3 = a2 + kstep; const char* b3 = b2 + kstep;
;             PG8_LDB(B0, 0, 0); PG8_SCHED; PG8_LDA(At, 0, 0); PG8_STAGE(PG8_SA(1, 1), a1 + hstep);
;             PG8_WAIT_L(8); PG8_BAR; PG8_WAIT_L(0); PG8_MMA(0, 0, At, B0); PG8_BAR; PG8_SCHED;
;             PG8_LDB(B1, 0, 1); PG8_STAGE(PG8_SB(0, 0), b2);
;             PG8_BAR; PG8_WAIT_L(0); PG8_MMA(0, 1, At, B1); PG8_BAR;
;             PG8_LDA(At, 0, 1); PG8_STAGE(PG8_SA(0, 0), a2);
;             PG8_BAR; PG8_WAIT_L(0); PG8_MMA(1, 0, At, B0); PG8_BAR; PG8_SCHED;
;             PG8_STAGE(PG8_SB(0, 1), b2 + hstep);
;             PG8_WAIT_V(6); PG8_BAR; PG8_MMA(1, 1, At, B1); PG8_BAR;
;             PG8_LDB(B0, 1, 0); PG8_SCHED; PG8_LDA(At, 1, 0); PG8_STAGE(PG8_SA(0, 1), a2 + hstep);
;             PG8_WAIT_L(8); PG8_BAR; PG8_WAIT_L(0); PG8_MMA(0, 0, At, B0); PG8_BAR; PG8_SCHED;
;             PG8_LDB(B1, 1, 1); PG8_STAGE(PG8_SB(1, 0), b3);
;             PG8_BAR; PG8_WAIT_L(0); PG8_MMA(0, 1, At, B1); PG8_BAR;
;             PG8_LDA(At, 1, 1); PG8_STAGE(PG8_SA(1, 0), a3);
;             PG8_BAR; PG8_WAIT_L(0); PG8_MMA(1, 0, At, B0); PG8_BAR; PG8_SCHED;
;             PG8_STAGE(PG8_SB(1, 1), b3 + hstep);
;             PG8_WAIT_V(6); PG8_BAR; PG8_MMA(1, 1, At, B1); PG8_BAR;
	v_mfma_f32_16x16x32_bf16 v[60:63], v[64:67], v[188:191], v[60:63]
	v_mfma_f32_16x16x32_bf16 v[56:59], v[72:75], v[188:191], v[56:59]
	v_mfma_f32_16x16x32_bf16 v[44:47], v[64:67], v[196:199], v[44:47]
	v_mfma_f32_16x16x32_bf16 v[40:43], v[72:75], v[196:199], v[40:43]
	v_mfma_f32_16x16x32_bf16 v[28:31], v[64:67], v[204:207], v[28:31]
	v_mfma_f32_16x16x32_bf16 v[24:27], v[72:75], v[204:207], v[24:27]
	v_mfma_f32_16x16x32_bf16 v[12:15], v[64:67], v[212:215], v[12:15]
	v_mfma_f32_16x16x32_bf16 v[8:11], v[72:75], v[212:215], v[8:11]
	v_mfma_f32_16x16x32_bf16 v[60:63], v[68:71], v[192:195], v[60:63]
	v_mfma_f32_16x16x32_bf16 v[56:59], v[76:79], v[192:195], v[56:59]
	v_mfma_f32_16x16x32_bf16 v[44:47], v[68:71], v[200:203], v[44:47]
	v_mfma_f32_16x16x32_bf16 v[40:43], v[76:79], v[200:203], v[40:43]
	v_mfma_f32_16x16x32_bf16 v[28:31], v[68:71], v[208:211], v[28:31]
	v_mfma_f32_16x16x32_bf16 v[24:27], v[76:79], v[208:211], v[24:27]
	v_mfma_f32_16x16x32_bf16 v[12:15], v[68:71], v[216:219], v[12:15]
	v_mfma_f32_16x16x32_bf16 v[8:11], v[76:79], v[216:219], v[8:11]
	v_mfma_f32_16x16x32_bf16 v[52:55], v[220:223], v[188:191], v[52:55]
	v_mfma_f32_16x16x32_bf16 v[48:51], v[228:231], v[188:191], v[48:51]
	v_mfma_f32_16x16x32_bf16 v[36:39], v[220:223], v[196:199], v[36:39]
	v_mfma_f32_16x16x32_bf16 v[32:35], v[228:231], v[196:199], v[32:35]
	v_mfma_f32_16x16x32_bf16 v[20:23], v[220:223], v[204:207], v[20:23]
	v_mfma_f32_16x16x32_bf16 v[16:19], v[228:231], v[204:207], v[16:19]
	v_mfma_f32_16x16x32_bf16 v[0:3], v[220:223], v[212:215], v[0:3]
	v_mfma_f32_16x16x32_bf16 v[4:7], v[228:231], v[212:215], v[4:7]
	v_mfma_f32_16x16x32_bf16 v[52:55], v[224:227], v[192:195], v[52:55]
	v_mfma_f32_16x16x32_bf16 v[48:51], v[246:249], v[192:195], v[48:51]
	v_mfma_f32_16x16x32_bf16 v[36:39], v[224:227], v[200:203], v[36:39]
	v_mfma_f32_16x16x32_bf16 v[32:35], v[246:249], v[200:203], v[32:35]
	v_mfma_f32_16x16x32_bf16 v[20:23], v[224:227], v[208:211], v[20:23]
	v_mfma_f32_16x16x32_bf16 v[16:19], v[246:249], v[208:211], v[16:19]
	v_mfma_f32_16x16x32_bf16 v[0:3], v[224:227], v[216:219], v[0:3]
	v_mfma_f32_16x16x32_bf16 v[4:7], v[246:249], v[216:219], v[4:7]
	s_barrier
	s_add_u32 s4, s4, s6
	s_addc_u32 s5, s5, s7
	s_mov_b32 m0, s11
	v_lshl_add_u64 v[220:221], s[4:5], 0, v[144:145]
	global_load_lds_dwordx4 v[220:221], off
	v_lshl_add_u64 v[220:221], s[4:5], 0, v[146:147]
	s_mov_b32 m0, s12
	s_nop 0
	global_load_lds_dwordx4 v[220:221], off
	v_add_u32_e32 v76, s13, v175
	ds_read_b128 v[64:67], v76
	ds_read_b128 v[68:71], v76 offset:1024
	ds_read_b128 v[72:75], v76 offset:2048
	ds_read_b128 v[76:79], v76 offset:3072
	ds_read_b128 v[188:191], v187 offset:32768
	ds_read_b128 v[192:195], v187 offset:33792
	ds_read_b128 v[196:199], v187 offset:34816
	ds_read_b128 v[200:203], v187 offset:35840
	ds_read_b128 v[204:207], v187 offset:36864
	ds_read_b128 v[208:211], v187 offset:37888
	ds_read_b128 v[212:215], v187 offset:38912
	ds_read_b128 v[216:219], v187 offset:39936
	v_add_u32_e32 v168, s80, v175
	ds_read_b128 v[220:223], v168
	ds_read_b128 v[224:227], v168 offset:1024
	ds_read_b128 v[228:231], v168 offset:2048
	ds_read_b128 v[246:249], v168 offset:3072
	s_waitcnt vmcnt(8)
	s_waitcnt lgkmcnt(0)
	s_barrier
	v_mfma_f32_16x16x32_bf16 v[140:143], v[64:67], v[188:191], v[140:143]
	v_mfma_f32_16x16x32_bf16 v[136:139], v[72:75], v[188:191], v[136:139]
	v_mfma_f32_16x16x32_bf16 v[124:127], v[64:67], v[196:199], v[124:127]
	v_mfma_f32_16x16x32_bf16 v[120:123], v[72:75], v[196:199], v[120:123]
	v_mfma_f32_16x16x32_bf16 v[108:111], v[64:67], v[204:207], v[108:111]
	v_mfma_f32_16x16x32_bf16 v[104:107], v[72:75], v[204:207], v[104:107]
	v_mfma_f32_16x16x32_bf16 v[92:95], v[64:67], v[212:215], v[92:95]
	v_mfma_f32_16x16x32_bf16 v[88:91], v[72:75], v[212:215], v[88:91]
	v_mfma_f32_16x16x32_bf16 v[140:143], v[68:71], v[192:195], v[140:143]
	v_mfma_f32_16x16x32_bf16 v[136:139], v[76:79], v[192:195], v[136:139]
	v_mfma_f32_16x16x32_bf16 v[124:127], v[68:71], v[200:203], v[124:127]
	v_mfma_f32_16x16x32_bf16 v[120:123], v[76:79], v[200:203], v[120:123]
	v_mfma_f32_16x16x32_bf16 v[108:111], v[68:71], v[208:211], v[108:111]
	v_mfma_f32_16x16x32_bf16 v[104:107], v[76:79], v[208:211], v[104:107]
	v_mfma_f32_16x16x32_bf16 v[92:95], v[68:71], v[216:219], v[92:95]
	v_mfma_f32_16x16x32_bf16 v[88:91], v[76:79], v[216:219], v[88:91]
	v_mfma_f32_16x16x32_bf16 v[132:135], v[220:223], v[188:191], v[132:135]
	v_mfma_f32_16x16x32_bf16 v[128:131], v[228:231], v[188:191], v[128:131]
	v_mfma_f32_16x16x32_bf16 v[116:119], v[220:223], v[196:199], v[116:119]
	v_mfma_f32_16x16x32_bf16 v[112:115], v[228:231], v[196:199], v[112:115]
	v_mfma_f32_16x16x32_bf16 v[100:103], v[220:223], v[204:207], v[100:103]
	v_mfma_f32_16x16x32_bf16 v[96:99], v[228:231], v[204:207], v[96:99]
	v_mfma_f32_16x16x32_bf16 v[84:87], v[220:223], v[212:215], v[84:87]
	v_mfma_f32_16x16x32_bf16 v[80:83], v[228:231], v[212:215], v[80:83]
	v_mfma_f32_16x16x32_bf16 v[132:135], v[224:227], v[192:195], v[132:135]
	v_mfma_f32_16x16x32_bf16 v[128:131], v[246:249], v[192:195], v[128:131]
	v_mfma_f32_16x16x32_bf16 v[116:119], v[224:227], v[200:203], v[116:119]
	v_mfma_f32_16x16x32_bf16 v[112:115], v[246:249], v[200:203], v[112:115]
	v_mfma_f32_16x16x32_bf16 v[100:103], v[224:227], v[208:211], v[100:103]
	v_mfma_f32_16x16x32_bf16 v[96:99], v[246:249], v[208:211], v[96:99]
	v_mfma_f32_16x16x32_bf16 v[84:87], v[224:227], v[216:219], v[84:87]
	v_mfma_f32_16x16x32_bf16 v[80:83], v[246:249], v[216:219], v[80:83]
	s_barrier
; #define PG8_STAGE(bufoff, gbase) do { _Pragma("unroll") for (int _i = 0; _i < 2; ++_i) \
;         __builtin_amdgcn_global_load_lds((const unsigned*)((const char*)(gbase) + voffA[_i]), (LAS unsigned*)(lds + (bufoff) + ldsw + _i * 8192), 16, 0, 0); } while (0)
; #define PG8_LDA(dst, b, h) do { _Pragma("unroll") for (int m = 0; m < 4; ++m) _Pragma("unroll") for (int k = 0; k < 2; ++k) dst[m][k] = *(const LAS bf16x8*)(lds + PG8_SA(b, h) + aoff + m * 2048 + k * 1024); } while (0)
; #define PG8_LDB(dst, b, h) do { _Pragma("unroll") for (int n = 0; n < 2; ++n) _Pragma("unroll") for (int k = 0; k < 2; ++k) dst[n][k] = *(const LAS bf16x8*)(lds + PG8_SB(b, h) + boff + n * 2048 + k * 1024); } while (0)
; template <class Epi>
; DI void gemm_phase(const int TID, const int BID, LAS unsigned char* lds, const Gemm g, const Epi& E) {
;     ...
;         for (int t = 0; t < nt; t += 2) {
;             const bool last = (t == nt - 2);
;             const char* a1 = cA + (size_t)(t + 1) * kstep;
;             const char* a2 = last ? nA : cA + (size_t)(t + 2) * kstep; const char* b2 = last ? nB : cB + (size_t)(t + 2) * kstep;
;             const char* a3 = a2 + kstep; const char* b3 = b2 + kstep;
;             PG8_LDB(B0, 0, 0); PG8_SCHED; PG8_LDA(At, 0, 0); PG8_STAGE(PG8_SA(1, 1), a1 + hstep);
;             PG8_WAIT_L(8); PG8_BAR; PG8_WAIT_L(0); PG8_MMA(0, 0, At, B0); PG8_BAR; PG8_SCHED;
;             PG8_LDB(B1, 0, 1); PG8_STAGE(PG8_SB(0, 0), b2);
;             PG8_BAR; PG8_WAIT_L(0); PG8_MMA(0, 1, At, B1); PG8_BAR;
;             PG8_LDA(At, 0, 1); PG8_STAGE(PG8_SA(0, 0), a2);
;             PG8_BAR; PG8_WAIT_L(0); PG8_MMA(1, 0, At, B0); PG8_BAR; PG8_SCHED;
;             PG8_STAGE(PG8_SB(0, 1), b2 + hstep);
;             PG8_WAIT_V(6); PG8_BAR; PG8_MMA(1, 1, At, B1); PG8_BAR;
;             PG8_LDB(B0, 1, 0); PG8_SCHED; PG8_LDA(At, 1, 0); PG8_STAGE(PG8_SA(0, 1), a2 + hstep);
;             PG8_WAIT_L(8); PG8_BAR; PG8_WAIT_L(0); PG8_MMA(0, 0, At, B0); PG8_BAR; PG8_SCHED;
;             PG8_LDB(B1, 1, 1); PG8_STAGE(PG8_SB(1, 0), b3);
;             PG8_BAR; PG8_WAIT_L(0); PG8_MMA(0, 1, At, B1); PG8_BAR;
;             PG8_LDA(At, 1, 1); PG8_STAGE(PG8_SA(1, 0), a3);
;             PG8_BAR; PG8_WAIT_L(0); PG8_MMA(1, 0, At, B0); PG8_BAR; PG8_SCHED;
;             PG8_STAGE(PG8_SB(1, 1), b3 + hstep);
;             PG8_WAIT_V(6); PG8_BAR; PG8_MMA(1, 1, At, B1); PG8_BAR;
	s_mov_b32 m0, s76
	v_lshl_add_u64 v[170:171], v[170:171], 0, s[92:93]
	global_load_lds_dwordx4 v[170:171], off
	v_lshl_add_u64 v[170:171], v[172:173], 0, s[92:93]
	s_mov_b32 m0, s77
	s_nop 0
	global_load_lds_dwordx4 v[170:171], off
	s_mov_b32 m0, s33
	v_lshl_add_u64 v[170:171], v[232:233], 0, s[92:93]
	global_load_lds_dwordx4 v[170:171], off
	v_lshl_add_u64 v[170:171], v[234:235], 0, s[92:93]
	s_mov_b32 m0, s15
	s_nop 0
	global_load_lds_dwordx4 v[170:171], off
	s_mov_b32 m0, s81
	v_lshl_add_u64 v[170:171], v[236:237], 0, s[92:93]
	global_load_lds_dwordx4 v[170:171], off
	v_lshl_add_u64 v[170:171], v[238:239], 0, s[92:93]
	s_mov_b32 m0, s8
	s_nop 0
	global_load_lds_dwordx4 v[170:171], off
	ds_read_b128 v[188:191], v187 offset:49152
	ds_read_b128 v[192:195], v187 offset:50176
	ds_read_b128 v[196:199], v187 offset:51200
	ds_read_b128 v[200:203], v187 offset:52224
	ds_read_b128 v[204:207], v187 offset:53248
	ds_read_b128 v[208:211], v187 offset:54272
	ds_read_b128 v[212:215], v187 offset:55296
	ds_read_b128 v[216:219], v187 offset:56320
	s_waitcnt vmcnt(8)
	s_waitcnt lgkmcnt(0)
	s_barrier
	v_mfma_f32_16x16x32_bf16 v[60:63], v[64:67], v[188:191], v[60:63]
	v_mfma_f32_16x16x32_bf16 v[56:59], v[72:75], v[188:191], v[56:59]
	v_mfma_f32_16x16x32_bf16 v[44:47], v[64:67], v[196:199], v[44:47]
	v_mfma_f32_16x16x32_bf16 v[40:43], v[72:75], v[196:199], v[40:43]
	v_mfma_f32_16x16x32_bf16 v[28:31], v[64:67], v[204:207], v[28:31]
	v_mfma_f32_16x16x32_bf16 v[24:27], v[72:75], v[204:207], v[24:27]
	v_mfma_f32_16x16x32_bf16 v[12:15], v[64:67], v[212:215], v[12:15]
	v_mfma_f32_16x16x32_bf16 v[8:11], v[72:75], v[212:215], v[8:11]
	v_mfma_f32_16x16x32_bf16 v[60:63], v[68:71], v[192:195], v[60:63]
	v_mfma_f32_16x16x32_bf16 v[56:59], v[76:79], v[192:195], v[56:59]
	v_mfma_f32_16x16x32_bf16 v[44:47], v[68:71], v[200:203], v[44:47]
	v_mfma_f32_16x16x32_bf16 v[40:43], v[76:79], v[200:203], v[40:43]
	v_mfma_f32_16x16x32_bf16 v[28:31], v[68:71], v[208:211], v[28:31]
	v_mfma_f32_16x16x32_bf16 v[24:27], v[76:79], v[208:211], v[24:27]
	v_mfma_f32_16x16x32_bf16 v[12:15], v[68:71], v[216:219], v[12:15]
	v_mfma_f32_16x16x32_bf16 v[8:11], v[76:79], v[216:219], v[8:11]
	v_mfma_f32_16x16x32_bf16 v[52:55], v[220:223], v[188:191], v[52:55]
	v_mfma_f32_16x16x32_bf16 v[48:51], v[228:231], v[188:191], v[48:51]
	v_mfma_f32_16x16x32_bf16 v[36:39], v[220:223], v[196:199], v[36:39]
	v_mfma_f32_16x16x32_bf16 v[32:35], v[228:231], v[196:199], v[32:35]
	v_mfma_f32_16x16x32_bf16 v[20:23], v[220:223], v[204:207], v[20:23]
	v_mfma_f32_16x16x32_bf16 v[16:19], v[228:231], v[204:207], v[16:19]
	v_mfma_f32_16x16x32_bf16 v[0:3], v[220:223], v[212:215], v[0:3]
	v_mfma_f32_16x16x32_bf16 v[4:7], v[228:231], v[212:215], v[4:7]
	v_mfma_f32_16x16x32_bf16 v[52:55], v[224:227], v[192:195], v[52:55]
	v_mfma_f32_16x16x32_bf16 v[48:51], v[246:249], v[192:195], v[48:51]
	v_mfma_f32_16x16x32_bf16 v[36:39], v[224:227], v[200:203], v[36:39]
	v_mfma_f32_16x16x32_bf16 v[32:35], v[246:249], v[200:203], v[32:35]
	v_mfma_f32_16x16x32_bf16 v[20:23], v[224:227], v[208:211], v[20:23]
	v_mfma_f32_16x16x32_bf16 v[16:19], v[246:249], v[208:211], v[16:19]
	v_mfma_f32_16x16x32_bf16 v[0:3], v[224:227], v[216:219], v[0:3]
	v_mfma_f32_16x16x32_bf16 v[4:7], v[246:249], v[216:219], v[4:7]
	s_add_u32 s2, s2, 0x100
	s_addc_u32 s3, s3, 0
	s_add_u32 s19, s19, 0x100
	s_addc_u32 s20, s20, 0
	s_cmp_ge_i32 s24, s9
	s_mov_b32 s23, s24
	s_barrier
	s_cbranch_scc0 .LBB0_746
	v_readlane_b32 s26, v255, 16
	v_readlane_b32 s27, v255, 17
